# GEMM epilogues: loads hoisted and batched (ssq loads, x residual, hb residual), counted vmcnt; chunk-local solve ring; stores no longer drained before scan images
# speedup vs baseline: 1.0192x; 1.0192x over previous
.LBB0_242:
	s_andn2_b64 vcc, exec, s[6:7]
	s_cbranch_vccnz .LBB0_244
	s_waitcnt lgkmcnt(0)
	v_add_u32_e32 v144, s8, v155
	v_lshlrev_b32_e32 v146, 1, v144
	v_ashrrev_i32_e32 v147, 31, v146
	v_lshl_add_u64 v[146:147], v[146:147], 2, s[60:61]
	global_load_dword v202, v[146:147], off offset:4
	global_load_dword v203, v[146:147], off offset:132
	global_load_dword v204, v[146:147], off offset:260
	global_load_dword v205, v[146:147], off offset:388
	global_load_dword v206, v[146:147], off offset:1028
	global_load_dword v207, v[146:147], off offset:1156
	global_load_dword v208, v[146:147], off offset:1284
	global_load_dword v209, v[146:147], off offset:1412
	s_lshl_b32 s6, s46, 7
	v_ashrrev_i32_e32 v145, 31, v144
	v_readlane_b32 s36, v255, 1
	s_ashr_i32 s7, s6, 31
	v_readlane_b32 s37, v255, 2
	s_lshl_b64 s[6:7], s[6:7], 1
	s_waitcnt vmcnt(0)
	v_fmamk_f32 v0, v202, 0x3b800000, v139
	v_rsq_f32_e32 v150, v0
	v_lshlrev_b32_e32 v0, 1, v138
	v_pk_mul_f32 v[148:149], v[128:129], v[150:151] op_sel_hi:[1,0]
	v_pk_mul_f32 v[146:147], v[126:127], v[150:151] op_sel_hi:[1,0]
	v_pk_mul_f32 v[160:161], v[124:125], v[150:151] op_sel_hi:[1,0]
	v_pk_mul_f32 v[162:163], v[122:123], v[150:151] op_sel_hi:[1,0]
	v_cvt_pk_bf16_f32 v146, v146, v147
	v_cvt_pk_bf16_f32 v147, v148, v149
	s_nop 0
	v_cvt_pk_bf16_f32 v148, v162, v163
	v_cvt_pk_bf16_f32 v149, v160, v161
	v_lshlrev_b64 v[160:161], 10, v[144:145]
	v_lshl_add_u64 v[160:161], s[36:37], 0, v[160:161]
	v_lshl_add_u64 v[160:161], v[160:161], 0, s[6:7]
	v_lshrrev_b32_e32 v145, 21, v145
	v_lshl_add_u64 v[160:161], v[160:161], 0, v[0:1]
	v_add_u32_e32 v159, v144, v145
	global_store_dwordx4 v[160:161], v[146:149], off
	v_pk_mul_f32 v[160:161], v[116:117], v[150:151] op_sel_hi:[1,0]
	v_ashrrev_i32_e32 v159, 11, v159
	v_pk_mul_f32 v[148:149], v[120:121], v[150:151] op_sel_hi:[1,0]
	v_pk_mul_f32 v[146:147], v[118:119], v[150:151] op_sel_hi:[1,0]
	v_pk_mul_f32 v[150:151], v[114:115], v[150:151] op_sel_hi:[1,0]
	v_mul_i32_i24_e32 v162, 0x800, v159
	v_cvt_pk_bf16_f32 v146, v146, v147
	v_cvt_pk_bf16_f32 v147, v148, v149
	v_cvt_pk_bf16_f32 v148, v150, v151
	v_lshl_add_u32 v150, v159, 2, s46
	v_sub_u32_e32 v162, v144, v162
	v_ashrrev_i32_e32 v151, 31, v150
	v_ashrrev_i32_e32 v163, 31, v162
	v_lshlrev_b64 v[150:151], 19, v[150:151]
	v_cvt_pk_bf16_f32 v149, v160, v161
	v_lshl_add_u64 v[150:151], s[96:97], 0, v[150:151]
	v_lshlrev_b64 v[160:161], 8, v[162:163]
	v_lshl_add_u64 v[150:151], v[150:151], 0, v[160:161]
	v_lshl_add_u64 v[150:151], v[150:151], 0, v[0:1]
	global_store_dwordx4 v[150:151], v[146:149], off
	v_or_b32_e32 v150, 16, v144
	v_ashrrev_i32_e32 v151, 31, v150
	v_lshlrev_b32_e32 v146, 1, v150
	v_ashrrev_i32_e32 v147, 31, v146
	v_lshl_add_u64 v[146:147], v[146:147], 2, s[60:61]
	v_fmamk_f32 v146, v203, 0x3b800000, v139
	v_rsq_f32_e32 v160, v146
	s_nop 0
	v_pk_mul_f32 v[148:149], v[112:113], v[160:161] op_sel_hi:[1,0]
	v_pk_mul_f32 v[146:147], v[110:111], v[160:161] op_sel_hi:[1,0]
	v_pk_mul_f32 v[162:163], v[108:109], v[160:161] op_sel_hi:[1,0]
	v_pk_mul_f32 v[164:165], v[106:107], v[160:161] op_sel_hi:[1,0]
	v_cvt_pk_bf16_f32 v146, v146, v147
	v_cvt_pk_bf16_f32 v147, v148, v149
	s_nop 0
	v_cvt_pk_bf16_f32 v148, v164, v165
	v_cvt_pk_bf16_f32 v149, v162, v163
	v_lshlrev_b64 v[162:163], 10, v[150:151]
	v_lshl_add_u64 v[162:163], s[36:37], 0, v[162:163]
	v_lshl_add_u64 v[162:163], v[162:163], 0, s[6:7]
	v_lshl_add_u64 v[162:163], v[162:163], 0, v[0:1]
	v_add_u32_e32 v151, v150, v145
	global_store_dwordx4 v[162:163], v[146:149], off
	v_pk_mul_f32 v[162:163], v[100:101], v[160:161] op_sel_hi:[1,0]
	v_ashrrev_i32_e32 v151, 11, v151
	v_pk_mul_f32 v[148:149], v[104:105], v[160:161] op_sel_hi:[1,0]
	v_pk_mul_f32 v[146:147], v[102:103], v[160:161] op_sel_hi:[1,0]
	v_pk_mul_f32 v[160:161], v[98:99], v[160:161] op_sel_hi:[1,0]
	v_mul_i32_i24_e32 v159, 0x800, v151
	v_cvt_pk_bf16_f32 v146, v146, v147
	v_cvt_pk_bf16_f32 v147, v148, v149
	v_cvt_pk_bf16_f32 v148, v160, v161
	v_lshl_add_u32 v160, v151, 2, s46
	v_sub_u32_e32 v150, v150, v159
	v_ashrrev_i32_e32 v161, 31, v160
	v_ashrrev_i32_e32 v151, 31, v150
	v_lshlrev_b64 v[160:161], 19, v[160:161]
	v_lshl_add_u64 v[160:161], s[96:97], 0, v[160:161]
	v_lshlrev_b64 v[150:151], 8, v[150:151]
	v_lshl_add_u64 v[150:151], v[160:161], 0, v[150:151]
	v_lshl_add_u64 v[150:151], v[150:151], 0, v[0:1]
	v_cvt_pk_bf16_f32 v149, v162, v163
	global_store_dwordx4 v[150:151], v[146:149], off
	v_or_b32_e32 v150, 32, v144
	v_ashrrev_i32_e32 v151, 31, v150
	v_lshlrev_b32_e32 v146, 1, v150
	v_ashrrev_i32_e32 v147, 31, v146
	v_lshl_add_u64 v[146:147], v[146:147], 2, s[60:61]
	v_fmamk_f32 v146, v204, 0x3b800000, v139
	v_rsq_f32_e32 v160, v146
	s_nop 0
	v_pk_mul_f32 v[148:149], v[96:97], v[160:161] op_sel_hi:[1,0]
	v_pk_mul_f32 v[146:147], v[94:95], v[160:161] op_sel_hi:[1,0]
	v_pk_mul_f32 v[162:163], v[92:93], v[160:161] op_sel_hi:[1,0]
	v_pk_mul_f32 v[164:165], v[90:91], v[160:161] op_sel_hi:[1,0]
	v_cvt_pk_bf16_f32 v146, v146, v147
	v_cvt_pk_bf16_f32 v147, v148, v149
	s_nop 0
	v_cvt_pk_bf16_f32 v148, v164, v165
	v_cvt_pk_bf16_f32 v149, v162, v163
	v_lshlrev_b64 v[162:163], 10, v[150:151]
	v_lshl_add_u64 v[162:163], s[36:37], 0, v[162:163]
	v_lshl_add_u64 v[162:163], v[162:163], 0, s[6:7]
	v_lshl_add_u64 v[162:163], v[162:163], 0, v[0:1]
	v_add_u32_e32 v151, v150, v145
	global_store_dwordx4 v[162:163], v[146:149], off
	v_pk_mul_f32 v[162:163], v[84:85], v[160:161] op_sel_hi:[1,0]
	v_ashrrev_i32_e32 v151, 11, v151
	v_pk_mul_f32 v[148:149], v[88:89], v[160:161] op_sel_hi:[1,0]
	v_pk_mul_f32 v[146:147], v[86:87], v[160:161] op_sel_hi:[1,0]
	v_pk_mul_f32 v[160:161], v[82:83], v[160:161] op_sel_hi:[1,0]
	v_mul_i32_i24_e32 v159, 0x800, v151
	v_cvt_pk_bf16_f32 v146, v146, v147
	v_cvt_pk_bf16_f32 v147, v148, v149
	v_cvt_pk_bf16_f32 v148, v160, v161
	v_lshl_add_u32 v160, v151, 2, s46
	v_sub_u32_e32 v150, v150, v159
	v_ashrrev_i32_e32 v161, 31, v160
	v_ashrrev_i32_e32 v151, 31, v150
	v_lshlrev_b64 v[160:161], 19, v[160:161]
	v_lshl_add_u64 v[160:161], s[96:97], 0, v[160:161]
	v_lshlrev_b64 v[150:151], 8, v[150:151]
	v_lshl_add_u64 v[150:151], v[160:161], 0, v[150:151]
	v_lshl_add_u64 v[150:151], v[150:151], 0, v[0:1]
	v_cvt_pk_bf16_f32 v149, v162, v163
	global_store_dwordx4 v[150:151], v[146:149], off
	v_or_b32_e32 v150, 48, v144
	v_ashrrev_i32_e32 v151, 31, v150
	v_lshlrev_b32_e32 v146, 1, v150
	v_ashrrev_i32_e32 v147, 31, v146
	v_lshl_add_u64 v[146:147], v[146:147], 2, s[60:61]
	v_add_u32_e32 v145, v150, v145
	v_ashrrev_i32_e32 v145, 11, v145
	v_fmamk_f32 v146, v205, 0x3b800000, v139
	v_rsq_f32_e32 v160, v146
	s_nop 0
	v_pk_mul_f32 v[148:149], v[80:81], v[160:161] op_sel_hi:[1,0]
	v_pk_mul_f32 v[146:147], v[78:79], v[160:161] op_sel_hi:[1,0]
	v_pk_mul_f32 v[162:163], v[76:77], v[160:161] op_sel_hi:[1,0]
	v_pk_mul_f32 v[164:165], v[74:75], v[160:161] op_sel_hi:[1,0]
	v_cvt_pk_bf16_f32 v146, v146, v147
	v_cvt_pk_bf16_f32 v147, v148, v149
	s_nop 0
	v_cvt_pk_bf16_f32 v148, v164, v165
	v_cvt_pk_bf16_f32 v149, v162, v163
	v_lshlrev_b64 v[162:163], 10, v[150:151]
	v_lshl_add_u64 v[162:163], s[36:37], 0, v[162:163]
	v_lshl_add_u64 v[162:163], v[162:163], 0, s[6:7]
	v_lshl_add_u64 v[162:163], v[162:163], 0, v[0:1]
	global_store_dwordx4 v[162:163], v[146:149], off
	v_pk_mul_f32 v[162:163], v[68:69], v[160:161] op_sel_hi:[1,0]
	v_mul_i32_i24_e32 v151, 0x800, v145
	v_pk_mul_f32 v[148:149], v[72:73], v[160:161] op_sel_hi:[1,0]
	v_pk_mul_f32 v[146:147], v[70:71], v[160:161] op_sel_hi:[1,0]
	v_pk_mul_f32 v[160:161], v[66:67], v[160:161] op_sel_hi:[1,0]
	v_cvt_pk_bf16_f32 v146, v146, v147
	v_cvt_pk_bf16_f32 v147, v148, v149
	v_sub_u32_e32 v150, v150, v151
	v_cvt_pk_bf16_f32 v148, v160, v161
	v_lshl_add_u32 v160, v145, 2, s46
	v_ashrrev_i32_e32 v161, 31, v160
	v_ashrrev_i32_e32 v151, 31, v150
	v_lshlrev_b64 v[160:161], 19, v[160:161]
	v_lshl_add_u64 v[160:161], s[96:97], 0, v[160:161]
	v_lshlrev_b64 v[150:151], 8, v[150:151]
	v_lshl_add_u64 v[150:151], v[160:161], 0, v[150:151]
	v_lshl_add_u64 v[150:151], v[150:151], 0, v[0:1]
	v_cvt_pk_bf16_f32 v149, v162, v163
	global_store_dwordx4 v[150:151], v[146:149], off
	v_add_u32_e32 v150, 0x80, v144
	v_ashrrev_i32_e32 v151, 31, v150
	v_lshlrev_b32_e32 v146, 1, v150
	v_ashrrev_i32_e32 v147, 31, v146
	v_lshl_add_u64 v[146:147], v[146:147], 2, s[60:61]
	v_fmamk_f32 v145, v206, 0x3b800000, v139
	v_rsq_f32_e32 v160, v145
	v_lshrrev_b32_e32 v145, 21, v151
	v_add_u32_e32 v145, v150, v145
	v_ashrrev_i32_e32 v145, 11, v145
	v_pk_mul_f32 v[148:149], v[64:65], v[160:161] op_sel_hi:[1,0]
	v_pk_mul_f32 v[146:147], v[62:63], v[160:161] op_sel_hi:[1,0]
	v_pk_mul_f32 v[162:163], v[60:61], v[160:161] op_sel_hi:[1,0]
	v_pk_mul_f32 v[164:165], v[58:59], v[160:161] op_sel_hi:[1,0]
	v_cvt_pk_bf16_f32 v146, v146, v147
	v_cvt_pk_bf16_f32 v147, v148, v149
	s_nop 0
	v_cvt_pk_bf16_f32 v148, v164, v165
	v_cvt_pk_bf16_f32 v149, v162, v163
	v_lshlrev_b64 v[162:163], 10, v[150:151]
	v_lshl_add_u64 v[162:163], s[36:37], 0, v[162:163]
	v_lshl_add_u64 v[162:163], v[162:163], 0, s[6:7]
	v_lshl_add_u64 v[162:163], v[162:163], 0, v[0:1]
	global_store_dwordx4 v[162:163], v[146:149], off
	v_pk_mul_f32 v[162:163], v[52:53], v[160:161] op_sel_hi:[1,0]
	v_mul_i32_i24_e32 v151, 0x800, v145
	v_pk_mul_f32 v[148:149], v[56:57], v[160:161] op_sel_hi:[1,0]
	v_pk_mul_f32 v[146:147], v[54:55], v[160:161] op_sel_hi:[1,0]
	v_pk_mul_f32 v[160:161], v[50:51], v[160:161] op_sel_hi:[1,0]
	v_cvt_pk_bf16_f32 v146, v146, v147
	v_cvt_pk_bf16_f32 v147, v148, v149
	v_sub_u32_e32 v150, v150, v151
	v_cvt_pk_bf16_f32 v148, v160, v161
	v_lshl_add_u32 v160, v145, 2, s46
	v_ashrrev_i32_e32 v161, 31, v160
	v_ashrrev_i32_e32 v151, 31, v150
	v_lshlrev_b64 v[160:161], 19, v[160:161]
	v_lshl_add_u64 v[160:161], s[96:97], 0, v[160:161]
	v_lshlrev_b64 v[150:151], 8, v[150:151]
	v_lshl_add_u64 v[150:151], v[160:161], 0, v[150:151]
	v_lshl_add_u64 v[150:151], v[150:151], 0, v[0:1]
	v_cvt_pk_bf16_f32 v149, v162, v163
	global_store_dwordx4 v[150:151], v[146:149], off
	v_add_u32_e32 v150, 0x90, v144
	v_ashrrev_i32_e32 v151, 31, v150
	v_lshlrev_b32_e32 v146, 1, v150
	v_ashrrev_i32_e32 v147, 31, v146
	v_lshl_add_u64 v[146:147], v[146:147], 2, s[60:61]
	v_fmamk_f32 v145, v207, 0x3b800000, v139
	v_rsq_f32_e32 v160, v145
	v_lshrrev_b32_e32 v145, 21, v151
	v_add_u32_e32 v145, v150, v145
	v_ashrrev_i32_e32 v145, 11, v145
	v_pk_mul_f32 v[148:149], v[48:49], v[160:161] op_sel_hi:[1,0]
	v_pk_mul_f32 v[146:147], v[46:47], v[160:161] op_sel_hi:[1,0]
	v_pk_mul_f32 v[162:163], v[44:45], v[160:161] op_sel_hi:[1,0]
	v_pk_mul_f32 v[164:165], v[42:43], v[160:161] op_sel_hi:[1,0]
	v_cvt_pk_bf16_f32 v146, v146, v147
	v_cvt_pk_bf16_f32 v147, v148, v149
	s_nop 0
	v_cvt_pk_bf16_f32 v148, v164, v165
	v_cvt_pk_bf16_f32 v149, v162, v163
	v_lshlrev_b64 v[162:163], 10, v[150:151]
	v_lshl_add_u64 v[162:163], s[36:37], 0, v[162:163]
	v_lshl_add_u64 v[162:163], v[162:163], 0, s[6:7]
	v_lshl_add_u64 v[162:163], v[162:163], 0, v[0:1]
	global_store_dwordx4 v[162:163], v[146:149], off
	v_pk_mul_f32 v[162:163], v[36:37], v[160:161] op_sel_hi:[1,0]
	v_mul_i32_i24_e32 v151, 0x800, v145
	v_pk_mul_f32 v[148:149], v[40:41], v[160:161] op_sel_hi:[1,0]
	v_pk_mul_f32 v[146:147], v[38:39], v[160:161] op_sel_hi:[1,0]
	v_pk_mul_f32 v[160:161], v[34:35], v[160:161] op_sel_hi:[1,0]
	v_cvt_pk_bf16_f32 v146, v146, v147
	v_cvt_pk_bf16_f32 v147, v148, v149
	v_sub_u32_e32 v150, v150, v151
	v_cvt_pk_bf16_f32 v148, v160, v161
	v_lshl_add_u32 v160, v145, 2, s46
	v_ashrrev_i32_e32 v161, 31, v160
	v_ashrrev_i32_e32 v151, 31, v150
	v_lshlrev_b64 v[160:161], 19, v[160:161]
	v_lshl_add_u64 v[160:161], s[96:97], 0, v[160:161]
	v_lshlrev_b64 v[150:151], 8, v[150:151]
	v_lshl_add_u64 v[150:151], v[160:161], 0, v[150:151]
	v_lshl_add_u64 v[150:151], v[150:151], 0, v[0:1]
	v_cvt_pk_bf16_f32 v149, v162, v163
	global_store_dwordx4 v[150:151], v[146:149], off
	v_add_u32_e32 v150, 0xa0, v144
	v_ashrrev_i32_e32 v151, 31, v150
	v_lshlrev_b32_e32 v146, 1, v150
	v_ashrrev_i32_e32 v147, 31, v146
	v_lshl_add_u64 v[146:147], v[146:147], 2, s[60:61]
	v_add_u32_e32 v144, 0xb0, v144
	v_fmamk_f32 v145, v208, 0x3b800000, v139
	v_rsq_f32_e32 v160, v145
	v_lshrrev_b32_e32 v145, 21, v151
	v_add_u32_e32 v145, v150, v145
	v_ashrrev_i32_e32 v145, 11, v145
	v_pk_mul_f32 v[148:149], v[32:33], v[160:161] op_sel_hi:[1,0]
	v_pk_mul_f32 v[146:147], v[30:31], v[160:161] op_sel_hi:[1,0]
	v_pk_mul_f32 v[162:163], v[28:29], v[160:161] op_sel_hi:[1,0]
	v_pk_mul_f32 v[164:165], v[26:27], v[160:161] op_sel_hi:[1,0]
	v_cvt_pk_bf16_f32 v146, v146, v147
	v_cvt_pk_bf16_f32 v147, v148, v149
	s_nop 0
	v_cvt_pk_bf16_f32 v148, v164, v165
	v_cvt_pk_bf16_f32 v149, v162, v163
	v_lshlrev_b64 v[162:163], 10, v[150:151]
	v_lshl_add_u64 v[162:163], s[36:37], 0, v[162:163]
	v_lshl_add_u64 v[162:163], v[162:163], 0, s[6:7]
	v_lshl_add_u64 v[162:163], v[162:163], 0, v[0:1]
	global_store_dwordx4 v[162:163], v[146:149], off
	v_pk_mul_f32 v[162:163], v[20:21], v[160:161] op_sel_hi:[1,0]
	v_mul_i32_i24_e32 v151, 0x800, v145
	v_pk_mul_f32 v[148:149], v[24:25], v[160:161] op_sel_hi:[1,0]
	v_pk_mul_f32 v[146:147], v[22:23], v[160:161] op_sel_hi:[1,0]
	v_pk_mul_f32 v[160:161], v[18:19], v[160:161] op_sel_hi:[1,0]
	v_cvt_pk_bf16_f32 v146, v146, v147
	v_cvt_pk_bf16_f32 v147, v148, v149
	v_sub_u32_e32 v150, v150, v151
	v_cvt_pk_bf16_f32 v148, v160, v161
	v_lshl_add_u32 v160, v145, 2, s46
	v_ashrrev_i32_e32 v161, 31, v160
	v_ashrrev_i32_e32 v151, 31, v150
	v_lshlrev_b64 v[160:161], 19, v[160:161]
	v_lshl_add_u64 v[160:161], s[96:97], 0, v[160:161]
	v_lshlrev_b64 v[150:151], 8, v[150:151]
	v_lshl_add_u64 v[150:151], v[160:161], 0, v[150:151]
	v_lshl_add_u64 v[150:151], v[150:151], 0, v[0:1]
	v_cvt_pk_bf16_f32 v149, v162, v163
	global_store_dwordx4 v[150:151], v[146:149], off
	s_nop 1
	v_lshlrev_b32_e32 v146, 1, v144
	v_ashrrev_i32_e32 v147, 31, v146
	v_lshl_add_u64 v[146:147], v[146:147], 2, s[60:61]
	v_fmamk_f32 v145, v209, 0x3b800000, v139
	v_rsq_f32_e32 v150, v145
	v_ashrrev_i32_e32 v145, 31, v144
	v_pk_mul_f32 v[148:149], v[16:17], v[150:151] op_sel_hi:[1,0]
	v_pk_mul_f32 v[146:147], v[14:15], v[150:151] op_sel_hi:[1,0]
	v_pk_mul_f32 v[160:161], v[12:13], v[150:151] op_sel_hi:[1,0]
	v_pk_mul_f32 v[162:163], v[10:11], v[150:151] op_sel_hi:[1,0]
	v_cvt_pk_bf16_f32 v146, v146, v147
	v_cvt_pk_bf16_f32 v147, v148, v149
	s_nop 0
	v_cvt_pk_bf16_f32 v148, v162, v163
	v_cvt_pk_bf16_f32 v149, v160, v161
	v_lshlrev_b64 v[160:161], 10, v[144:145]
	v_lshl_add_u64 v[160:161], s[36:37], 0, v[160:161]
	v_lshrrev_b32_e32 v145, 21, v145
	v_lshl_add_u64 v[160:161], v[160:161], 0, s[6:7]
	v_add_u32_e32 v145, v144, v145
	v_lshl_add_u64 v[160:161], v[160:161], 0, v[0:1]
	v_ashrrev_i32_e32 v159, 11, v145
	global_store_dwordx4 v[160:161], v[146:149], off
	v_mul_i32_i24_e32 v145, 0x800, v159
	v_sub_u32_e32 v162, v144, v145
	v_pk_mul_f32 v[148:149], v[6:7], v[150:151] op_sel_hi:[1,0]
	v_pk_mul_f32 v[146:147], v[8:9], v[150:151] op_sel_hi:[1,0]
	v_cvt_pk_bf16_f32 v144, v148, v149
	v_lshl_add_u32 v148, v159, 2, s46
	v_ashrrev_i32_e32 v149, 31, v148
	v_pk_mul_f32 v[160:161], v[4:5], v[150:151] op_sel_hi:[1,0]
	v_pk_mul_f32 v[150:151], v[2:3], v[150:151] op_sel_hi:[1,0]
	v_ashrrev_i32_e32 v163, 31, v162
	v_lshlrev_b64 v[148:149], 19, v[148:149]
	v_cvt_pk_bf16_f32 v145, v146, v147
	v_cvt_pk_bf16_f32 v146, v150, v151
	v_lshl_add_u64 v[148:149], s[96:97], 0, v[148:149]
	v_lshlrev_b64 v[150:151], 8, v[162:163]
	v_lshl_add_u64 v[148:149], v[148:149], 0, v[150:151]
	v_lshl_add_u64 v[148:149], v[148:149], 0, v[0:1]
	v_cvt_pk_bf16_f32 v147, v160, v161
	global_store_dwordx4 v[148:149], v[144:147], off

.LBB0_245:
	s_mov_b64 s[6:7], -1
	s_cmp_gt_i32 s45, 0
	v_add_u32_e32 v146, s8, v155
	s_waitcnt lgkmcnt(0)
	v_lshl_or_b32 v144, s46, 8, v138
	s_cbranch_scc0 .LBB0_247
	v_lshlrev_b32_e32 v150, 1, v146
	v_ashrrev_i32_e32 v151, 31, v150
	v_lshl_add_u64 v[150:151], v[150:151], 2, s[60:61]
	global_load_dword v202, v[150:151], off
	global_load_dword v203, v[150:151], off offset:128
	global_load_dword v204, v[150:151], off offset:256
	global_load_dword v205, v[150:151], off offset:384
	global_load_dword v206, v[150:151], off offset:1024
	global_load_dword v207, v[150:151], off offset:1152
	global_load_dword v208, v[150:151], off offset:1280
	global_load_dword v209, v[150:151], off offset:1408
	v_readlane_b32 s6, v254, 44
	v_ashrrev_i32_e32 v145, 31, v144
	v_readlane_b32 s7, v254, 45
	s_waitcnt vmcnt(0)
	v_fmamk_f32 v0, v202, 0x3b800000, v139
	v_rsq_f32_e32 v0, v0
	v_lshl_add_u64 v[148:149], v[144:145], 1, s[6:7]
	v_mad_i64_i32 v[150:151], s[6:7], v146, s41, v[148:149]
	v_pk_mul_f32 v[162:163], v[128:129], v[0:1] op_sel_hi:[1,0]
	v_pk_mul_f32 v[160:161], v[126:127], v[0:1] op_sel_hi:[1,0]
	v_pk_mul_f32 v[164:165], v[124:125], v[0:1] op_sel_hi:[1,0]
	v_pk_mul_f32 v[166:167], v[122:123], v[0:1] op_sel_hi:[1,0]
	v_cvt_pk_bf16_f32 v160, v160, v161
	v_cvt_pk_bf16_f32 v161, v162, v163
	v_or_b32_e32 v145, 16, v146
	v_cvt_pk_bf16_f32 v162, v166, v167
	v_cvt_pk_bf16_f32 v163, v164, v165
	global_store_dwordx4 v[150:151], v[160:163], off
	v_pk_mul_f32 v[164:165], v[116:117], v[0:1] op_sel_hi:[1,0]
	v_pk_mul_f32 v[166:167], v[114:115], v[0:1] op_sel_hi:[1,0]
	v_pk_mul_f32 v[162:163], v[120:121], v[0:1] op_sel_hi:[1,0]
	v_pk_mul_f32 v[160:161], v[118:119], v[0:1] op_sel_hi:[1,0]
	s_nop 0
	v_cvt_pk_bf16_f32 v160, v160, v161
	v_cvt_pk_bf16_f32 v161, v162, v163
	v_cvt_pk_bf16_f32 v162, v166, v167
	v_cvt_pk_bf16_f32 v163, v164, v165
	global_store_dwordx4 v[150:151], v[160:163], off offset:256
	v_lshlrev_b32_e32 v150, 1, v145
	v_ashrrev_i32_e32 v151, 31, v150
	v_lshl_add_u64 v[150:151], v[150:151], 2, s[60:61]
	v_mad_i64_i32 v[150:151], s[6:7], v145, s41, v[148:149]
	v_or_b32_e32 v145, 32, v146
	v_fmamk_f32 v0, v203, 0x3b800000, v139
	v_rsq_f32_e32 v0, v0
	s_nop 0
	v_pk_mul_f32 v[162:163], v[112:113], v[0:1] op_sel_hi:[1,0]
	v_pk_mul_f32 v[160:161], v[110:111], v[0:1] op_sel_hi:[1,0]
	v_pk_mul_f32 v[164:165], v[108:109], v[0:1] op_sel_hi:[1,0]
	v_pk_mul_f32 v[166:167], v[106:107], v[0:1] op_sel_hi:[1,0]
	v_cvt_pk_bf16_f32 v160, v160, v161
	v_cvt_pk_bf16_f32 v161, v162, v163
	s_nop 0
	v_cvt_pk_bf16_f32 v162, v166, v167
	v_cvt_pk_bf16_f32 v163, v164, v165
	global_store_dwordx4 v[150:151], v[160:163], off
	v_pk_mul_f32 v[164:165], v[100:101], v[0:1] op_sel_hi:[1,0]
	v_pk_mul_f32 v[166:167], v[98:99], v[0:1] op_sel_hi:[1,0]
	v_pk_mul_f32 v[162:163], v[104:105], v[0:1] op_sel_hi:[1,0]
	v_pk_mul_f32 v[160:161], v[102:103], v[0:1] op_sel_hi:[1,0]
	s_nop 0
	v_cvt_pk_bf16_f32 v160, v160, v161
	v_cvt_pk_bf16_f32 v161, v162, v163
	v_cvt_pk_bf16_f32 v162, v166, v167
	v_cvt_pk_bf16_f32 v163, v164, v165
	global_store_dwordx4 v[150:151], v[160:163], off offset:256
	v_lshlrev_b32_e32 v150, 1, v145
	v_ashrrev_i32_e32 v151, 31, v150
	v_lshl_add_u64 v[150:151], v[150:151], 2, s[60:61]
	v_mad_i64_i32 v[150:151], s[6:7], v145, s41, v[148:149]
	v_or_b32_e32 v145, 48, v146
	v_fmamk_f32 v0, v204, 0x3b800000, v139
	v_rsq_f32_e32 v0, v0
	s_nop 0
	v_pk_mul_f32 v[162:163], v[96:97], v[0:1] op_sel_hi:[1,0]
	v_pk_mul_f32 v[160:161], v[94:95], v[0:1] op_sel_hi:[1,0]
	v_pk_mul_f32 v[164:165], v[92:93], v[0:1] op_sel_hi:[1,0]
	v_pk_mul_f32 v[166:167], v[90:91], v[0:1] op_sel_hi:[1,0]
	v_cvt_pk_bf16_f32 v160, v160, v161
	v_cvt_pk_bf16_f32 v161, v162, v163
	s_nop 0
	v_cvt_pk_bf16_f32 v162, v166, v167
	v_cvt_pk_bf16_f32 v163, v164, v165
	global_store_dwordx4 v[150:151], v[160:163], off
	v_pk_mul_f32 v[164:165], v[84:85], v[0:1] op_sel_hi:[1,0]
	v_pk_mul_f32 v[166:167], v[82:83], v[0:1] op_sel_hi:[1,0]
	v_pk_mul_f32 v[162:163], v[88:89], v[0:1] op_sel_hi:[1,0]
	v_pk_mul_f32 v[160:161], v[86:87], v[0:1] op_sel_hi:[1,0]
	s_nop 0
	v_cvt_pk_bf16_f32 v160, v160, v161
	v_cvt_pk_bf16_f32 v161, v162, v163
	v_cvt_pk_bf16_f32 v162, v166, v167
	v_cvt_pk_bf16_f32 v163, v164, v165
	global_store_dwordx4 v[150:151], v[160:163], off offset:256
	v_lshlrev_b32_e32 v150, 1, v145
	v_ashrrev_i32_e32 v151, 31, v150
	v_lshl_add_u64 v[150:151], v[150:151], 2, s[60:61]
	v_mad_i64_i32 v[150:151], s[6:7], v145, s41, v[148:149]
	v_add_u32_e32 v145, 0x80, v146
	v_fmamk_f32 v0, v205, 0x3b800000, v139
	v_rsq_f32_e32 v0, v0
	s_nop 0
	v_pk_mul_f32 v[162:163], v[80:81], v[0:1] op_sel_hi:[1,0]
	v_pk_mul_f32 v[160:161], v[78:79], v[0:1] op_sel_hi:[1,0]
	v_pk_mul_f32 v[164:165], v[76:77], v[0:1] op_sel_hi:[1,0]
	v_pk_mul_f32 v[166:167], v[74:75], v[0:1] op_sel_hi:[1,0]
	v_cvt_pk_bf16_f32 v160, v160, v161
	v_cvt_pk_bf16_f32 v161, v162, v163
	s_nop 0
	v_cvt_pk_bf16_f32 v162, v166, v167
	v_cvt_pk_bf16_f32 v163, v164, v165
	global_store_dwordx4 v[150:151], v[160:163], off
	v_pk_mul_f32 v[164:165], v[68:69], v[0:1] op_sel_hi:[1,0]
	v_pk_mul_f32 v[166:167], v[66:67], v[0:1] op_sel_hi:[1,0]
	v_pk_mul_f32 v[162:163], v[72:73], v[0:1] op_sel_hi:[1,0]
	v_pk_mul_f32 v[160:161], v[70:71], v[0:1] op_sel_hi:[1,0]
	s_nop 0
	v_cvt_pk_bf16_f32 v160, v160, v161
	v_cvt_pk_bf16_f32 v161, v162, v163
	v_cvt_pk_bf16_f32 v162, v166, v167
	v_cvt_pk_bf16_f32 v163, v164, v165
	global_store_dwordx4 v[150:151], v[160:163], off offset:256
	v_lshlrev_b32_e32 v150, 1, v145
	v_ashrrev_i32_e32 v151, 31, v150
	v_lshl_add_u64 v[150:151], v[150:151], 2, s[60:61]
	v_mad_i64_i32 v[150:151], s[6:7], v145, s41, v[148:149]
	v_add_u32_e32 v145, 0x90, v146
	v_fmamk_f32 v0, v206, 0x3b800000, v139
	v_rsq_f32_e32 v0, v0
	s_nop 0
	v_pk_mul_f32 v[162:163], v[64:65], v[0:1] op_sel_hi:[1,0]
	v_pk_mul_f32 v[160:161], v[62:63], v[0:1] op_sel_hi:[1,0]
	v_pk_mul_f32 v[164:165], v[60:61], v[0:1] op_sel_hi:[1,0]
	v_pk_mul_f32 v[166:167], v[58:59], v[0:1] op_sel_hi:[1,0]
	v_cvt_pk_bf16_f32 v160, v160, v161
	v_cvt_pk_bf16_f32 v161, v162, v163
	s_nop 0
	v_cvt_pk_bf16_f32 v162, v166, v167
	v_cvt_pk_bf16_f32 v163, v164, v165
	global_store_dwordx4 v[150:151], v[160:163], off
	v_pk_mul_f32 v[164:165], v[52:53], v[0:1] op_sel_hi:[1,0]
	v_pk_mul_f32 v[166:167], v[50:51], v[0:1] op_sel_hi:[1,0]
	v_pk_mul_f32 v[162:163], v[56:57], v[0:1] op_sel_hi:[1,0]
	v_pk_mul_f32 v[160:161], v[54:55], v[0:1] op_sel_hi:[1,0]
	s_nop 0
	v_cvt_pk_bf16_f32 v160, v160, v161
	v_cvt_pk_bf16_f32 v161, v162, v163
	v_cvt_pk_bf16_f32 v162, v166, v167
	v_cvt_pk_bf16_f32 v163, v164, v165
	global_store_dwordx4 v[150:151], v[160:163], off offset:256
	v_lshlrev_b32_e32 v150, 1, v145
	v_ashrrev_i32_e32 v151, 31, v150
	v_lshl_add_u64 v[150:151], v[150:151], 2, s[60:61]
	v_mad_i64_i32 v[150:151], s[6:7], v145, s41, v[148:149]
	v_add_u32_e32 v145, 0xa0, v146
	v_fmamk_f32 v0, v207, 0x3b800000, v139
	v_rsq_f32_e32 v0, v0
	s_nop 0
	v_pk_mul_f32 v[162:163], v[48:49], v[0:1] op_sel_hi:[1,0]
	v_pk_mul_f32 v[160:161], v[46:47], v[0:1] op_sel_hi:[1,0]
	v_pk_mul_f32 v[164:165], v[44:45], v[0:1] op_sel_hi:[1,0]
	v_pk_mul_f32 v[166:167], v[42:43], v[0:1] op_sel_hi:[1,0]
	v_cvt_pk_bf16_f32 v160, v160, v161
	v_cvt_pk_bf16_f32 v161, v162, v163
	s_nop 0
	v_cvt_pk_bf16_f32 v162, v166, v167
	v_cvt_pk_bf16_f32 v163, v164, v165
	global_store_dwordx4 v[150:151], v[160:163], off
	v_pk_mul_f32 v[164:165], v[36:37], v[0:1] op_sel_hi:[1,0]
	v_pk_mul_f32 v[166:167], v[34:35], v[0:1] op_sel_hi:[1,0]
	v_pk_mul_f32 v[162:163], v[40:41], v[0:1] op_sel_hi:[1,0]
	v_pk_mul_f32 v[160:161], v[38:39], v[0:1] op_sel_hi:[1,0]
	s_nop 0
	v_cvt_pk_bf16_f32 v160, v160, v161
	v_cvt_pk_bf16_f32 v161, v162, v163
	v_cvt_pk_bf16_f32 v162, v166, v167
	v_cvt_pk_bf16_f32 v163, v164, v165
	global_store_dwordx4 v[150:151], v[160:163], off offset:256
	v_lshlrev_b32_e32 v150, 1, v145
	v_ashrrev_i32_e32 v151, 31, v150
	v_lshl_add_u64 v[150:151], v[150:151], 2, s[60:61]
	v_mad_i64_i32 v[150:151], s[6:7], v145, s41, v[148:149]
	v_add_u32_e32 v145, 0xb0, v146
	v_fmamk_f32 v0, v208, 0x3b800000, v139
	v_rsq_f32_e32 v0, v0
	s_nop 0
	v_pk_mul_f32 v[162:163], v[32:33], v[0:1] op_sel_hi:[1,0]
	v_pk_mul_f32 v[160:161], v[30:31], v[0:1] op_sel_hi:[1,0]
	v_pk_mul_f32 v[164:165], v[28:29], v[0:1] op_sel_hi:[1,0]
	v_pk_mul_f32 v[166:167], v[26:27], v[0:1] op_sel_hi:[1,0]
	v_cvt_pk_bf16_f32 v160, v160, v161
	v_cvt_pk_bf16_f32 v161, v162, v163
	s_nop 0
	v_cvt_pk_bf16_f32 v162, v166, v167
	v_cvt_pk_bf16_f32 v163, v164, v165
	global_store_dwordx4 v[150:151], v[160:163], off
	v_pk_mul_f32 v[164:165], v[20:21], v[0:1] op_sel_hi:[1,0]
	v_pk_mul_f32 v[166:167], v[18:19], v[0:1] op_sel_hi:[1,0]
	v_pk_mul_f32 v[162:163], v[24:25], v[0:1] op_sel_hi:[1,0]
	v_pk_mul_f32 v[160:161], v[22:23], v[0:1] op_sel_hi:[1,0]
	s_nop 0
	v_cvt_pk_bf16_f32 v160, v160, v161
	v_cvt_pk_bf16_f32 v161, v162, v163
	v_cvt_pk_bf16_f32 v162, v166, v167
	v_cvt_pk_bf16_f32 v163, v164, v165
	global_store_dwordx4 v[150:151], v[160:163], off offset:256
	v_lshlrev_b32_e32 v150, 1, v145
	v_ashrrev_i32_e32 v151, 31, v150
	v_lshl_add_u64 v[150:151], v[150:151], 2, s[60:61]
	v_mad_i64_i32 v[160:161], s[6:7], v145, s41, v[148:149]
	s_mov_b64 s[6:7], 0
	v_fmamk_f32 v0, v209, 0x3b800000, v139
	v_rsq_f32_e32 v0, v0
	s_nop 0
	v_pk_mul_f32 v[150:151], v[16:17], v[0:1] op_sel_hi:[1,0]
	v_pk_mul_f32 v[148:149], v[14:15], v[0:1] op_sel_hi:[1,0]
	v_pk_mul_f32 v[162:163], v[12:13], v[0:1] op_sel_hi:[1,0]
	v_pk_mul_f32 v[164:165], v[10:11], v[0:1] op_sel_hi:[1,0]
	v_cvt_pk_bf16_f32 v148, v148, v149
	v_cvt_pk_bf16_f32 v149, v150, v151
	s_nop 0
	v_cvt_pk_bf16_f32 v150, v164, v165
	v_cvt_pk_bf16_f32 v151, v162, v163
	global_store_dwordx4 v[160:161], v[148:151], off
	v_pk_mul_f32 v[162:163], v[4:5], v[0:1] op_sel_hi:[1,0]
	v_pk_mul_f32 v[164:165], v[2:3], v[0:1] op_sel_hi:[1,0]
	v_pk_mul_f32 v[150:151], v[8:9], v[0:1] op_sel_hi:[1,0]
	v_pk_mul_f32 v[148:149], v[6:7], v[0:1] op_sel_hi:[1,0]
	s_nop 0
	v_cvt_pk_bf16_f32 v148, v148, v149
	v_cvt_pk_bf16_f32 v149, v150, v151
	v_cvt_pk_bf16_f32 v150, v164, v165
	v_cvt_pk_bf16_f32 v151, v162, v163
	global_store_dwordx4 v[160:161], v[148:151], off offset:256

.LBB0_643:
	v_add_u32_e32 v72, s3, v221
	ds_read_b128 v[66:69], v72
	v_add_co_u32_e32 v70, vcc, 0xffff5000, v64
	s_addk_i32 s3, 0x800
	s_nop 0
	v_addc_co_u32_e32 v71, vcc, -1, v65, vcc
	s_waitcnt lgkmcnt(0)
	global_store_dwordx4 v[70:71], v[66:69], off
	ds_read_b128 v[66:69], v72 offset:1024
	s_cmpk_lg_i32 s3, 0x2000
	s_waitcnt lgkmcnt(0)
	global_store_dwordx4 v[64:65], v[66:69], off
	v_lshl_add_u64 v[64:65], v[64:65], 0, s[72:73]
	s_cbranch_scc1 .LBB0_643
	v_mfma_f32_16x16x32_bf16 v[72:75], v[60:63], v[60:63], 0
	ds_read_b128 v[64:67], v148 offset:17408
	ds_read_b128 v[68:71], v148 offset:17664
	s_mov_b32 s3, 0
	s_waitcnt lgkmcnt(1)
	v_sub_f32_e32 v64, v64, v146
	v_mfma_f32_16x16x32_bf16 v[72:75], v[56:59], v[56:59], v[72:75]
	v_mul_f32_e32 v64, 0x3fb8aa3b, v64
	v_exp_f32_e32 v64, v64
	v_sub_f32_e32 v65, v65, v146
	v_mfma_f32_16x16x32_bf16 v[72:75], v[52:55], v[52:55], v[72:75]
	v_mul_f32_e32 v65, 0x3fb8aa3b, v65
	v_sub_f32_e32 v66, v66, v146
	v_exp_f32_e32 v65, v65
	v_mfma_f32_16x16x32_bf16 v[72:75], v[48:51], v[48:51], v[72:75]
	v_mul_f32_e32 v66, 0x3fb8aa3b, v66
	v_exp_f32_e32 v66, v66
	s_waitcnt lgkmcnt(0)
	s_nop 4
	v_mul_f32_e32 v68, v68, v72
	v_mul_f32_e32 v64, v64, v68
	v_cndmask_b32_e64 v64, 0, v64, s[30:31]
	ds_write_b32 v241, v64
	v_mul_f32_e32 v64, v69, v73
	v_mul_f32_e32 v64, v65, v64
	v_mul_f32_e32 v65, v70, v74
	v_mul_f32_e32 v65, v66, v65
	v_cndmask_b32_e64 v64, v64, 0, s[4:5]
	v_cndmask_b32_e64 v65, 0, v65, s[34:35]
	ds_write2_b32 v242, v64, v65 offset1:68
	v_sub_f32_e32 v65, v67, v146
	v_mul_f32_e32 v65, 0x3fb8aa3b, v65
	v_mul_f32_e32 v64, v71, v75
	v_exp_f32_e32 v65, v65
	v_mfma_f32_16x16x32_bf16 v[72:75], v[44:47], v[60:63], 0
	v_mul_f32_e32 v64, v65, v64
	v_mfma_f32_16x16x32_bf16 v[72:75], v[40:43], v[56:59], v[72:75]
	v_cndmask_b32_e64 v64, 0, v64, s[36:37]
	ds_write_b32 v242, v64 offset:544
	ds_read_b128 v[64:67], v148 offset:17472
	ds_read_b128 v[68:71], v148 offset:17728
	v_mfma_f32_16x16x32_bf16 v[72:75], v[32:35], v[52:55], v[72:75]
	s_waitcnt lgkmcnt(1)
	v_sub_f32_e32 v76, v64, v146
	v_mfma_f32_16x16x32_bf16 v[72:75], v[36:39], v[48:51], v[72:75]
	v_mul_f32_e32 v76, 0x3fb8aa3b, v76
	v_exp_f32_e32 v76, v76
	v_sub_f32_e32 v64, v64, v147
	v_mul_f32_e32 v64, 0x3fb8aa3b, v64
	v_exp_f32_e32 v64, v64
	s_waitcnt lgkmcnt(0)
	s_nop 1
	v_mul_f32_e32 v72, v68, v72
	v_mul_f32_e32 v76, v76, v72
	v_mul_f32_e32 v72, v69, v73
	v_sub_f32_e32 v73, v65, v146
	v_mul_f32_e32 v73, 0x3fb8aa3b, v73
	v_exp_f32_e32 v73, v73
	v_sub_f32_e32 v65, v65, v147
	v_mul_f32_e32 v65, 0x3fb8aa3b, v65
	v_exp_f32_e32 v65, v65
	v_mul_f32_e32 v77, v73, v72
	v_sub_f32_e32 v73, v66, v146
	v_mul_f32_e32 v73, 0x3fb8aa3b, v73
	v_exp_f32_e32 v73, v73
	v_mul_f32_e32 v72, v70, v74
	v_sub_f32_e32 v66, v66, v147
	v_mul_f32_e32 v66, 0x3fb8aa3b, v66
	v_mul_f32_e32 v78, v73, v72
	v_sub_f32_e32 v73, v67, v146
	v_mul_f32_e32 v73, 0x3fb8aa3b, v73
	v_exp_f32_e32 v73, v73
	v_mul_f32_e32 v72, v71, v75
	v_exp_f32_e32 v66, v66
	v_mul_f32_e32 v79, v73, v72
	v_mfma_f32_16x16x32_bf16 v[72:75], v[44:47], v[44:47], 0
	v_mfma_f32_16x16x32_bf16 v[72:75], v[40:43], v[40:43], v[72:75]
	v_mfma_f32_16x16x32_bf16 v[72:75], v[32:35], v[32:35], v[72:75]
	v_mfma_f32_16x16x32_bf16 v[72:75], v[36:39], v[36:39], v[72:75]
	s_nop 7
	v_mul_f32_e32 v68, v68, v72
	v_mul_f32_e32 v64, v64, v68
	v_cndmask_b32_e64 v64, 0, v64, s[30:31]
	v_add_u32_e32 v68, 0xe00, v242
	ds_write2_b32 v68, v76, v64 offset0:124 offset1:140
	v_mul_f32_e32 v64, v69, v73
	v_mul_f32_e32 v64, v65, v64
	v_cndmask_b32_e64 v64, 0, v64, s[38:39]
	v_add_u32_e32 v65, 0x1000, v242
	ds_write2_b32 v65, v77, v64 offset0:64 offset1:80
	v_mul_f32_e32 v64, v70, v74
	v_mul_f32_e32 v64, v66, v64
	v_sub_f32_e32 v66, v67, v147
	v_cndmask_b32_e64 v64, 0, v64, s[40:41]
	v_mul_f32_e32 v66, 0x3fb8aa3b, v66
	ds_write2_b32 v65, v78, v64 offset0:132 offset1:148
	v_mul_f32_e32 v64, v71, v75
	v_exp_f32_e32 v66, v66
	v_mfma_f32_16x16x32_bf16 v[72:75], v[28:31], v[60:63], 0
	v_mul_f32_e32 v64, v66, v64
	v_mfma_f32_16x16x32_bf16 v[72:75], v[24:27], v[56:59], v[72:75]
	v_cndmask_b32_e64 v64, 0, v64, s[42:43]
	ds_write2_b32 v65, v79, v64 offset0:200 offset1:216
	ds_read_b128 v[64:67], v148 offset:17536
	ds_read_b128 v[68:71], v148 offset:17792
	v_mfma_f32_16x16x32_bf16 v[72:75], v[20:23], v[52:55], v[72:75]
	s_waitcnt lgkmcnt(1)
	v_sub_f32_e32 v76, v64, v146
	v_mfma_f32_16x16x32_bf16 v[72:75], v[16:19], v[48:51], v[72:75]
	v_mul_f32_e32 v76, 0x3fb8aa3b, v76
	v_exp_f32_e32 v76, v76
	v_sub_f32_e32 v80, v64, v147
	v_mul_f32_e32 v80, 0x3fb8aa3b, v80
	v_exp_f32_e32 v80, v80
	s_waitcnt lgkmcnt(0)
	s_nop 1
	v_mul_f32_e32 v72, v68, v72
	v_mul_f32_e32 v76, v76, v72
	v_mul_f32_e32 v72, v69, v73
	v_sub_f32_e32 v73, v65, v146
	v_mul_f32_e32 v73, 0x3fb8aa3b, v73
	v_exp_f32_e32 v73, v73
	v_sub_f32_e32 v64, v64, v144
	v_mul_f32_e32 v64, 0x3fb8aa3b, v64
	v_exp_f32_e32 v64, v64
	v_mul_f32_e32 v77, v73, v72
	v_sub_f32_e32 v73, v66, v146
	v_mul_f32_e32 v73, 0x3fb8aa3b, v73
	v_exp_f32_e32 v73, v73
	v_mul_f32_e32 v72, v70, v74
	v_mfma_f32_16x16x32_bf16 v[60:63], v[12:15], v[60:63], 0
	v_mul_f32_e32 v78, v73, v72
	v_sub_f32_e32 v73, v67, v146
	v_mul_f32_e32 v73, 0x3fb8aa3b, v73
	v_exp_f32_e32 v73, v73
	v_mul_f32_e32 v72, v71, v75
	v_mfma_f32_16x16x32_bf16 v[56:59], v[8:11], v[56:59], v[60:63]
	v_mul_f32_e32 v79, v73, v72
	v_mfma_f32_16x16x32_bf16 v[72:75], v[28:31], v[44:47], 0
	v_mfma_f32_16x16x32_bf16 v[72:75], v[24:27], v[40:43], v[72:75]
	v_mfma_f32_16x16x32_bf16 v[72:75], v[20:23], v[32:35], v[72:75]
	v_mfma_f32_16x16x32_bf16 v[72:75], v[16:19], v[36:39], v[72:75]
	v_mfma_f32_16x16x32_bf16 v[44:47], v[12:15], v[44:47], 0
	v_mfma_f32_16x16x32_bf16 v[40:43], v[8:11], v[40:43], v[44:47]
	s_nop 5
	v_mul_f32_e32 v72, v68, v72
	v_mul_f32_e32 v72, v80, v72
	v_add_u32_e32 v80, 0x2000, v242
	ds_write2_b32 v80, v76, v72 offset0:60 offset1:76
	v_mul_f32_e32 v72, v69, v73
	v_sub_f32_e32 v73, v65, v147
	v_mul_f32_e32 v73, 0x3fb8aa3b, v73
	v_exp_f32_e32 v73, v73
	v_sub_f32_e32 v65, v65, v144
	v_mul_f32_e32 v65, 0x3fb8aa3b, v65
	v_exp_f32_e32 v65, v65
	v_mul_f32_e32 v76, v73, v72
	v_sub_f32_e32 v73, v66, v147
	v_mul_f32_e32 v73, 0x3fb8aa3b, v73
	v_exp_f32_e32 v73, v73
	v_mul_f32_e32 v72, v70, v74
	v_mfma_f32_16x16x32_bf16 v[52:55], v[0:3], v[52:55], v[56:59]
	v_mul_f32_e32 v72, v73, v72
	v_sub_f32_e32 v73, v67, v147
	v_mul_f32_e32 v73, 0x3fb8aa3b, v73
	v_exp_f32_e32 v73, v73
	ds_write2_b32 v80, v78, v72 offset0:196 offset1:212
	v_mul_f32_e32 v72, v71, v75
	v_mfma_f32_16x16x32_bf16 v[32:35], v[0:3], v[32:35], v[40:43]
	v_mul_f32_e32 v78, v73, v72
	v_mfma_f32_16x16x32_bf16 v[72:75], v[28:31], v[28:31], 0
	v_mfma_f32_16x16x32_bf16 v[72:75], v[24:27], v[24:27], v[72:75]
	v_mfma_f32_16x16x32_bf16 v[72:75], v[20:23], v[20:23], v[72:75]
	v_mfma_f32_16x16x32_bf16 v[72:75], v[16:19], v[16:19], v[72:75]
	v_mfma_f32_16x16x32_bf16 v[28:31], v[12:15], v[28:31], 0
	v_mfma_f32_16x16x32_bf16 v[12:15], v[12:15], v[12:15], 0
	s_nop 5
	v_mul_f32_e32 v68, v68, v72
	v_mul_f32_e32 v64, v64, v68
	v_cndmask_b32_e64 v64, 0, v64, s[30:31]
	ds_write2_b32 v80, v64, v77 offset0:92 offset1:128
	v_mul_f32_e32 v64, v69, v73
	v_mul_f32_e32 v64, v65, v64
	v_sub_f32_e32 v65, v66, v144
	v_mul_f32_e32 v65, 0x3fb8aa3b, v65
	v_exp_f32_e32 v65, v65
	v_cndmask_b32_e64 v64, 0, v64, s[44:45]
	ds_write2_b32 v80, v76, v64 offset0:144 offset1:160
	v_mul_f32_e32 v64, v70, v74
	v_mul_f32_e32 v64, v65, v64
	v_cndmask_b32_e64 v64, 0, v64, s[46:47]
	v_add_u32_e32 v65, 0x2200, v242
	ds_write2_b32 v65, v64, v79 offset0:100 offset1:136
	v_sub_f32_e32 v65, v67, v144
	v_mul_f32_e32 v65, 0x3fb8aa3b, v65
	v_exp_f32_e32 v65, v65
	v_mul_f32_e32 v64, v71, v75
	v_mfma_f32_16x16x32_bf16 v[24:27], v[8:11], v[24:27], v[28:31]
	v_mul_f32_e32 v64, v65, v64
	v_cndmask_b32_e64 v64, 0, v64, s[48:49]
	v_mfma_f32_16x16x32_bf16 v[8:11], v[8:11], v[8:11], v[12:15]
	v_add_u32_e32 v65, 0x2400, v242
	ds_write2_b32 v65, v78, v64 offset0:24 offset1:40
	ds_read_b128 v[64:67], v148 offset:17600
	ds_read_b128 v[68:71], v148 offset:17856
	v_mfma_f32_16x16x32_bf16 v[20:23], v[0:3], v[20:23], v[24:27]
	v_mfma_f32_16x16x32_bf16 v[0:3], v[0:3], v[0:3], v[8:11]
	v_mfma_f32_16x16x32_bf16 v[48:51], v[4:7], v[48:51], v[52:55]
	v_mfma_f32_16x16x32_bf16 v[32:35], v[4:7], v[36:39], v[32:35]
	s_waitcnt lgkmcnt(1)
	v_sub_f32_e32 v36, v64, v147
	v_mul_f32_e32 v36, 0x3fb8aa3b, v36
	v_sub_f32_e32 v52, v64, v146
	v_mfma_f32_16x16x32_bf16 v[16:19], v[4:7], v[16:19], v[20:23]
	v_exp_f32_e32 v36, v36
	v_mul_f32_e32 v52, 0x3fb8aa3b, v52
	v_exp_f32_e32 v52, v52
	v_mfma_f32_16x16x32_bf16 v[0:3], v[4:7], v[4:7], v[0:3]
	v_sub_f32_e32 v4, v64, v145
	v_sub_f32_e32 v20, v64, v144
	v_mul_f32_e32 v4, 0x3fb8aa3b, v4
	v_mul_f32_e32 v20, 0x3fb8aa3b, v20
	v_exp_f32_e32 v4, v4
	v_exp_f32_e32 v20, v20
	s_waitcnt lgkmcnt(0)
	s_nop 0
	v_mul_f32_e32 v0, v68, v0
	v_mul_f32_e32 v32, v68, v32
	v_mul_f32_e32 v16, v68, v16
	v_mul_f32_e32 v0, v4, v0
	v_mul_f32_e32 v32, v36, v32
	v_add_u32_e32 v36, 0x3000, v242
	v_mul_f32_e32 v16, v20, v16
	v_cndmask_b32_e64 v0, 0, v0, s[30:31]
	v_mul_f32_e32 v48, v68, v48
	ds_write2_b32 v36, v16, v0 offset0:156 offset1:172
	v_mul_f32_e32 v0, v69, v1
	v_sub_f32_e32 v1, v65, v145
	v_mul_f32_e32 v48, v52, v48
	v_sub_f32_e32 v52, v65, v146
	v_sub_f32_e32 v20, v65, v144
	v_mul_f32_e32 v1, 0x3fb8aa3b, v1
	v_mul_f32_e32 v52, 0x3fb8aa3b, v52
	v_mul_f32_e32 v20, 0x3fb8aa3b, v20
	v_exp_f32_e32 v1, v1
	v_exp_f32_e32 v52, v52
	v_exp_f32_e32 v20, v20
	ds_write2_b32 v36, v48, v32 offset0:124 offset1:140
	v_mul_f32_e32 v32, v69, v33
	v_sub_f32_e32 v33, v65, v147
	v_mul_f32_e32 v33, 0x3fb8aa3b, v33
	v_mul_f32_e32 v49, v69, v49
	v_exp_f32_e32 v33, v33
	v_mul_f32_e32 v17, v69, v17
	v_mul_f32_e32 v0, v1, v0
	v_sub_f32_e32 v1, v66, v145
	v_mul_f32_e32 v49, v52, v49
	v_sub_f32_e32 v52, v66, v146
	v_mul_f32_e32 v17, v20, v17
	v_sub_f32_e32 v20, v66, v144
	v_mul_f32_e32 v1, 0x3fb8aa3b, v1
	v_mul_f32_e32 v52, 0x3fb8aa3b, v52
	v_mul_f32_e32 v20, 0x3fb8aa3b, v20
	v_exp_f32_e32 v1, v1
	v_exp_f32_e32 v52, v52
	v_exp_f32_e32 v20, v20
	v_mul_f32_e32 v32, v33, v32
	v_sub_f32_e32 v33, v66, v147
	v_cndmask_b32_e64 v0, 0, v0, s[50:51]
	v_mul_f32_e32 v33, 0x3fb8aa3b, v33
	ds_write2_b32 v36, v17, v0 offset0:224 offset1:240
	v_mul_f32_e32 v0, v70, v2
	v_mul_f32_e32 v50, v70, v50
	v_exp_f32_e32 v33, v33
	v_mul_f32_e32 v18, v70, v18
	v_mul_f32_e32 v0, v1, v0
	v_sub_f32_e32 v1, v67, v145
	v_mul_f32_e32 v50, v52, v50
	v_sub_f32_e32 v52, v67, v146
	ds_write2_b32 v36, v49, v32 offset0:192 offset1:208
	v_mul_f32_e32 v32, v70, v34
	v_sub_f32_e32 v34, v67, v147
	v_mul_f32_e32 v18, v20, v18
	v_sub_f32_e32 v20, v67, v144
	v_mul_f32_e32 v1, 0x3fb8aa3b, v1
	v_mul_f32_e32 v52, 0x3fb8aa3b, v52
	v_mul_f32_e32 v34, 0x3fb8aa3b, v34
	v_mul_f32_e32 v20, 0x3fb8aa3b, v20
	v_exp_f32_e32 v1, v1
	v_exp_f32_e32 v52, v52
	v_exp_f32_e32 v34, v34
	v_exp_f32_e32 v20, v20
	v_mul_f32_e32 v32, v33, v32
	v_add_u32_e32 v33, 0x3400, v242
	v_cndmask_b32_e64 v0, 0, v0, s[52:53]
	ds_write2_b32 v33, v18, v0 offset0:36 offset1:52
	v_mul_f32_e32 v0, v71, v3
	v_mul_f32_e32 v51, v71, v51
	ds_write2_b32 v33, v50, v32 offset0:4 offset1:20
	v_mul_f32_e32 v32, v71, v35
	v_mul_f32_e32 v19, v71, v19
	v_mul_f32_e32 v0, v1, v0
	v_mul_f32_e32 v51, v52, v51
	v_mul_f32_e32 v32, v34, v32
	v_mul_f32_e32 v19, v20, v19
	v_cndmask_b32_e64 v0, 0, v0, s[54:55]
	ds_write2_b32 v33, v51, v32 offset0:72 offset1:88
	ds_write2_b32 v33, v19, v0 offset0:104 offset1:120
	v_mov_b32_e32 v64, s63
	ds_read_b128 v[68:71], v64 offset:272
	ds_read_b128 v[72:75], v64 offset:544
	ds_read_b128 v[76:79], v64 offset:816
	ds_read_b128 v[80:83], v64 offset:1088
	ds_read_b128 v[84:87], v64 offset:1360
	ds_read_b128 v[88:91], v64 offset:1632
	ds_read_b128 v[92:95], v64 offset:1376
	ds_read_b128 v[96:99], v64 offset:1648
	ds_read_b128 v[100:103], v64 offset:1904
	ds_read_b128 v[104:107], v64 offset:2176
	ds_read_b128 v[108:111], v64 offset:1920
	ds_read_b128 v[112:115], v64 offset:2192
	s_waitcnt lgkmcnt(11)
	v_fma_f32 v1, -v68, v153, v154
	ds_read_b128 v[68:71], v64 offset:2448
	s_waitcnt lgkmcnt(11)
	v_fma_f32 v2, -v72, v153, v155
	v_fma_f32 v2, -v73, v1, v2
	ds_read_b128 v[72:75], v64 offset:2720
	s_waitcnt lgkmcnt(11)
	v_fma_f32 v3, -v76, v153, v156
	v_fma_f32 v3, -v77, v1, v3
	v_fma_f32 v3, -v78, v2, v3
	ds_read_b128 v[76:79], v64 offset:2464
	s_waitcnt lgkmcnt(11)
	v_fma_f32 v4, -v80, v153, v157
	v_fma_f32 v4, -v81, v1, v4
	v_fma_f32 v4, -v82, v2, v4
	v_fma_f32 v4, -v83, v3, v4
	ds_read_b128 v[80:83], v64 offset:2736
	s_waitcnt lgkmcnt(11)
	v_fma_f32 v5, -v84, v153, v158
	v_fma_f32 v5, -v85, v1, v5
	v_fma_f32 v5, -v86, v2, v5
	v_fma_f32 v5, -v87, v3, v5
	ds_read_b128 v[84:87], v64 offset:2480
	s_waitcnt lgkmcnt(11)
	v_fma_f32 v6, -v88, v153, v159
	v_fma_f32 v6, -v89, v1, v6
	v_fma_f32 v6, -v90, v2, v6
	v_fma_f32 v6, -v91, v3, v6
	ds_read_b128 v[88:91], v64 offset:2752
	s_waitcnt lgkmcnt(11)
	v_fma_f32 v5, -v92, v4, v5
	ds_read_b128 v[92:95], v64 offset:2992
	s_waitcnt lgkmcnt(11)
	v_fma_f32 v6, -v96, v4, v6
	v_fma_f32 v6, -v97, v5, v6
	ds_read_b128 v[96:99], v64 offset:3264
	s_waitcnt lgkmcnt(11)
	v_fma_f32 v7, -v100, v153, v160
	v_fma_f32 v7, -v101, v1, v7
	v_fma_f32 v7, -v102, v2, v7
	v_fma_f32 v7, -v103, v3, v7
	ds_read_b128 v[100:103], v64 offset:3008
	s_waitcnt lgkmcnt(11)
	v_fma_f32 v8, -v104, v153, v161
	v_fma_f32 v8, -v105, v1, v8
	v_fma_f32 v8, -v106, v2, v8
	v_fma_f32 v8, -v107, v3, v8
	ds_read_b128 v[104:107], v64 offset:3280
	s_waitcnt lgkmcnt(11)
	v_fma_f32 v7, -v108, v4, v7
	v_fma_f32 v7, -v109, v5, v7
	v_fma_f32 v7, -v110, v6, v7
	ds_read_b128 v[108:111], v64 offset:3024
	s_waitcnt lgkmcnt(11)
	v_fma_f32 v8, -v112, v4, v8
	v_fma_f32 v8, -v113, v5, v8
	v_fma_f32 v8, -v114, v6, v8
	v_fma_f32 v8, -v115, v7, v8
	ds_read_b128 v[112:115], v64 offset:3296
	s_waitcnt lgkmcnt(11)
	v_fma_f32 v9, -v68, v153, v162
	v_fma_f32 v9, -v69, v1, v9
	v_fma_f32 v9, -v70, v2, v9
	v_fma_f32 v9, -v71, v3, v9
	ds_read_b128 v[68:71], v64 offset:3536
	s_waitcnt lgkmcnt(11)
	v_fma_f32 v10, -v72, v153, v163
	v_fma_f32 v10, -v73, v1, v10
	v_fma_f32 v10, -v74, v2, v10
	v_fma_f32 v10, -v75, v3, v10
	ds_read_b128 v[72:75], v64 offset:3808
	s_waitcnt lgkmcnt(11)
	v_fma_f32 v9, -v76, v4, v9
	v_fma_f32 v9, -v77, v5, v9
	v_fma_f32 v9, -v78, v6, v9
	v_fma_f32 v9, -v79, v7, v9
	ds_read_b128 v[76:79], v64 offset:3552
	s_waitcnt lgkmcnt(11)
	v_fma_f32 v10, -v80, v4, v10
	v_fma_f32 v10, -v81, v5, v10
	v_fma_f32 v10, -v82, v6, v10
	v_fma_f32 v10, -v83, v7, v10
	ds_read_b128 v[80:83], v64 offset:3824
	s_waitcnt lgkmcnt(11)
	v_fma_f32 v9, -v84, v8, v9
	ds_read_b128 v[84:87], v64 offset:3568
	s_waitcnt lgkmcnt(11)
	v_fma_f32 v10, -v88, v8, v10
	v_fma_f32 v10, -v89, v9, v10
	ds_read_b128 v[88:91], v64 offset:3840
	s_waitcnt lgkmcnt(11)
	v_fma_f32 v11, -v92, v153, v164
	v_fma_f32 v11, -v93, v1, v11
	v_fma_f32 v11, -v94, v2, v11
	v_fma_f32 v11, -v95, v3, v11
	ds_read_b128 v[92:95], v64 offset:3584
	s_waitcnt lgkmcnt(11)
	v_fma_f32 v12, -v96, v153, v165
	v_fma_f32 v12, -v97, v1, v12
	v_fma_f32 v12, -v98, v2, v12
	v_fma_f32 v12, -v99, v3, v12
	ds_read_b128 v[96:99], v64 offset:3856
	s_waitcnt lgkmcnt(11)
	v_fma_f32 v11, -v100, v4, v11
	v_fma_f32 v11, -v101, v5, v11
	v_fma_f32 v11, -v102, v6, v11
	v_fma_f32 v11, -v103, v7, v11
	ds_read_b128 v[100:103], v64 offset:4080
	s_waitcnt lgkmcnt(11)
	v_fma_f32 v12, -v104, v4, v12
	v_fma_f32 v12, -v105, v5, v12
	v_fma_f32 v12, -v106, v6, v12
	v_fma_f32 v12, -v107, v7, v12
	ds_read_b128 v[104:107], v64 offset:4352
	s_waitcnt lgkmcnt(11)
	v_fma_f32 v11, -v108, v8, v11
	v_fma_f32 v11, -v109, v9, v11
	v_fma_f32 v11, -v110, v10, v11
	ds_read_b128 v[108:111], v64 offset:4096
	s_waitcnt lgkmcnt(11)
	v_fma_f32 v12, -v112, v8, v12
	v_fma_f32 v12, -v113, v9, v12
	v_fma_f32 v12, -v114, v10, v12
	v_fma_f32 v12, -v115, v11, v12
	ds_read_b128 v[112:115], v64 offset:4368
	s_waitcnt lgkmcnt(11)
	v_fma_f32 v13, -v68, v153, v166
	v_fma_f32 v13, -v69, v1, v13
	v_fma_f32 v13, -v70, v2, v13
	v_fma_f32 v13, -v71, v3, v13
	ds_read_b128 v[68:71], v64 offset:4112
	s_waitcnt lgkmcnt(11)
	v_fma_f32 v14, -v72, v153, v167
	v_fma_f32 v14, -v73, v1, v14
	v_fma_f32 v14, -v74, v2, v14
	v_fma_f32 v14, -v75, v3, v14
	ds_read_b128 v[72:75], v64 offset:4384
	s_waitcnt lgkmcnt(11)
	v_fma_f32 v13, -v76, v4, v13
	v_fma_f32 v13, -v77, v5, v13
	v_fma_f32 v13, -v78, v6, v13
	v_fma_f32 v13, -v79, v7, v13
	ds_read_b128 v[76:79], v64 offset:4128
	s_waitcnt lgkmcnt(11)
	v_fma_f32 v14, -v80, v4, v14
	v_fma_f32 v14, -v81, v5, v14
	v_fma_f32 v14, -v82, v6, v14
	v_fma_f32 v14, -v83, v7, v14
	ds_read_b128 v[80:83], v64 offset:4400
	s_waitcnt lgkmcnt(11)
	v_fma_f32 v13, -v84, v8, v13
	v_fma_f32 v13, -v85, v9, v13
	v_fma_f32 v13, -v86, v10, v13
	v_fma_f32 v13, -v87, v11, v13
	ds_read_b128 v[84:87], v64 offset:4624
	s_waitcnt lgkmcnt(11)
	v_fma_f32 v14, -v88, v8, v14
	v_fma_f32 v14, -v89, v9, v14
	v_fma_f32 v14, -v90, v10, v14
	v_fma_f32 v14, -v91, v11, v14
	ds_read_b128 v[88:91], v64 offset:4896
	s_waitcnt lgkmcnt(11)
	v_fma_f32 v13, -v92, v12, v13
	ds_read_b128 v[92:95], v64 offset:4640
	s_waitcnt lgkmcnt(11)
	v_fma_f32 v14, -v96, v12, v14
	v_fma_f32 v14, -v97, v13, v14
	ds_read_b128 v[96:99], v64 offset:4912
	s_waitcnt lgkmcnt(11)
	v_fma_f32 v15, -v100, v153, v168
	v_fma_f32 v15, -v101, v1, v15
	v_fma_f32 v15, -v102, v2, v15
	v_fma_f32 v15, -v103, v3, v15
	ds_read_b128 v[100:103], v64 offset:4656
	s_waitcnt lgkmcnt(11)
	v_fma_f32 v16, -v104, v153, v169
	v_fma_f32 v16, -v105, v1, v16
	v_fma_f32 v16, -v106, v2, v16
	v_fma_f32 v16, -v107, v3, v16
	ds_read_b128 v[104:107], v64 offset:4928
	s_waitcnt lgkmcnt(11)
	v_fma_f32 v15, -v108, v4, v15
	v_fma_f32 v15, -v109, v5, v15
	v_fma_f32 v15, -v110, v6, v15
	v_fma_f32 v15, -v111, v7, v15
	ds_read_b128 v[108:111], v64 offset:4672
	s_waitcnt lgkmcnt(11)
	v_fma_f32 v16, -v112, v4, v16
	v_fma_f32 v16, -v113, v5, v16
	v_fma_f32 v16, -v114, v6, v16
	v_fma_f32 v16, -v115, v7, v16
	ds_read_b128 v[112:115], v64 offset:4944
	s_waitcnt lgkmcnt(11)
	v_fma_f32 v15, -v68, v8, v15
	v_fma_f32 v15, -v69, v9, v15
	v_fma_f32 v15, -v70, v10, v15
	v_fma_f32 v15, -v71, v11, v15
	ds_read_b128 v[68:71], v64 offset:4688
	s_waitcnt lgkmcnt(11)
	v_fma_f32 v16, -v72, v8, v16
	v_fma_f32 v16, -v73, v9, v16
	v_fma_f32 v16, -v74, v10, v16
	v_fma_f32 v16, -v75, v11, v16
	ds_read_b128 v[72:75], v64 offset:4960
	s_waitcnt lgkmcnt(11)
	v_fma_f32 v15, -v76, v12, v15
	v_fma_f32 v15, -v77, v13, v15
	v_fma_f32 v15, -v78, v14, v15
	ds_read_b128 v[76:79], v64 offset:5168
	s_waitcnt lgkmcnt(11)
	v_fma_f32 v16, -v80, v12, v16
	v_fma_f32 v16, -v81, v13, v16
	v_fma_f32 v16, -v82, v14, v16
	v_fma_f32 v16, -v83, v15, v16
	ds_read_b128 v[80:83], v64 offset:5440
	s_waitcnt lgkmcnt(11)
	v_fma_f32 v17, -v84, v153, v170
	v_fma_f32 v17, -v85, v1, v17
	v_fma_f32 v17, -v86, v2, v17
	v_fma_f32 v17, -v87, v3, v17
	ds_read_b128 v[84:87], v64 offset:5184
	s_waitcnt lgkmcnt(11)
	v_fma_f32 v18, -v88, v153, v171
	v_fma_f32 v18, -v89, v1, v18
	v_fma_f32 v18, -v90, v2, v18
	v_fma_f32 v18, -v91, v3, v18
	ds_read_b128 v[88:91], v64 offset:5456
	s_waitcnt lgkmcnt(11)
	v_fma_f32 v17, -v92, v4, v17
	v_fma_f32 v17, -v93, v5, v17
	v_fma_f32 v17, -v94, v6, v17
	v_fma_f32 v17, -v95, v7, v17
	ds_read_b128 v[92:95], v64 offset:5200
	s_waitcnt lgkmcnt(11)
	v_fma_f32 v18, -v96, v4, v18
	v_fma_f32 v18, -v97, v5, v18
	v_fma_f32 v18, -v98, v6, v18
	v_fma_f32 v18, -v99, v7, v18
	ds_read_b128 v[96:99], v64 offset:5472
	s_waitcnt lgkmcnt(11)
	v_fma_f32 v17, -v100, v8, v17
	v_fma_f32 v17, -v101, v9, v17
	v_fma_f32 v17, -v102, v10, v17
	v_fma_f32 v17, -v103, v11, v17
	ds_read_b128 v[100:103], v64 offset:5216
	s_waitcnt lgkmcnt(11)
	v_fma_f32 v18, -v104, v8, v18
	v_fma_f32 v18, -v105, v9, v18
	v_fma_f32 v18, -v106, v10, v18
	v_fma_f32 v18, -v107, v11, v18
	ds_read_b128 v[104:107], v64 offset:5488
	s_waitcnt lgkmcnt(11)
	v_fma_f32 v17, -v108, v12, v17
	v_fma_f32 v17, -v109, v13, v17
	v_fma_f32 v17, -v110, v14, v17
	v_fma_f32 v17, -v111, v15, v17
	ds_read_b128 v[108:111], v64 offset:5232
	s_waitcnt lgkmcnt(11)
	v_fma_f32 v18, -v112, v12, v18
	v_fma_f32 v18, -v113, v13, v18
	v_fma_f32 v18, -v114, v14, v18
	v_fma_f32 v18, -v115, v15, v18
	ds_read_b128 v[112:115], v64 offset:5504
	s_waitcnt lgkmcnt(11)
	v_fma_f32 v17, -v68, v16, v17
	ds_read_b128 v[68:71], v64 offset:5712
	s_waitcnt lgkmcnt(11)
	v_fma_f32 v18, -v72, v16, v18
	v_fma_f32 v18, -v73, v17, v18
	ds_read_b128 v[72:75], v64 offset:5984
	s_waitcnt lgkmcnt(11)
	v_fma_f32 v19, -v76, v153, v172
	v_fma_f32 v19, -v77, v1, v19
	v_fma_f32 v19, -v78, v2, v19
	v_fma_f32 v19, -v79, v3, v19
	ds_read_b128 v[76:79], v64 offset:5728
	s_waitcnt lgkmcnt(11)
	v_fma_f32 v20, -v80, v153, v173
	v_fma_f32 v20, -v81, v1, v20
	v_fma_f32 v20, -v82, v2, v20
	v_fma_f32 v20, -v83, v3, v20
	ds_read_b128 v[80:83], v64 offset:6000
	s_waitcnt lgkmcnt(11)
	v_fma_f32 v19, -v84, v4, v19
	v_fma_f32 v19, -v85, v5, v19
	v_fma_f32 v19, -v86, v6, v19
	v_fma_f32 v19, -v87, v7, v19
	ds_read_b128 v[84:87], v64 offset:5744
	s_waitcnt lgkmcnt(11)
	v_fma_f32 v20, -v88, v4, v20
	v_fma_f32 v20, -v89, v5, v20
	v_fma_f32 v20, -v90, v6, v20
	v_fma_f32 v20, -v91, v7, v20
	ds_read_b128 v[88:91], v64 offset:6016
	s_waitcnt lgkmcnt(11)
	v_fma_f32 v19, -v92, v8, v19
	v_fma_f32 v19, -v93, v9, v19
	v_fma_f32 v19, -v94, v10, v19
	v_fma_f32 v19, -v95, v11, v19
	ds_read_b128 v[92:95], v64 offset:5760
	s_waitcnt lgkmcnt(11)
	v_fma_f32 v20, -v96, v8, v20
	v_fma_f32 v20, -v97, v9, v20
	v_fma_f32 v20, -v98, v10, v20
	v_fma_f32 v20, -v99, v11, v20
	ds_read_b128 v[96:99], v64 offset:6032
	s_waitcnt lgkmcnt(11)
	v_fma_f32 v19, -v100, v12, v19
	v_fma_f32 v19, -v101, v13, v19
	v_fma_f32 v19, -v102, v14, v19
	v_fma_f32 v19, -v103, v15, v19
	ds_read_b128 v[100:103], v64 offset:5776
	s_waitcnt lgkmcnt(11)
	v_fma_f32 v20, -v104, v12, v20
	v_fma_f32 v20, -v105, v13, v20
	v_fma_f32 v20, -v106, v14, v20
	v_fma_f32 v20, -v107, v15, v20
	ds_read_b128 v[104:107], v64 offset:6048
	s_waitcnt lgkmcnt(11)
	v_fma_f32 v19, -v108, v16, v19
	v_fma_f32 v19, -v109, v17, v19
	v_fma_f32 v19, -v110, v18, v19
	ds_read_b128 v[108:111], v64 offset:5792
	s_waitcnt lgkmcnt(11)
	v_fma_f32 v20, -v112, v16, v20
	v_fma_f32 v20, -v113, v17, v20
	v_fma_f32 v20, -v114, v18, v20
	v_fma_f32 v20, -v115, v19, v20
	ds_read_b128 v[112:115], v64 offset:6064
	s_waitcnt lgkmcnt(11)
	v_fma_f32 v21, -v68, v153, v174
	v_fma_f32 v21, -v69, v1, v21
	v_fma_f32 v21, -v70, v2, v21
	v_fma_f32 v21, -v71, v3, v21
	ds_read_b128 v[68:71], v64 offset:6256
	s_waitcnt lgkmcnt(11)
	v_fma_f32 v22, -v72, v153, v175
	v_fma_f32 v22, -v73, v1, v22
	v_fma_f32 v22, -v74, v2, v22
	v_fma_f32 v22, -v75, v3, v22
	ds_read_b128 v[72:75], v64 offset:6528
	s_waitcnt lgkmcnt(11)
	v_fma_f32 v21, -v76, v4, v21
	v_fma_f32 v21, -v77, v5, v21
	v_fma_f32 v21, -v78, v6, v21
	v_fma_f32 v21, -v79, v7, v21
	ds_read_b128 v[76:79], v64 offset:6272
	s_waitcnt lgkmcnt(11)
	v_fma_f32 v22, -v80, v4, v22
	v_fma_f32 v22, -v81, v5, v22
	v_fma_f32 v22, -v82, v6, v22
	v_fma_f32 v22, -v83, v7, v22
	ds_read_b128 v[80:83], v64 offset:6544
	s_waitcnt lgkmcnt(11)
	v_fma_f32 v21, -v84, v8, v21
	v_fma_f32 v21, -v85, v9, v21
	v_fma_f32 v21, -v86, v10, v21
	v_fma_f32 v21, -v87, v11, v21
	ds_read_b128 v[84:87], v64 offset:6288
	s_waitcnt lgkmcnt(11)
	v_fma_f32 v22, -v88, v8, v22
	v_fma_f32 v22, -v89, v9, v22
	v_fma_f32 v22, -v90, v10, v22
	v_fma_f32 v22, -v91, v11, v22
	ds_read_b128 v[88:91], v64 offset:6560
	s_waitcnt lgkmcnt(11)
	v_fma_f32 v21, -v92, v12, v21
	v_fma_f32 v21, -v93, v13, v21
	v_fma_f32 v21, -v94, v14, v21
	v_fma_f32 v21, -v95, v15, v21
	ds_read_b128 v[92:95], v64 offset:6304
	s_waitcnt lgkmcnt(11)
	v_fma_f32 v22, -v96, v12, v22
	v_fma_f32 v22, -v97, v13, v22
	v_fma_f32 v22, -v98, v14, v22
	v_fma_f32 v22, -v99, v15, v22
	ds_read_b128 v[96:99], v64 offset:6576
	s_waitcnt lgkmcnt(11)
	v_fma_f32 v21, -v100, v16, v21
	v_fma_f32 v21, -v101, v17, v21
	v_fma_f32 v21, -v102, v18, v21
	v_fma_f32 v21, -v103, v19, v21
	ds_read_b128 v[100:103], v64 offset:6320
	s_waitcnt lgkmcnt(11)
	v_fma_f32 v22, -v104, v16, v22
	v_fma_f32 v22, -v105, v17, v22
	v_fma_f32 v22, -v106, v18, v22
	v_fma_f32 v22, -v107, v19, v22
	ds_read_b128 v[104:107], v64 offset:6592
	s_waitcnt lgkmcnt(11)
	v_fma_f32 v21, -v108, v20, v21
	ds_read_b128 v[108:111], v64 offset:6336
	s_waitcnt lgkmcnt(11)
	v_fma_f32 v22, -v112, v20, v22
	v_fma_f32 v22, -v113, v21, v22
	ds_read_b128 v[112:115], v64 offset:6608
	s_waitcnt lgkmcnt(11)
	v_fma_f32 v23, -v68, v153, v176
	v_fma_f32 v23, -v69, v1, v23
	v_fma_f32 v23, -v70, v2, v23
	v_fma_f32 v23, -v71, v3, v23
	ds_read_b128 v[68:71], v64 offset:6800
	s_waitcnt lgkmcnt(11)
	v_fma_f32 v24, -v72, v153, v177
	v_fma_f32 v24, -v73, v1, v24
	v_fma_f32 v24, -v74, v2, v24
	v_fma_f32 v24, -v75, v3, v24
	ds_read_b128 v[72:75], v64 offset:7072
	s_waitcnt lgkmcnt(11)
	v_fma_f32 v23, -v76, v4, v23
	v_fma_f32 v23, -v77, v5, v23
	v_fma_f32 v23, -v78, v6, v23
	v_fma_f32 v23, -v79, v7, v23
	ds_read_b128 v[76:79], v64 offset:6816
	s_waitcnt lgkmcnt(11)
	v_fma_f32 v24, -v80, v4, v24
	v_fma_f32 v24, -v81, v5, v24
	v_fma_f32 v24, -v82, v6, v24
	v_fma_f32 v24, -v83, v7, v24
	ds_read_b128 v[80:83], v64 offset:7088
	s_waitcnt lgkmcnt(11)
	v_fma_f32 v23, -v84, v8, v23
	v_fma_f32 v23, -v85, v9, v23
	v_fma_f32 v23, -v86, v10, v23
	v_fma_f32 v23, -v87, v11, v23
	ds_read_b128 v[84:87], v64 offset:6832
	s_waitcnt lgkmcnt(11)
	v_fma_f32 v24, -v88, v8, v24
	v_fma_f32 v24, -v89, v9, v24
	v_fma_f32 v24, -v90, v10, v24
	v_fma_f32 v24, -v91, v11, v24
	ds_read_b128 v[88:91], v64 offset:7104
	s_waitcnt lgkmcnt(11)
	v_fma_f32 v23, -v92, v12, v23
	v_fma_f32 v23, -v93, v13, v23
	v_fma_f32 v23, -v94, v14, v23
	v_fma_f32 v23, -v95, v15, v23
	ds_read_b128 v[92:95], v64 offset:6848
	s_waitcnt lgkmcnt(11)
	v_fma_f32 v24, -v96, v12, v24
	v_fma_f32 v24, -v97, v13, v24
	v_fma_f32 v24, -v98, v14, v24
	v_fma_f32 v24, -v99, v15, v24
	ds_read_b128 v[96:99], v64 offset:7120
	s_waitcnt lgkmcnt(11)
	v_fma_f32 v23, -v100, v16, v23
	v_fma_f32 v23, -v101, v17, v23
	v_fma_f32 v23, -v102, v18, v23
	v_fma_f32 v23, -v103, v19, v23
	ds_read_b128 v[100:103], v64 offset:6864
	s_waitcnt lgkmcnt(11)
	v_fma_f32 v24, -v104, v16, v24
	v_fma_f32 v24, -v105, v17, v24
	v_fma_f32 v24, -v106, v18, v24
	v_fma_f32 v24, -v107, v19, v24
	ds_read_b128 v[104:107], v64 offset:7136
	s_waitcnt lgkmcnt(11)
	v_fma_f32 v23, -v108, v20, v23
	v_fma_f32 v23, -v109, v21, v23
	v_fma_f32 v23, -v110, v22, v23
	ds_read_b128 v[108:111], v64 offset:6880
	s_waitcnt lgkmcnt(11)
	v_fma_f32 v24, -v112, v20, v24
	v_fma_f32 v24, -v113, v21, v24
	v_fma_f32 v24, -v114, v22, v24
	v_fma_f32 v24, -v115, v23, v24
	ds_read_b128 v[112:115], v64 offset:7152
	s_waitcnt lgkmcnt(11)
	v_fma_f32 v25, -v68, v153, v178
	v_fma_f32 v25, -v69, v1, v25
	v_fma_f32 v25, -v70, v2, v25
	v_fma_f32 v25, -v71, v3, v25
	ds_read_b128 v[68:71], v64 offset:6896
	s_waitcnt lgkmcnt(11)
	v_fma_f32 v26, -v72, v153, v179
	v_fma_f32 v26, -v73, v1, v26
	v_fma_f32 v26, -v74, v2, v26
	v_fma_f32 v26, -v75, v3, v26
	ds_read_b128 v[72:75], v64 offset:7168
	s_waitcnt lgkmcnt(11)
	v_fma_f32 v25, -v76, v4, v25
	v_fma_f32 v25, -v77, v5, v25
	v_fma_f32 v25, -v78, v6, v25
	v_fma_f32 v25, -v79, v7, v25
	ds_read_b128 v[76:79], v64 offset:7344
	s_waitcnt lgkmcnt(11)
	v_fma_f32 v26, -v80, v4, v26
	v_fma_f32 v26, -v81, v5, v26
	v_fma_f32 v26, -v82, v6, v26
	v_fma_f32 v26, -v83, v7, v26
	ds_read_b128 v[80:83], v64 offset:7616
	s_waitcnt lgkmcnt(11)
	v_fma_f32 v25, -v84, v8, v25
	v_fma_f32 v25, -v85, v9, v25
	v_fma_f32 v25, -v86, v10, v25
	v_fma_f32 v25, -v87, v11, v25
	ds_read_b128 v[84:87], v64 offset:7360
	s_waitcnt lgkmcnt(11)
	v_fma_f32 v26, -v88, v8, v26
	v_fma_f32 v26, -v89, v9, v26
	v_fma_f32 v26, -v90, v10, v26
	v_fma_f32 v26, -v91, v11, v26
	ds_read_b128 v[88:91], v64 offset:7632
	s_waitcnt lgkmcnt(11)
	v_fma_f32 v25, -v92, v12, v25
	v_fma_f32 v25, -v93, v13, v25
	v_fma_f32 v25, -v94, v14, v25
	v_fma_f32 v25, -v95, v15, v25
	ds_read_b128 v[92:95], v64 offset:7376
	s_waitcnt lgkmcnt(11)
	v_fma_f32 v26, -v96, v12, v26
	v_fma_f32 v26, -v97, v13, v26
	v_fma_f32 v26, -v98, v14, v26
	v_fma_f32 v26, -v99, v15, v26
	ds_read_b128 v[96:99], v64 offset:7648
	s_waitcnt lgkmcnt(11)
	v_fma_f32 v25, -v100, v16, v25
	v_fma_f32 v25, -v101, v17, v25
	v_fma_f32 v25, -v102, v18, v25
	v_fma_f32 v25, -v103, v19, v25
	ds_read_b128 v[100:103], v64 offset:7392
	s_waitcnt lgkmcnt(11)
	v_fma_f32 v26, -v104, v16, v26
	v_fma_f32 v26, -v105, v17, v26
	v_fma_f32 v26, -v106, v18, v26
	v_fma_f32 v26, -v107, v19, v26
	ds_read_b128 v[104:107], v64 offset:7664
	s_waitcnt lgkmcnt(11)
	v_fma_f32 v25, -v108, v20, v25
	v_fma_f32 v25, -v109, v21, v25
	v_fma_f32 v25, -v110, v22, v25
	v_fma_f32 v25, -v111, v23, v25
	ds_read_b128 v[108:111], v64 offset:7408
	s_waitcnt lgkmcnt(11)
	v_fma_f32 v26, -v112, v20, v26
	v_fma_f32 v26, -v113, v21, v26
	v_fma_f32 v26, -v114, v22, v26
	v_fma_f32 v26, -v115, v23, v26
	ds_read_b128 v[112:115], v64 offset:7680
	s_waitcnt lgkmcnt(11)
	v_fma_f32 v25, -v68, v24, v25
	ds_read_b128 v[68:71], v64 offset:7424
	s_waitcnt lgkmcnt(11)
	v_fma_f32 v26, -v72, v24, v26
	v_fma_f32 v26, -v73, v25, v26
	ds_read_b128 v[72:75], v64 offset:7696
	s_waitcnt lgkmcnt(11)
	v_fma_f32 v27, -v76, v153, v180
	v_fma_f32 v27, -v77, v1, v27
	v_fma_f32 v27, -v78, v2, v27
	v_fma_f32 v27, -v79, v3, v27
	ds_read_b128 v[76:79], v64 offset:7440
	s_waitcnt lgkmcnt(11)
	v_fma_f32 v28, -v80, v153, v181
	v_fma_f32 v28, -v81, v1, v28
	v_fma_f32 v28, -v82, v2, v28
	v_fma_f32 v28, -v83, v3, v28
	ds_read_b128 v[80:83], v64 offset:7712
	s_waitcnt lgkmcnt(11)
	v_fma_f32 v27, -v84, v4, v27
	v_fma_f32 v27, -v85, v5, v27
	v_fma_f32 v27, -v86, v6, v27
	v_fma_f32 v27, -v87, v7, v27
	ds_read_b128 v[84:87], v64 offset:7888
	s_waitcnt lgkmcnt(11)
	v_fma_f32 v28, -v88, v4, v28
	v_fma_f32 v28, -v89, v5, v28
	v_fma_f32 v28, -v90, v6, v28
	v_fma_f32 v28, -v91, v7, v28
	ds_read_b128 v[88:91], v64 offset:8160
	s_waitcnt lgkmcnt(11)
	v_fma_f32 v27, -v92, v8, v27
	v_fma_f32 v27, -v93, v9, v27
	v_fma_f32 v27, -v94, v10, v27
	v_fma_f32 v27, -v95, v11, v27
	ds_read_b128 v[92:95], v64 offset:7904
	s_waitcnt lgkmcnt(11)
	v_fma_f32 v28, -v96, v8, v28
	v_fma_f32 v28, -v97, v9, v28
	v_fma_f32 v28, -v98, v10, v28
	v_fma_f32 v28, -v99, v11, v28
	ds_read_b128 v[96:99], v64 offset:8176
	s_waitcnt lgkmcnt(11)
	v_fma_f32 v27, -v100, v12, v27
	v_fma_f32 v27, -v101, v13, v27
	v_fma_f32 v27, -v102, v14, v27
	v_fma_f32 v27, -v103, v15, v27
	ds_read_b128 v[100:103], v64 offset:7920
	s_waitcnt lgkmcnt(11)
	v_fma_f32 v28, -v104, v12, v28
	v_fma_f32 v28, -v105, v13, v28
	v_fma_f32 v28, -v106, v14, v28
	v_fma_f32 v28, -v107, v15, v28
	ds_read_b128 v[104:107], v64 offset:8192
	s_waitcnt lgkmcnt(11)
	v_fma_f32 v27, -v108, v16, v27
	v_fma_f32 v27, -v109, v17, v27
	v_fma_f32 v27, -v110, v18, v27
	v_fma_f32 v27, -v111, v19, v27
	ds_read_b128 v[108:111], v64 offset:7936
	s_waitcnt lgkmcnt(11)
	v_fma_f32 v28, -v112, v16, v28
	v_fma_f32 v28, -v113, v17, v28
	v_fma_f32 v28, -v114, v18, v28
	v_fma_f32 v28, -v115, v19, v28
	ds_read_b128 v[112:115], v64 offset:8208
	s_waitcnt lgkmcnt(11)
	v_fma_f32 v27, -v68, v20, v27
	v_fma_f32 v27, -v69, v21, v27
	v_fma_f32 v27, -v70, v22, v27
	v_fma_f32 v27, -v71, v23, v27
	ds_read_b128 v[68:71], v64 offset:7952
	s_waitcnt lgkmcnt(11)
	v_fma_f32 v28, -v72, v20, v28
	v_fma_f32 v28, -v73, v21, v28
	v_fma_f32 v28, -v74, v22, v28
	v_fma_f32 v28, -v75, v23, v28
	ds_read_b128 v[72:75], v64 offset:8224
	s_waitcnt lgkmcnt(11)
	v_fma_f32 v27, -v76, v24, v27
	v_fma_f32 v27, -v77, v25, v27
	v_fma_f32 v27, -v78, v26, v27
	ds_read_b128 v[76:79], v64 offset:7968
	s_waitcnt lgkmcnt(11)
	v_fma_f32 v28, -v80, v24, v28
	v_fma_f32 v28, -v81, v25, v28
	v_fma_f32 v28, -v82, v26, v28
	v_fma_f32 v28, -v83, v27, v28
	ds_read_b128 v[80:83], v64 offset:8240
	s_waitcnt lgkmcnt(11)
	v_fma_f32 v29, -v84, v153, v182
	v_fma_f32 v29, -v85, v1, v29
	v_fma_f32 v29, -v86, v2, v29
	v_fma_f32 v29, -v87, v3, v29
	ds_read_b128 v[84:87], v64 offset:7984
	s_waitcnt lgkmcnt(11)
	v_fma_f32 v30, -v88, v153, v183
	v_fma_f32 v30, -v89, v1, v30
	v_fma_f32 v30, -v90, v2, v30
	v_fma_f32 v30, -v91, v3, v30
	ds_read_b128 v[88:91], v64 offset:8256
	s_waitcnt lgkmcnt(11)
	v_fma_f32 v29, -v92, v4, v29
	v_fma_f32 v29, -v93, v5, v29
	v_fma_f32 v29, -v94, v6, v29
	v_fma_f32 v29, -v95, v7, v29
	ds_read_b128 v[92:95], v64 offset:8000
	s_waitcnt lgkmcnt(11)
	v_fma_f32 v30, -v96, v4, v30
	v_fma_f32 v30, -v97, v5, v30
	v_fma_f32 v30, -v98, v6, v30
	v_fma_f32 v30, -v99, v7, v30
	ds_read_b128 v[96:99], v64 offset:8272
	s_waitcnt lgkmcnt(11)
	v_fma_f32 v29, -v100, v8, v29
	v_fma_f32 v29, -v101, v9, v29
	v_fma_f32 v29, -v102, v10, v29
	v_fma_f32 v29, -v103, v11, v29
	ds_read_b128 v[100:103], v64 offset:8432
	s_waitcnt lgkmcnt(11)
	v_fma_f32 v30, -v104, v8, v30
	v_fma_f32 v30, -v105, v9, v30
	v_fma_f32 v30, -v106, v10, v30
	v_fma_f32 v30, -v107, v11, v30
	ds_read_b128 v[104:107], v64 offset:8704
	s_waitcnt lgkmcnt(11)
	v_fma_f32 v29, -v108, v12, v29
	v_fma_f32 v29, -v109, v13, v29
	v_fma_f32 v29, -v110, v14, v29
	v_fma_f32 v29, -v111, v15, v29
	ds_read_b128 v[108:111], v64 offset:8448
	s_waitcnt lgkmcnt(11)
	v_fma_f32 v30, -v112, v12, v30
	v_fma_f32 v30, -v113, v13, v30
	v_fma_f32 v30, -v114, v14, v30
	v_fma_f32 v30, -v115, v15, v30
	ds_read_b128 v[112:115], v64 offset:8720
	s_waitcnt lgkmcnt(11)
	v_fma_f32 v29, -v68, v16, v29
	v_fma_f32 v29, -v69, v17, v29
	v_fma_f32 v29, -v70, v18, v29
	v_fma_f32 v29, -v71, v19, v29
	ds_read_b128 v[68:71], v64 offset:8464
	s_waitcnt lgkmcnt(11)
	v_fma_f32 v30, -v72, v16, v30
	v_fma_f32 v30, -v73, v17, v30
	v_fma_f32 v30, -v74, v18, v30
	v_fma_f32 v30, -v75, v19, v30
	ds_read_b128 v[72:75], v64 offset:8736
	s_waitcnt lgkmcnt(11)
	v_fma_f32 v29, -v76, v20, v29
	v_fma_f32 v29, -v77, v21, v29
	v_fma_f32 v29, -v78, v22, v29
	v_fma_f32 v29, -v79, v23, v29
	ds_read_b128 v[76:79], v64 offset:8480
	s_waitcnt lgkmcnt(11)
	v_fma_f32 v30, -v80, v20, v30
	v_fma_f32 v30, -v81, v21, v30
	v_fma_f32 v30, -v82, v22, v30
	v_fma_f32 v30, -v83, v23, v30
	ds_read_b128 v[80:83], v64 offset:8752
	s_waitcnt lgkmcnt(11)
	v_fma_f32 v29, -v84, v24, v29
	v_fma_f32 v29, -v85, v25, v29
	v_fma_f32 v29, -v86, v26, v29
	v_fma_f32 v29, -v87, v27, v29
	ds_read_b128 v[84:87], v64 offset:8496
	s_waitcnt lgkmcnt(11)
	v_fma_f32 v30, -v88, v24, v30
	v_fma_f32 v30, -v89, v25, v30
	v_fma_f32 v30, -v90, v26, v30
	v_fma_f32 v30, -v91, v27, v30
	ds_read_b128 v[88:91], v64 offset:8768
	s_waitcnt lgkmcnt(11)
	v_fma_f32 v29, -v92, v28, v29
	ds_read_b128 v[92:95], v64 offset:8512
	s_waitcnt lgkmcnt(11)
	v_fma_f32 v30, -v96, v28, v30
	v_fma_f32 v30, -v97, v29, v30
	ds_read_b128 v[96:99], v64 offset:8784
	s_waitcnt lgkmcnt(11)
	v_fma_f32 v31, -v100, v153, v184
	v_fma_f32 v31, -v101, v1, v31
	v_fma_f32 v31, -v102, v2, v31
	v_fma_f32 v31, -v103, v3, v31
	ds_read_b128 v[100:103], v64 offset:8528
	s_waitcnt lgkmcnt(11)
	v_fma_f32 v32, -v104, v153, v185
	v_fma_f32 v32, -v105, v1, v32
	v_fma_f32 v32, -v106, v2, v32
	v_fma_f32 v32, -v107, v3, v32
	ds_read_b128 v[104:107], v64 offset:8800
	s_waitcnt lgkmcnt(11)
	v_fma_f32 v31, -v108, v4, v31
	v_fma_f32 v31, -v109, v5, v31
	v_fma_f32 v31, -v110, v6, v31
	v_fma_f32 v31, -v111, v7, v31
	ds_read_b128 v[108:111], v64 offset:8544
	s_waitcnt lgkmcnt(11)
	v_fma_f32 v32, -v112, v4, v32
	v_fma_f32 v32, -v113, v5, v32
	v_fma_f32 v32, -v114, v6, v32
	v_fma_f32 v32, -v115, v7, v32
	ds_read_b128 v[112:115], v64 offset:8816
	s_waitcnt lgkmcnt(11)
	v_fma_f32 v31, -v68, v8, v31
	v_fma_f32 v31, -v69, v9, v31
	v_fma_f32 v31, -v70, v10, v31
	v_fma_f32 v31, -v71, v11, v31
	ds_read_b128 v[68:71], v64 offset:8976
	s_waitcnt lgkmcnt(11)
	v_fma_f32 v32, -v72, v8, v32
	v_fma_f32 v32, -v73, v9, v32
	v_fma_f32 v32, -v74, v10, v32
	v_fma_f32 v32, -v75, v11, v32
	ds_read_b128 v[72:75], v64 offset:9248
	s_waitcnt lgkmcnt(11)
	v_fma_f32 v31, -v76, v12, v31
	v_fma_f32 v31, -v77, v13, v31
	v_fma_f32 v31, -v78, v14, v31
	v_fma_f32 v31, -v79, v15, v31
	ds_read_b128 v[76:79], v64 offset:8992
	s_waitcnt lgkmcnt(11)
	v_fma_f32 v32, -v80, v12, v32
	v_fma_f32 v32, -v81, v13, v32
	v_fma_f32 v32, -v82, v14, v32
	v_fma_f32 v32, -v83, v15, v32
	ds_read_b128 v[80:83], v64 offset:9264
	s_waitcnt lgkmcnt(11)
	v_fma_f32 v31, -v84, v16, v31
	v_fma_f32 v31, -v85, v17, v31
	v_fma_f32 v31, -v86, v18, v31
	v_fma_f32 v31, -v87, v19, v31
	ds_read_b128 v[84:87], v64 offset:9008
	s_waitcnt lgkmcnt(11)
	v_fma_f32 v32, -v88, v16, v32
	v_fma_f32 v32, -v89, v17, v32
	v_fma_f32 v32, -v90, v18, v32
	v_fma_f32 v32, -v91, v19, v32
	ds_read_b128 v[88:91], v64 offset:9280
	s_waitcnt lgkmcnt(11)
	v_fma_f32 v31, -v92, v20, v31
	v_fma_f32 v31, -v93, v21, v31
	v_fma_f32 v31, -v94, v22, v31
	v_fma_f32 v31, -v95, v23, v31
	ds_read_b128 v[92:95], v64 offset:9024
	s_waitcnt lgkmcnt(11)
	v_fma_f32 v32, -v96, v20, v32
	v_fma_f32 v32, -v97, v21, v32
	v_fma_f32 v32, -v98, v22, v32
	v_fma_f32 v32, -v99, v23, v32
	ds_read_b128 v[96:99], v64 offset:9296
	s_waitcnt lgkmcnt(11)
	v_fma_f32 v31, -v100, v24, v31
	v_fma_f32 v31, -v101, v25, v31
	v_fma_f32 v31, -v102, v26, v31
	v_fma_f32 v31, -v103, v27, v31
	ds_read_b128 v[100:103], v64 offset:9040
	s_waitcnt lgkmcnt(11)
	v_fma_f32 v32, -v104, v24, v32
	v_fma_f32 v32, -v105, v25, v32
	v_fma_f32 v32, -v106, v26, v32
	v_fma_f32 v32, -v107, v27, v32
	ds_read_b128 v[104:107], v64 offset:9312
	s_waitcnt lgkmcnt(11)
	v_fma_f32 v31, -v108, v28, v31
	v_fma_f32 v31, -v109, v29, v31
	v_fma_f32 v31, -v110, v30, v31
	ds_read_b128 v[108:111], v64 offset:9056
	s_waitcnt lgkmcnt(11)
	v_fma_f32 v32, -v112, v28, v32
	v_fma_f32 v32, -v113, v29, v32
	v_fma_f32 v32, -v114, v30, v32
	v_fma_f32 v32, -v115, v31, v32
	ds_read_b128 v[112:115], v64 offset:9328
	s_waitcnt lgkmcnt(11)
	v_fma_f32 v33, -v68, v153, v186
	v_fma_f32 v33, -v69, v1, v33
	v_fma_f32 v33, -v70, v2, v33
	v_fma_f32 v33, -v71, v3, v33
	ds_read_b128 v[68:71], v64 offset:9072
	s_waitcnt lgkmcnt(11)
	v_fma_f32 v34, -v72, v153, v187
	v_fma_f32 v34, -v73, v1, v34
	v_fma_f32 v34, -v74, v2, v34
	v_fma_f32 v34, -v75, v3, v34
	ds_read_b128 v[72:75], v64 offset:9344
	s_waitcnt lgkmcnt(11)
	v_fma_f32 v33, -v76, v4, v33
	v_fma_f32 v33, -v77, v5, v33
	v_fma_f32 v33, -v78, v6, v33
	v_fma_f32 v33, -v79, v7, v33
	ds_read_b128 v[76:79], v64 offset:9088
	s_waitcnt lgkmcnt(11)
	v_fma_f32 v34, -v80, v4, v34
	v_fma_f32 v34, -v81, v5, v34
	v_fma_f32 v34, -v82, v6, v34
	v_fma_f32 v34, -v83, v7, v34
	ds_read_b128 v[80:83], v64 offset:9360
	s_waitcnt lgkmcnt(11)
	v_fma_f32 v33, -v84, v8, v33
	v_fma_f32 v33, -v85, v9, v33
	v_fma_f32 v33, -v86, v10, v33
	v_fma_f32 v33, -v87, v11, v33
	ds_read_b128 v[84:87], v64 offset:9104
	s_waitcnt lgkmcnt(11)
	v_fma_f32 v34, -v88, v8, v34
	v_fma_f32 v34, -v89, v9, v34
	v_fma_f32 v34, -v90, v10, v34
	v_fma_f32 v34, -v91, v11, v34
	ds_read_b128 v[88:91], v64 offset:9376
	s_waitcnt lgkmcnt(11)
	v_fma_f32 v33, -v92, v12, v33
	v_fma_f32 v33, -v93, v13, v33
	v_fma_f32 v33, -v94, v14, v33
	v_fma_f32 v33, -v95, v15, v33
	ds_read_b128 v[92:95], v64 offset:9520
	s_waitcnt lgkmcnt(11)
	v_fma_f32 v34, -v96, v12, v34
	v_fma_f32 v34, -v97, v13, v34
	v_fma_f32 v34, -v98, v14, v34
	v_fma_f32 v34, -v99, v15, v34
	ds_read_b128 v[96:99], v64 offset:9792
	s_waitcnt lgkmcnt(11)
	v_fma_f32 v33, -v100, v16, v33
	v_fma_f32 v33, -v101, v17, v33
	v_fma_f32 v33, -v102, v18, v33
	v_fma_f32 v33, -v103, v19, v33
	ds_read_b128 v[100:103], v64 offset:9536
	s_waitcnt lgkmcnt(11)
	v_fma_f32 v34, -v104, v16, v34
	v_fma_f32 v34, -v105, v17, v34
	v_fma_f32 v34, -v106, v18, v34
	v_fma_f32 v34, -v107, v19, v34
	ds_read_b128 v[104:107], v64 offset:9808
	s_waitcnt lgkmcnt(11)
	v_fma_f32 v33, -v108, v20, v33
	v_fma_f32 v33, -v109, v21, v33
	v_fma_f32 v33, -v110, v22, v33
	v_fma_f32 v33, -v111, v23, v33
	ds_read_b128 v[108:111], v64 offset:9552
	s_waitcnt lgkmcnt(11)
	v_fma_f32 v34, -v112, v20, v34
	v_fma_f32 v34, -v113, v21, v34
	v_fma_f32 v34, -v114, v22, v34
	v_fma_f32 v34, -v115, v23, v34
	ds_read_b128 v[112:115], v64 offset:9824
	s_waitcnt lgkmcnt(11)
	v_fma_f32 v33, -v68, v24, v33
	v_fma_f32 v33, -v69, v25, v33
	v_fma_f32 v33, -v70, v26, v33
	v_fma_f32 v33, -v71, v27, v33
	ds_read_b128 v[68:71], v64 offset:9568
	s_waitcnt lgkmcnt(11)
	v_fma_f32 v34, -v72, v24, v34
	v_fma_f32 v34, -v73, v25, v34
	v_fma_f32 v34, -v74, v26, v34
	v_fma_f32 v34, -v75, v27, v34
	ds_read_b128 v[72:75], v64 offset:9840
	s_waitcnt lgkmcnt(11)
	v_fma_f32 v33, -v76, v28, v33
	v_fma_f32 v33, -v77, v29, v33
	v_fma_f32 v33, -v78, v30, v33
	v_fma_f32 v33, -v79, v31, v33
	ds_read_b128 v[76:79], v64 offset:9584
	s_waitcnt lgkmcnt(11)
	v_fma_f32 v34, -v80, v28, v34
	v_fma_f32 v34, -v81, v29, v34
	v_fma_f32 v34, -v82, v30, v34
	v_fma_f32 v34, -v83, v31, v34
	ds_read_b128 v[80:83], v64 offset:9856
	s_waitcnt lgkmcnt(11)
	v_fma_f32 v33, -v84, v32, v33
	ds_read_b128 v[84:87], v64 offset:9600
	s_waitcnt lgkmcnt(11)
	v_fma_f32 v34, -v88, v32, v34
	v_fma_f32 v34, -v89, v33, v34
	ds_read_b128 v[88:91], v64 offset:9872
	s_waitcnt lgkmcnt(11)
	v_fma_f32 v35, -v92, v153, v188
	v_fma_f32 v35, -v93, v1, v35
	v_fma_f32 v35, -v94, v2, v35
	v_fma_f32 v35, -v95, v3, v35
	ds_read_b128 v[92:95], v64 offset:9616
	s_waitcnt lgkmcnt(11)
	v_fma_f32 v36, -v96, v153, v189
	v_fma_f32 v36, -v97, v1, v36
	v_fma_f32 v36, -v98, v2, v36
	v_fma_f32 v36, -v99, v3, v36
	ds_read_b128 v[96:99], v64 offset:9888
	s_waitcnt lgkmcnt(11)
	v_fma_f32 v35, -v100, v4, v35
	v_fma_f32 v35, -v101, v5, v35
	v_fma_f32 v35, -v102, v6, v35
	v_fma_f32 v35, -v103, v7, v35
	ds_read_b128 v[100:103], v64 offset:9632
	s_waitcnt lgkmcnt(11)
	v_fma_f32 v36, -v104, v4, v36
	v_fma_f32 v36, -v105, v5, v36
	v_fma_f32 v36, -v106, v6, v36
	v_fma_f32 v36, -v107, v7, v36
	ds_read_b128 v[104:107], v64 offset:9904
	s_waitcnt lgkmcnt(11)
	v_fma_f32 v35, -v108, v8, v35
	v_fma_f32 v35, -v109, v9, v35
	v_fma_f32 v35, -v110, v10, v35
	v_fma_f32 v35, -v111, v11, v35
	ds_read_b128 v[108:111], v64 offset:9648
	s_waitcnt lgkmcnt(11)
	v_fma_f32 v36, -v112, v8, v36
	v_fma_f32 v36, -v113, v9, v36
	v_fma_f32 v36, -v114, v10, v36
	v_fma_f32 v36, -v115, v11, v36
	ds_read_b128 v[112:115], v64 offset:9920
	s_waitcnt lgkmcnt(11)
	v_fma_f32 v35, -v68, v12, v35
	v_fma_f32 v35, -v69, v13, v35
	v_fma_f32 v35, -v70, v14, v35
	v_fma_f32 v35, -v71, v15, v35
	ds_read_b128 v[68:71], v64 offset:10064
	s_waitcnt lgkmcnt(11)
	v_fma_f32 v36, -v72, v12, v36
	v_fma_f32 v36, -v73, v13, v36
	v_fma_f32 v36, -v74, v14, v36
	v_fma_f32 v36, -v75, v15, v36
	ds_read_b128 v[72:75], v64 offset:10336
	s_waitcnt lgkmcnt(11)
	v_fma_f32 v35, -v76, v16, v35
	v_fma_f32 v35, -v77, v17, v35
	v_fma_f32 v35, -v78, v18, v35
	v_fma_f32 v35, -v79, v19, v35
	ds_read_b128 v[76:79], v64 offset:10080
	s_waitcnt lgkmcnt(11)
	v_fma_f32 v36, -v80, v16, v36
	v_fma_f32 v36, -v81, v17, v36
	v_fma_f32 v36, -v82, v18, v36
	v_fma_f32 v36, -v83, v19, v36
	ds_read_b128 v[80:83], v64 offset:10352
	s_waitcnt lgkmcnt(11)
	v_fma_f32 v35, -v84, v20, v35
	v_fma_f32 v35, -v85, v21, v35
	v_fma_f32 v35, -v86, v22, v35
	v_fma_f32 v35, -v87, v23, v35
	ds_read_b128 v[84:87], v64 offset:10096
	s_waitcnt lgkmcnt(11)
	v_fma_f32 v36, -v88, v20, v36
	v_fma_f32 v36, -v89, v21, v36
	v_fma_f32 v36, -v90, v22, v36
	v_fma_f32 v36, -v91, v23, v36
	ds_read_b128 v[88:91], v64 offset:10368
	s_waitcnt lgkmcnt(11)
	v_fma_f32 v35, -v92, v24, v35
	v_fma_f32 v35, -v93, v25, v35
	v_fma_f32 v35, -v94, v26, v35
	v_fma_f32 v35, -v95, v27, v35
	ds_read_b128 v[92:95], v64 offset:10112
	s_waitcnt lgkmcnt(11)
	v_fma_f32 v36, -v96, v24, v36
	v_fma_f32 v36, -v97, v25, v36
	v_fma_f32 v36, -v98, v26, v36
	v_fma_f32 v36, -v99, v27, v36
	ds_read_b128 v[96:99], v64 offset:10384
	s_waitcnt lgkmcnt(11)
	v_fma_f32 v35, -v100, v28, v35
	v_fma_f32 v35, -v101, v29, v35
	v_fma_f32 v35, -v102, v30, v35
	v_fma_f32 v35, -v103, v31, v35
	ds_read_b128 v[100:103], v64 offset:10128
	s_waitcnt lgkmcnt(11)
	v_fma_f32 v36, -v104, v28, v36
	v_fma_f32 v36, -v105, v29, v36
	v_fma_f32 v36, -v106, v30, v36
	v_fma_f32 v36, -v107, v31, v36
	ds_read_b128 v[104:107], v64 offset:10400
	s_waitcnt lgkmcnt(11)
	v_fma_f32 v35, -v108, v32, v35
	v_fma_f32 v35, -v109, v33, v35
	v_fma_f32 v35, -v110, v34, v35
	ds_read_b128 v[108:111], v64 offset:10144
	s_waitcnt lgkmcnt(11)
	v_fma_f32 v36, -v112, v32, v36
	v_fma_f32 v36, -v113, v33, v36
	v_fma_f32 v36, -v114, v34, v36
	v_fma_f32 v36, -v115, v35, v36
	ds_read_b128 v[112:115], v64 offset:10416
	s_waitcnt lgkmcnt(11)
	v_fma_f32 v37, -v68, v153, v190
	v_fma_f32 v37, -v69, v1, v37
	v_fma_f32 v37, -v70, v2, v37
	v_fma_f32 v37, -v71, v3, v37
	ds_read_b128 v[68:71], v64 offset:10160
	s_waitcnt lgkmcnt(11)
	v_fma_f32 v38, -v72, v153, v191
	v_fma_f32 v38, -v73, v1, v38
	v_fma_f32 v38, -v74, v2, v38
	v_fma_f32 v38, -v75, v3, v38
	ds_read_b128 v[72:75], v64 offset:10432
	s_waitcnt lgkmcnt(11)
	v_fma_f32 v37, -v76, v4, v37
	v_fma_f32 v37, -v77, v5, v37
	v_fma_f32 v37, -v78, v6, v37
	v_fma_f32 v37, -v79, v7, v37
	ds_read_b128 v[76:79], v64 offset:10176
	s_waitcnt lgkmcnt(11)
	v_fma_f32 v38, -v80, v4, v38
	v_fma_f32 v38, -v81, v5, v38
	v_fma_f32 v38, -v82, v6, v38
	v_fma_f32 v38, -v83, v7, v38
	ds_read_b128 v[80:83], v64 offset:10448
	s_waitcnt lgkmcnt(11)
	v_fma_f32 v37, -v84, v8, v37
	v_fma_f32 v37, -v85, v9, v37
	v_fma_f32 v37, -v86, v10, v37
	v_fma_f32 v37, -v87, v11, v37
	ds_read_b128 v[84:87], v64 offset:10192
	s_waitcnt lgkmcnt(11)
	v_fma_f32 v38, -v88, v8, v38
	v_fma_f32 v38, -v89, v9, v38
	v_fma_f32 v38, -v90, v10, v38
	v_fma_f32 v38, -v91, v11, v38
	ds_read_b128 v[88:91], v64 offset:10464
	s_waitcnt lgkmcnt(11)
	v_fma_f32 v37, -v92, v12, v37
	v_fma_f32 v37, -v93, v13, v37
	v_fma_f32 v37, -v94, v14, v37
	v_fma_f32 v37, -v95, v15, v37
	ds_read_b128 v[92:95], v64 offset:10208
	s_waitcnt lgkmcnt(11)
	v_fma_f32 v38, -v96, v12, v38
	v_fma_f32 v38, -v97, v13, v38
	v_fma_f32 v38, -v98, v14, v38
	v_fma_f32 v38, -v99, v15, v38
	ds_read_b128 v[96:99], v64 offset:10480
	s_waitcnt lgkmcnt(11)
	v_fma_f32 v37, -v100, v16, v37
	v_fma_f32 v37, -v101, v17, v37
	v_fma_f32 v37, -v102, v18, v37
	v_fma_f32 v37, -v103, v19, v37
	ds_read_b128 v[100:103], v64 offset:10608
	s_waitcnt lgkmcnt(11)
	v_fma_f32 v38, -v104, v16, v38
	v_fma_f32 v38, -v105, v17, v38
	v_fma_f32 v38, -v106, v18, v38
	v_fma_f32 v38, -v107, v19, v38
	ds_read_b128 v[104:107], v64 offset:10880
	s_waitcnt lgkmcnt(11)
	v_fma_f32 v37, -v108, v20, v37
	v_fma_f32 v37, -v109, v21, v37
	v_fma_f32 v37, -v110, v22, v37
	v_fma_f32 v37, -v111, v23, v37
	ds_read_b128 v[108:111], v64 offset:10624
	s_waitcnt lgkmcnt(11)
	v_fma_f32 v38, -v112, v20, v38
	v_fma_f32 v38, -v113, v21, v38
	v_fma_f32 v38, -v114, v22, v38
	v_fma_f32 v38, -v115, v23, v38
	ds_read_b128 v[112:115], v64 offset:10896
	s_waitcnt lgkmcnt(11)
	v_fma_f32 v37, -v68, v24, v37
	v_fma_f32 v37, -v69, v25, v37
	v_fma_f32 v37, -v70, v26, v37
	v_fma_f32 v37, -v71, v27, v37
	ds_read_b128 v[68:71], v64 offset:10640
	s_waitcnt lgkmcnt(11)
	v_fma_f32 v38, -v72, v24, v38
	v_fma_f32 v38, -v73, v25, v38
	v_fma_f32 v38, -v74, v26, v38
	v_fma_f32 v38, -v75, v27, v38
	ds_read_b128 v[72:75], v64 offset:10912
	s_waitcnt lgkmcnt(11)
	v_fma_f32 v37, -v76, v28, v37
	v_fma_f32 v37, -v77, v29, v37
	v_fma_f32 v37, -v78, v30, v37
	v_fma_f32 v37, -v79, v31, v37
	ds_read_b128 v[76:79], v64 offset:10656
	s_waitcnt lgkmcnt(11)
	v_fma_f32 v38, -v80, v28, v38
	v_fma_f32 v38, -v81, v29, v38
	v_fma_f32 v38, -v82, v30, v38
	v_fma_f32 v38, -v83, v31, v38
	ds_read_b128 v[80:83], v64 offset:10928
	s_waitcnt lgkmcnt(11)
	v_fma_f32 v37, -v84, v32, v37
	v_fma_f32 v37, -v85, v33, v37
	v_fma_f32 v37, -v86, v34, v37
	v_fma_f32 v37, -v87, v35, v37
	ds_read_b128 v[84:87], v64 offset:10672
	s_waitcnt lgkmcnt(11)
	v_fma_f32 v38, -v88, v32, v38
	v_fma_f32 v38, -v89, v33, v38
	v_fma_f32 v38, -v90, v34, v38
	v_fma_f32 v38, -v91, v35, v38
	ds_read_b128 v[88:91], v64 offset:10944
	s_waitcnt lgkmcnt(11)
	v_fma_f32 v37, -v92, v36, v37
	ds_read_b128 v[92:95], v64 offset:10688
	s_waitcnt lgkmcnt(11)
	v_fma_f32 v38, -v96, v36, v38
	v_fma_f32 v38, -v97, v37, v38
	ds_read_b128 v[96:99], v64 offset:10960
	s_waitcnt lgkmcnt(11)
	v_fma_f32 v39, -v100, v153, v192
	v_fma_f32 v39, -v101, v1, v39
	v_fma_f32 v39, -v102, v2, v39
	v_fma_f32 v39, -v103, v3, v39
	ds_read_b128 v[100:103], v64 offset:10704
	s_waitcnt lgkmcnt(11)
	v_fma_f32 v40, -v104, v153, v193
	v_fma_f32 v40, -v105, v1, v40
	v_fma_f32 v40, -v106, v2, v40
	v_fma_f32 v40, -v107, v3, v40
	ds_read_b128 v[104:107], v64 offset:10976
	s_waitcnt lgkmcnt(11)
	v_fma_f32 v39, -v108, v4, v39
	v_fma_f32 v39, -v109, v5, v39
	v_fma_f32 v39, -v110, v6, v39
	v_fma_f32 v39, -v111, v7, v39
	ds_read_b128 v[108:111], v64 offset:10720
	s_waitcnt lgkmcnt(11)
	v_fma_f32 v40, -v112, v4, v40
	v_fma_f32 v40, -v113, v5, v40
	v_fma_f32 v40, -v114, v6, v40
	v_fma_f32 v40, -v115, v7, v40
	ds_read_b128 v[112:115], v64 offset:10992
	s_waitcnt lgkmcnt(11)
	v_fma_f32 v39, -v68, v8, v39
	v_fma_f32 v39, -v69, v9, v39
	v_fma_f32 v39, -v70, v10, v39
	v_fma_f32 v39, -v71, v11, v39
	ds_read_b128 v[68:71], v64 offset:10736
	s_waitcnt lgkmcnt(11)
	v_fma_f32 v40, -v72, v8, v40
	v_fma_f32 v40, -v73, v9, v40
	v_fma_f32 v40, -v74, v10, v40
	v_fma_f32 v40, -v75, v11, v40
	ds_read_b128 v[72:75], v64 offset:11008
	s_waitcnt lgkmcnt(11)
	v_fma_f32 v39, -v76, v12, v39
	v_fma_f32 v39, -v77, v13, v39
	v_fma_f32 v39, -v78, v14, v39
	v_fma_f32 v39, -v79, v15, v39
	ds_read_b128 v[76:79], v64 offset:10752
	s_waitcnt lgkmcnt(11)
	v_fma_f32 v40, -v80, v12, v40
	v_fma_f32 v40, -v81, v13, v40
	v_fma_f32 v40, -v82, v14, v40
	v_fma_f32 v40, -v83, v15, v40
	ds_read_b128 v[80:83], v64 offset:11024
	s_waitcnt lgkmcnt(11)
	v_fma_f32 v39, -v84, v16, v39
	v_fma_f32 v39, -v85, v17, v39
	v_fma_f32 v39, -v86, v18, v39
	v_fma_f32 v39, -v87, v19, v39
	ds_read_b128 v[84:87], v64 offset:11152
	s_waitcnt lgkmcnt(11)
	v_fma_f32 v40, -v88, v16, v40
	v_fma_f32 v40, -v89, v17, v40
	v_fma_f32 v40, -v90, v18, v40
	v_fma_f32 v40, -v91, v19, v40
	ds_read_b128 v[88:91], v64 offset:11424
	s_waitcnt lgkmcnt(11)
	v_fma_f32 v39, -v92, v20, v39
	v_fma_f32 v39, -v93, v21, v39
	v_fma_f32 v39, -v94, v22, v39
	v_fma_f32 v39, -v95, v23, v39
	ds_read_b128 v[92:95], v64 offset:11168
	s_waitcnt lgkmcnt(11)
	v_fma_f32 v40, -v96, v20, v40
	v_fma_f32 v40, -v97, v21, v40
	v_fma_f32 v40, -v98, v22, v40
	v_fma_f32 v40, -v99, v23, v40
	ds_read_b128 v[96:99], v64 offset:11440
	s_waitcnt lgkmcnt(11)
	v_fma_f32 v39, -v100, v24, v39
	v_fma_f32 v39, -v101, v25, v39
	v_fma_f32 v39, -v102, v26, v39
	v_fma_f32 v39, -v103, v27, v39
	ds_read_b128 v[100:103], v64 offset:11184
	s_waitcnt lgkmcnt(11)
	v_fma_f32 v40, -v104, v24, v40
	v_fma_f32 v40, -v105, v25, v40
	v_fma_f32 v40, -v106, v26, v40
	v_fma_f32 v40, -v107, v27, v40
	ds_read_b128 v[104:107], v64 offset:11456
	s_waitcnt lgkmcnt(11)
	v_fma_f32 v39, -v108, v28, v39
	v_fma_f32 v39, -v109, v29, v39
	v_fma_f32 v39, -v110, v30, v39
	v_fma_f32 v39, -v111, v31, v39
	ds_read_b128 v[108:111], v64 offset:11200
	s_waitcnt lgkmcnt(11)
	v_fma_f32 v40, -v112, v28, v40
	v_fma_f32 v40, -v113, v29, v40
	v_fma_f32 v40, -v114, v30, v40
	v_fma_f32 v40, -v115, v31, v40
	ds_read_b128 v[112:115], v64 offset:11472
	s_waitcnt lgkmcnt(11)
	v_fma_f32 v39, -v68, v32, v39
	v_fma_f32 v39, -v69, v33, v39
	v_fma_f32 v39, -v70, v34, v39
	v_fma_f32 v39, -v71, v35, v39
	ds_read_b128 v[68:71], v64 offset:11216
	s_waitcnt lgkmcnt(11)
	v_fma_f32 v40, -v72, v32, v40
	v_fma_f32 v40, -v73, v33, v40
	v_fma_f32 v40, -v74, v34, v40
	v_fma_f32 v40, -v75, v35, v40
	ds_read_b128 v[72:75], v64 offset:11488
	s_waitcnt lgkmcnt(11)
	v_fma_f32 v39, -v76, v36, v39
	v_fma_f32 v39, -v77, v37, v39
	v_fma_f32 v39, -v78, v38, v39
	ds_read_b128 v[76:79], v64 offset:11232
	s_waitcnt lgkmcnt(11)
	v_fma_f32 v40, -v80, v36, v40
	v_fma_f32 v40, -v81, v37, v40
	v_fma_f32 v40, -v82, v38, v40
	v_fma_f32 v40, -v83, v39, v40
	ds_read_b128 v[80:83], v64 offset:11504
	s_waitcnt lgkmcnt(11)
	v_fma_f32 v41, -v84, v153, v194
	v_fma_f32 v41, -v85, v1, v41
	v_fma_f32 v41, -v86, v2, v41
	v_fma_f32 v41, -v87, v3, v41
	ds_read_b128 v[84:87], v64 offset:11248
	s_waitcnt lgkmcnt(11)
	v_fma_f32 v42, -v88, v153, v195
	v_fma_f32 v42, -v89, v1, v42
	v_fma_f32 v42, -v90, v2, v42
	v_fma_f32 v42, -v91, v3, v42
	ds_read_b128 v[88:91], v64 offset:11520
	s_waitcnt lgkmcnt(11)
	v_fma_f32 v41, -v92, v4, v41
	v_fma_f32 v41, -v93, v5, v41
	v_fma_f32 v41, -v94, v6, v41
	v_fma_f32 v41, -v95, v7, v41
	ds_read_b128 v[92:95], v64 offset:11264
	s_waitcnt lgkmcnt(11)
	v_fma_f32 v42, -v96, v4, v42
	v_fma_f32 v42, -v97, v5, v42
	v_fma_f32 v42, -v98, v6, v42
	v_fma_f32 v42, -v99, v7, v42
	ds_read_b128 v[96:99], v64 offset:11536
	s_waitcnt lgkmcnt(11)
	v_fma_f32 v41, -v100, v8, v41
	v_fma_f32 v41, -v101, v9, v41
	v_fma_f32 v41, -v102, v10, v41
	v_fma_f32 v41, -v103, v11, v41
	ds_read_b128 v[100:103], v64 offset:11280
	s_waitcnt lgkmcnt(11)
	v_fma_f32 v42, -v104, v8, v42
	v_fma_f32 v42, -v105, v9, v42
	v_fma_f32 v42, -v106, v10, v42
	v_fma_f32 v42, -v107, v11, v42
	ds_read_b128 v[104:107], v64 offset:11552
	s_waitcnt lgkmcnt(11)
	v_fma_f32 v41, -v108, v12, v41
	v_fma_f32 v41, -v109, v13, v41
	v_fma_f32 v41, -v110, v14, v41
	v_fma_f32 v41, -v111, v15, v41
	ds_read_b128 v[108:111], v64 offset:11296
	s_waitcnt lgkmcnt(11)
	v_fma_f32 v42, -v112, v12, v42
	v_fma_f32 v42, -v113, v13, v42
	v_fma_f32 v42, -v114, v14, v42
	v_fma_f32 v42, -v115, v15, v42
	ds_read_b128 v[112:115], v64 offset:11568
	s_waitcnt lgkmcnt(11)
	v_fma_f32 v41, -v68, v16, v41
	v_fma_f32 v41, -v69, v17, v41
	v_fma_f32 v41, -v70, v18, v41
	v_fma_f32 v41, -v71, v19, v41
	ds_read_b128 v[68:71], v64 offset:11312
	s_waitcnt lgkmcnt(11)
	v_fma_f32 v42, -v72, v16, v42
	v_fma_f32 v42, -v73, v17, v42
	v_fma_f32 v42, -v74, v18, v42
	v_fma_f32 v42, -v75, v19, v42
	ds_read_b128 v[72:75], v64 offset:11584
	s_waitcnt lgkmcnt(11)
	v_fma_f32 v41, -v76, v20, v41
	v_fma_f32 v41, -v77, v21, v41
	v_fma_f32 v41, -v78, v22, v41
	v_fma_f32 v41, -v79, v23, v41
	ds_read_b128 v[76:79], v64 offset:11696
	s_waitcnt lgkmcnt(11)
	v_fma_f32 v42, -v80, v20, v42
	v_fma_f32 v42, -v81, v21, v42
	v_fma_f32 v42, -v82, v22, v42
	v_fma_f32 v42, -v83, v23, v42
	ds_read_b128 v[80:83], v64 offset:11968
	s_waitcnt lgkmcnt(11)
	v_fma_f32 v41, -v84, v24, v41
	v_fma_f32 v41, -v85, v25, v41
	v_fma_f32 v41, -v86, v26, v41
	v_fma_f32 v41, -v87, v27, v41
	ds_read_b128 v[84:87], v64 offset:11712
	s_waitcnt lgkmcnt(11)
	v_fma_f32 v42, -v88, v24, v42
	v_fma_f32 v42, -v89, v25, v42
	v_fma_f32 v42, -v90, v26, v42
	v_fma_f32 v42, -v91, v27, v42
	ds_read_b128 v[88:91], v64 offset:11984
	s_waitcnt lgkmcnt(11)
	v_fma_f32 v41, -v92, v28, v41
	v_fma_f32 v41, -v93, v29, v41
	v_fma_f32 v41, -v94, v30, v41
	v_fma_f32 v41, -v95, v31, v41
	ds_read_b128 v[92:95], v64 offset:11728
	s_waitcnt lgkmcnt(11)
	v_fma_f32 v42, -v96, v28, v42
	v_fma_f32 v42, -v97, v29, v42
	v_fma_f32 v42, -v98, v30, v42
	v_fma_f32 v42, -v99, v31, v42
	ds_read_b128 v[96:99], v64 offset:12000
	s_waitcnt lgkmcnt(11)
	v_fma_f32 v41, -v100, v32, v41
	v_fma_f32 v41, -v101, v33, v41
	v_fma_f32 v41, -v102, v34, v41
	v_fma_f32 v41, -v103, v35, v41
	ds_read_b128 v[100:103], v64 offset:11744
	s_waitcnt lgkmcnt(11)
	v_fma_f32 v42, -v104, v32, v42
	v_fma_f32 v42, -v105, v33, v42
	v_fma_f32 v42, -v106, v34, v42
	v_fma_f32 v42, -v107, v35, v42
	ds_read_b128 v[104:107], v64 offset:12016
	s_waitcnt lgkmcnt(11)
	v_fma_f32 v41, -v108, v36, v41
	v_fma_f32 v41, -v109, v37, v41
	v_fma_f32 v41, -v110, v38, v41
	v_fma_f32 v41, -v111, v39, v41
	ds_read_b128 v[108:111], v64 offset:11760
	s_waitcnt lgkmcnt(11)
	v_fma_f32 v42, -v112, v36, v42
	v_fma_f32 v42, -v113, v37, v42
	v_fma_f32 v42, -v114, v38, v42
	v_fma_f32 v42, -v115, v39, v42
	ds_read_b128 v[112:115], v64 offset:12032
	s_waitcnt lgkmcnt(11)
	v_fma_f32 v41, -v68, v40, v41
	ds_read_b128 v[68:71], v64 offset:11776
	s_waitcnt lgkmcnt(11)
	v_fma_f32 v42, -v72, v40, v42
	v_fma_f32 v42, -v73, v41, v42
	ds_read_b128 v[72:75], v64 offset:12048
	s_waitcnt lgkmcnt(11)
	v_fma_f32 v43, -v76, v153, v196
	v_fma_f32 v43, -v77, v1, v43
	v_fma_f32 v43, -v78, v2, v43
	v_fma_f32 v43, -v79, v3, v43
	ds_read_b128 v[76:79], v64 offset:11792
	s_waitcnt lgkmcnt(11)
	v_fma_f32 v44, -v80, v153, v197
	v_fma_f32 v44, -v81, v1, v44
	v_fma_f32 v44, -v82, v2, v44
	v_fma_f32 v44, -v83, v3, v44
	ds_read_b128 v[80:83], v64 offset:12064
	s_waitcnt lgkmcnt(11)
	v_fma_f32 v43, -v84, v4, v43
	v_fma_f32 v43, -v85, v5, v43
	v_fma_f32 v43, -v86, v6, v43
	v_fma_f32 v43, -v87, v7, v43
	ds_read_b128 v[84:87], v64 offset:11808
	s_waitcnt lgkmcnt(11)
	v_fma_f32 v44, -v88, v4, v44
	v_fma_f32 v44, -v89, v5, v44
	v_fma_f32 v44, -v90, v6, v44
	v_fma_f32 v44, -v91, v7, v44
	ds_read_b128 v[88:91], v64 offset:12080
	s_waitcnt lgkmcnt(11)
	v_fma_f32 v43, -v92, v8, v43
	v_fma_f32 v43, -v93, v9, v43
	v_fma_f32 v43, -v94, v10, v43
	v_fma_f32 v43, -v95, v11, v43
	ds_read_b128 v[92:95], v64 offset:11824
	s_waitcnt lgkmcnt(11)
	v_fma_f32 v44, -v96, v8, v44
	v_fma_f32 v44, -v97, v9, v44
	v_fma_f32 v44, -v98, v10, v44
	v_fma_f32 v44, -v99, v11, v44
	ds_read_b128 v[96:99], v64 offset:12096
	s_waitcnt lgkmcnt(11)
	v_fma_f32 v43, -v100, v12, v43
	v_fma_f32 v43, -v101, v13, v43
	v_fma_f32 v43, -v102, v14, v43
	v_fma_f32 v43, -v103, v15, v43
	ds_read_b128 v[100:103], v64 offset:11840
	s_waitcnt lgkmcnt(11)
	v_fma_f32 v44, -v104, v12, v44
	v_fma_f32 v44, -v105, v13, v44
	v_fma_f32 v44, -v106, v14, v44
	v_fma_f32 v44, -v107, v15, v44
	ds_read_b128 v[104:107], v64 offset:12112
	s_waitcnt lgkmcnt(11)
	v_fma_f32 v43, -v108, v16, v43
	v_fma_f32 v43, -v109, v17, v43
	v_fma_f32 v43, -v110, v18, v43
	v_fma_f32 v43, -v111, v19, v43
	ds_read_b128 v[108:111], v64 offset:11856
	s_waitcnt lgkmcnt(11)
	v_fma_f32 v44, -v112, v16, v44
	v_fma_f32 v44, -v113, v17, v44
	v_fma_f32 v44, -v114, v18, v44
	v_fma_f32 v44, -v115, v19, v44
	ds_read_b128 v[112:115], v64 offset:12128
	s_waitcnt lgkmcnt(11)
	v_fma_f32 v43, -v68, v20, v43
	v_fma_f32 v43, -v69, v21, v43
	v_fma_f32 v43, -v70, v22, v43
	v_fma_f32 v43, -v71, v23, v43
	ds_read_b128 v[68:71], v64 offset:12240
	s_waitcnt lgkmcnt(11)
	v_fma_f32 v44, -v72, v20, v44
	v_fma_f32 v44, -v73, v21, v44
	v_fma_f32 v44, -v74, v22, v44
	v_fma_f32 v44, -v75, v23, v44
	ds_read_b128 v[72:75], v64 offset:12512
	s_waitcnt lgkmcnt(11)
	v_fma_f32 v43, -v76, v24, v43
	v_fma_f32 v43, -v77, v25, v43
	v_fma_f32 v43, -v78, v26, v43
	v_fma_f32 v43, -v79, v27, v43
	ds_read_b128 v[76:79], v64 offset:12256
	s_waitcnt lgkmcnt(11)
	v_fma_f32 v44, -v80, v24, v44
	v_fma_f32 v44, -v81, v25, v44
	v_fma_f32 v44, -v82, v26, v44
	v_fma_f32 v44, -v83, v27, v44
	ds_read_b128 v[80:83], v64 offset:12528
	s_waitcnt lgkmcnt(11)
	v_fma_f32 v43, -v84, v28, v43
	v_fma_f32 v43, -v85, v29, v43
	v_fma_f32 v43, -v86, v30, v43
	v_fma_f32 v43, -v87, v31, v43
	ds_read_b128 v[84:87], v64 offset:12272
	s_waitcnt lgkmcnt(11)
	v_fma_f32 v44, -v88, v28, v44
	v_fma_f32 v44, -v89, v29, v44
	v_fma_f32 v44, -v90, v30, v44
	v_fma_f32 v44, -v91, v31, v44
	ds_read_b128 v[88:91], v64 offset:12544
	s_waitcnt lgkmcnt(11)
	v_fma_f32 v43, -v92, v32, v43
	v_fma_f32 v43, -v93, v33, v43
	v_fma_f32 v43, -v94, v34, v43
	v_fma_f32 v43, -v95, v35, v43
	ds_read_b128 v[92:95], v64 offset:12288
	s_waitcnt lgkmcnt(11)
	v_fma_f32 v44, -v96, v32, v44
	v_fma_f32 v44, -v97, v33, v44
	v_fma_f32 v44, -v98, v34, v44
	v_fma_f32 v44, -v99, v35, v44
	ds_read_b128 v[96:99], v64 offset:12560
	s_waitcnt lgkmcnt(11)
	v_fma_f32 v43, -v100, v36, v43
	v_fma_f32 v43, -v101, v37, v43
	v_fma_f32 v43, -v102, v38, v43
	v_fma_f32 v43, -v103, v39, v43
	ds_read_b128 v[100:103], v64 offset:12304
	s_waitcnt lgkmcnt(11)
	v_fma_f32 v44, -v104, v36, v44
	v_fma_f32 v44, -v105, v37, v44
	v_fma_f32 v44, -v106, v38, v44
	v_fma_f32 v44, -v107, v39, v44
	ds_read_b128 v[104:107], v64 offset:12576
	s_waitcnt lgkmcnt(11)
	v_fma_f32 v43, -v108, v40, v43
	v_fma_f32 v43, -v109, v41, v43
	v_fma_f32 v43, -v110, v42, v43
	ds_read_b128 v[108:111], v64 offset:12320
	s_waitcnt lgkmcnt(11)
	v_fma_f32 v44, -v112, v40, v44
	v_fma_f32 v44, -v113, v41, v44
	v_fma_f32 v44, -v114, v42, v44
	v_fma_f32 v44, -v115, v43, v44
	ds_read_b128 v[112:115], v64 offset:12592
	s_waitcnt lgkmcnt(11)
	v_fma_f32 v45, -v68, v153, v198
	v_fma_f32 v45, -v69, v1, v45
	v_fma_f32 v45, -v70, v2, v45
	v_fma_f32 v45, -v71, v3, v45
	ds_read_b128 v[68:71], v64 offset:12336
	s_waitcnt lgkmcnt(11)
	v_fma_f32 v46, -v72, v153, v199
	v_fma_f32 v46, -v73, v1, v46
	v_fma_f32 v46, -v74, v2, v46
	v_fma_f32 v46, -v75, v3, v46
	ds_read_b128 v[72:75], v64 offset:12608
	s_waitcnt lgkmcnt(11)
	v_fma_f32 v45, -v76, v4, v45
	v_fma_f32 v45, -v77, v5, v45
	v_fma_f32 v45, -v78, v6, v45
	v_fma_f32 v45, -v79, v7, v45
	ds_read_b128 v[76:79], v64 offset:12352
	s_waitcnt lgkmcnt(11)
	v_fma_f32 v46, -v80, v4, v46
	v_fma_f32 v46, -v81, v5, v46
	v_fma_f32 v46, -v82, v6, v46
	v_fma_f32 v46, -v83, v7, v46
	ds_read_b128 v[80:83], v64 offset:12624
	s_waitcnt lgkmcnt(11)
	v_fma_f32 v45, -v84, v8, v45
	v_fma_f32 v45, -v85, v9, v45
	v_fma_f32 v45, -v86, v10, v45
	v_fma_f32 v45, -v87, v11, v45
	ds_read_b128 v[84:87], v64 offset:12368
	s_waitcnt lgkmcnt(11)
	v_fma_f32 v46, -v88, v8, v46
	v_fma_f32 v46, -v89, v9, v46
	v_fma_f32 v46, -v90, v10, v46
	v_fma_f32 v46, -v91, v11, v46
	ds_read_b128 v[88:91], v64 offset:12640
	s_waitcnt lgkmcnt(11)
	v_fma_f32 v45, -v92, v12, v45
	v_fma_f32 v45, -v93, v13, v45
	v_fma_f32 v45, -v94, v14, v45
	v_fma_f32 v45, -v95, v15, v45
	ds_read_b128 v[92:95], v64 offset:12384
	s_waitcnt lgkmcnt(11)
	v_fma_f32 v46, -v96, v12, v46
	v_fma_f32 v46, -v97, v13, v46
	v_fma_f32 v46, -v98, v14, v46
	v_fma_f32 v46, -v99, v15, v46
	ds_read_b128 v[96:99], v64 offset:12656
	s_waitcnt lgkmcnt(11)
	v_fma_f32 v45, -v100, v16, v45
	v_fma_f32 v45, -v101, v17, v45
	v_fma_f32 v45, -v102, v18, v45
	v_fma_f32 v45, -v103, v19, v45
	ds_read_b128 v[100:103], v64 offset:12400
	s_waitcnt lgkmcnt(11)
	v_fma_f32 v46, -v104, v16, v46
	v_fma_f32 v46, -v105, v17, v46
	v_fma_f32 v46, -v106, v18, v46
	v_fma_f32 v46, -v107, v19, v46
	ds_read_b128 v[104:107], v64 offset:12672
	s_waitcnt lgkmcnt(11)
	v_fma_f32 v45, -v108, v20, v45
	v_fma_f32 v45, -v109, v21, v45
	v_fma_f32 v45, -v110, v22, v45
	v_fma_f32 v45, -v111, v23, v45
	ds_read_b128 v[108:111], v64 offset:12416
	s_waitcnt lgkmcnt(11)
	v_fma_f32 v46, -v112, v20, v46
	v_fma_f32 v46, -v113, v21, v46
	v_fma_f32 v46, -v114, v22, v46
	v_fma_f32 v46, -v115, v23, v46
	ds_read_b128 v[112:115], v64 offset:12688
	s_waitcnt lgkmcnt(11)
	v_fma_f32 v45, -v68, v24, v45
	v_fma_f32 v45, -v69, v25, v45
	v_fma_f32 v45, -v70, v26, v45
	v_fma_f32 v45, -v71, v27, v45
	ds_read_b128 v[68:71], v64 offset:12784
	s_waitcnt lgkmcnt(11)
	v_fma_f32 v46, -v72, v24, v46
	v_fma_f32 v46, -v73, v25, v46
	v_fma_f32 v46, -v74, v26, v46
	v_fma_f32 v46, -v75, v27, v46
	ds_read_b128 v[72:75], v64 offset:13056
	s_waitcnt lgkmcnt(11)
	v_fma_f32 v45, -v76, v28, v45
	v_fma_f32 v45, -v77, v29, v45
	v_fma_f32 v45, -v78, v30, v45
	v_fma_f32 v45, -v79, v31, v45
	ds_read_b128 v[76:79], v64 offset:12800
	s_waitcnt lgkmcnt(11)
	v_fma_f32 v46, -v80, v28, v46
	v_fma_f32 v46, -v81, v29, v46
	v_fma_f32 v46, -v82, v30, v46
	v_fma_f32 v46, -v83, v31, v46
	ds_read_b128 v[80:83], v64 offset:13072
	s_waitcnt lgkmcnt(11)
	v_fma_f32 v45, -v84, v32, v45
	v_fma_f32 v45, -v85, v33, v45
	v_fma_f32 v45, -v86, v34, v45
	v_fma_f32 v45, -v87, v35, v45
	ds_read_b128 v[84:87], v64 offset:12816
	s_waitcnt lgkmcnt(11)
	v_fma_f32 v46, -v88, v32, v46
	v_fma_f32 v46, -v89, v33, v46
	v_fma_f32 v46, -v90, v34, v46
	v_fma_f32 v46, -v91, v35, v46
	ds_read_b128 v[88:91], v64 offset:13088
	s_waitcnt lgkmcnt(11)
	v_fma_f32 v45, -v92, v36, v45
	v_fma_f32 v45, -v93, v37, v45
	v_fma_f32 v45, -v94, v38, v45
	v_fma_f32 v45, -v95, v39, v45
	ds_read_b128 v[92:95], v64 offset:12832
	s_waitcnt lgkmcnt(11)
	v_fma_f32 v46, -v96, v36, v46
	v_fma_f32 v46, -v97, v37, v46
	v_fma_f32 v46, -v98, v38, v46
	v_fma_f32 v46, -v99, v39, v46
	ds_read_b128 v[96:99], v64 offset:13104
	s_waitcnt lgkmcnt(11)
	v_fma_f32 v45, -v100, v40, v45
	v_fma_f32 v45, -v101, v41, v45
	v_fma_f32 v45, -v102, v42, v45
	v_fma_f32 v45, -v103, v43, v45
	ds_read_b128 v[100:103], v64 offset:12848
	s_waitcnt lgkmcnt(11)
	v_fma_f32 v46, -v104, v40, v46
	v_fma_f32 v46, -v105, v41, v46
	v_fma_f32 v46, -v106, v42, v46
	v_fma_f32 v46, -v107, v43, v46
	ds_read_b128 v[104:107], v64 offset:13120
	s_waitcnt lgkmcnt(11)
	v_fma_f32 v45, -v108, v44, v45
	ds_read_b128 v[108:111], v64 offset:12864
	s_waitcnt lgkmcnt(11)
	v_fma_f32 v46, -v112, v44, v46
	v_fma_f32 v46, -v113, v45, v46
	ds_read_b128 v[112:115], v64 offset:13136
	s_waitcnt lgkmcnt(11)
	v_fma_f32 v47, -v68, v153, v202
	v_fma_f32 v47, -v69, v1, v47
	v_fma_f32 v47, -v70, v2, v47
	v_fma_f32 v47, -v71, v3, v47
	ds_read_b128 v[68:71], v64 offset:12880
	s_waitcnt lgkmcnt(11)
	v_fma_f32 v48, -v72, v153, v203
	v_fma_f32 v48, -v73, v1, v48
	v_fma_f32 v48, -v74, v2, v48
	v_fma_f32 v48, -v75, v3, v48
	ds_read_b128 v[72:75], v64 offset:13152
	s_waitcnt lgkmcnt(11)
	v_fma_f32 v47, -v76, v4, v47
	v_fma_f32 v47, -v77, v5, v47
	v_fma_f32 v47, -v78, v6, v47
	v_fma_f32 v47, -v79, v7, v47
	ds_read_b128 v[76:79], v64 offset:12896
	s_waitcnt lgkmcnt(11)
	v_fma_f32 v48, -v80, v4, v48
	v_fma_f32 v48, -v81, v5, v48
	v_fma_f32 v48, -v82, v6, v48
	v_fma_f32 v48, -v83, v7, v48
	ds_read_b128 v[80:83], v64 offset:13168
	s_waitcnt lgkmcnt(11)
	v_fma_f32 v47, -v84, v8, v47
	v_fma_f32 v47, -v85, v9, v47
	v_fma_f32 v47, -v86, v10, v47
	v_fma_f32 v47, -v87, v11, v47
	ds_read_b128 v[84:87], v64 offset:12912
	s_waitcnt lgkmcnt(11)
	v_fma_f32 v48, -v88, v8, v48
	v_fma_f32 v48, -v89, v9, v48
	v_fma_f32 v48, -v90, v10, v48
	v_fma_f32 v48, -v91, v11, v48
	ds_read_b128 v[88:91], v64 offset:13184
	s_waitcnt lgkmcnt(11)
	v_fma_f32 v47, -v92, v12, v47
	v_fma_f32 v47, -v93, v13, v47
	v_fma_f32 v47, -v94, v14, v47
	v_fma_f32 v47, -v95, v15, v47
	ds_read_b128 v[92:95], v64 offset:12928
	s_waitcnt lgkmcnt(11)
	v_fma_f32 v48, -v96, v12, v48
	v_fma_f32 v48, -v97, v13, v48
	v_fma_f32 v48, -v98, v14, v48
	v_fma_f32 v48, -v99, v15, v48
	ds_read_b128 v[96:99], v64 offset:13200
	s_waitcnt lgkmcnt(11)
	v_fma_f32 v47, -v100, v16, v47
	v_fma_f32 v47, -v101, v17, v47
	v_fma_f32 v47, -v102, v18, v47
	v_fma_f32 v47, -v103, v19, v47
	ds_read_b128 v[100:103], v64 offset:12944
	s_waitcnt lgkmcnt(11)
	v_fma_f32 v48, -v104, v16, v48
	v_fma_f32 v48, -v105, v17, v48
	v_fma_f32 v48, -v106, v18, v48
	v_fma_f32 v48, -v107, v19, v48
	ds_read_b128 v[104:107], v64 offset:13216
	s_waitcnt lgkmcnt(11)
	v_fma_f32 v47, -v108, v20, v47
	v_fma_f32 v47, -v109, v21, v47
	v_fma_f32 v47, -v110, v22, v47
	v_fma_f32 v47, -v111, v23, v47
	ds_read_b128 v[108:111], v64 offset:12960
	s_waitcnt lgkmcnt(11)
	v_fma_f32 v48, -v112, v20, v48
	v_fma_f32 v48, -v113, v21, v48
	v_fma_f32 v48, -v114, v22, v48
	v_fma_f32 v48, -v115, v23, v48
	ds_read_b128 v[112:115], v64 offset:13232
	s_waitcnt lgkmcnt(11)
	v_fma_f32 v47, -v68, v24, v47
	v_fma_f32 v47, -v69, v25, v47
	v_fma_f32 v47, -v70, v26, v47
	v_fma_f32 v47, -v71, v27, v47
	ds_read_b128 v[68:71], v64 offset:13328
	s_waitcnt lgkmcnt(11)
	v_fma_f32 v48, -v72, v24, v48
	v_fma_f32 v48, -v73, v25, v48
	v_fma_f32 v48, -v74, v26, v48
	v_fma_f32 v48, -v75, v27, v48
	ds_read_b128 v[72:75], v64 offset:13600
	s_waitcnt lgkmcnt(11)
	v_fma_f32 v47, -v76, v28, v47
	v_fma_f32 v47, -v77, v29, v47
	v_fma_f32 v47, -v78, v30, v47
	v_fma_f32 v47, -v79, v31, v47
	ds_read_b128 v[76:79], v64 offset:13344
	s_waitcnt lgkmcnt(11)
	v_fma_f32 v48, -v80, v28, v48
	v_fma_f32 v48, -v81, v29, v48
	v_fma_f32 v48, -v82, v30, v48
	v_fma_f32 v48, -v83, v31, v48
	ds_read_b128 v[80:83], v64 offset:13616
	s_waitcnt lgkmcnt(11)
	v_fma_f32 v47, -v84, v32, v47
	v_fma_f32 v47, -v85, v33, v47
	v_fma_f32 v47, -v86, v34, v47
	v_fma_f32 v47, -v87, v35, v47
	ds_read_b128 v[84:87], v64 offset:13360
	s_waitcnt lgkmcnt(11)
	v_fma_f32 v48, -v88, v32, v48
	v_fma_f32 v48, -v89, v33, v48
	v_fma_f32 v48, -v90, v34, v48
	v_fma_f32 v48, -v91, v35, v48
	ds_read_b128 v[88:91], v64 offset:13632
	s_waitcnt lgkmcnt(11)
	v_fma_f32 v47, -v92, v36, v47
	v_fma_f32 v47, -v93, v37, v47
	v_fma_f32 v47, -v94, v38, v47
	v_fma_f32 v47, -v95, v39, v47
	ds_read_b128 v[92:95], v64 offset:13376
	s_waitcnt lgkmcnt(11)
	v_fma_f32 v48, -v96, v36, v48
	v_fma_f32 v48, -v97, v37, v48
	v_fma_f32 v48, -v98, v38, v48
	v_fma_f32 v48, -v99, v39, v48
	ds_read_b128 v[96:99], v64 offset:13648
	s_waitcnt lgkmcnt(11)
	v_fma_f32 v47, -v100, v40, v47
	v_fma_f32 v47, -v101, v41, v47
	v_fma_f32 v47, -v102, v42, v47
	v_fma_f32 v47, -v103, v43, v47
	ds_read_b128 v[100:103], v64 offset:13392
	s_waitcnt lgkmcnt(11)
	v_fma_f32 v48, -v104, v40, v48
	v_fma_f32 v48, -v105, v41, v48
	v_fma_f32 v48, -v106, v42, v48
	v_fma_f32 v48, -v107, v43, v48
	ds_read_b128 v[104:107], v64 offset:13664
	s_waitcnt lgkmcnt(11)
	v_fma_f32 v47, -v108, v44, v47
	v_fma_f32 v47, -v109, v45, v47
	v_fma_f32 v47, -v110, v46, v47
	ds_read_b128 v[108:111], v64 offset:13408
	s_waitcnt lgkmcnt(11)
	v_fma_f32 v48, -v112, v44, v48
	v_fma_f32 v48, -v113, v45, v48
	v_fma_f32 v48, -v114, v46, v48
	v_fma_f32 v48, -v115, v47, v48
	ds_read_b128 v[112:115], v64 offset:13680
	s_waitcnt lgkmcnt(11)
	v_fma_f32 v49, -v68, v153, v204
	v_fma_f32 v49, -v69, v1, v49
	v_fma_f32 v49, -v70, v2, v49
	v_fma_f32 v49, -v71, v3, v49
	ds_read_b128 v[68:71], v64 offset:13424
	s_waitcnt lgkmcnt(11)
	v_fma_f32 v50, -v72, v153, v205
	v_fma_f32 v50, -v73, v1, v50
	v_fma_f32 v50, -v74, v2, v50
	v_fma_f32 v50, -v75, v3, v50
	ds_read_b128 v[72:75], v64 offset:13696
	s_waitcnt lgkmcnt(11)
	v_fma_f32 v49, -v76, v4, v49
	v_fma_f32 v49, -v77, v5, v49
	v_fma_f32 v49, -v78, v6, v49
	v_fma_f32 v49, -v79, v7, v49
	ds_read_b128 v[76:79], v64 offset:13440
	s_waitcnt lgkmcnt(11)
	v_fma_f32 v50, -v80, v4, v50
	v_fma_f32 v50, -v81, v5, v50
	v_fma_f32 v50, -v82, v6, v50
	v_fma_f32 v50, -v83, v7, v50
	ds_read_b128 v[80:83], v64 offset:13712
	s_waitcnt lgkmcnt(11)
	v_fma_f32 v49, -v84, v8, v49
	v_fma_f32 v49, -v85, v9, v49
	v_fma_f32 v49, -v86, v10, v49
	v_fma_f32 v49, -v87, v11, v49
	ds_read_b128 v[84:87], v64 offset:13456
	s_waitcnt lgkmcnt(11)
	v_fma_f32 v50, -v88, v8, v50
	v_fma_f32 v50, -v89, v9, v50
	v_fma_f32 v50, -v90, v10, v50
	v_fma_f32 v50, -v91, v11, v50
	ds_read_b128 v[88:91], v64 offset:13728
	s_waitcnt lgkmcnt(11)
	v_fma_f32 v49, -v92, v12, v49
	v_fma_f32 v49, -v93, v13, v49
	v_fma_f32 v49, -v94, v14, v49
	v_fma_f32 v49, -v95, v15, v49
	ds_read_b128 v[92:95], v64 offset:13472
	s_waitcnt lgkmcnt(11)
	v_fma_f32 v50, -v96, v12, v50
	v_fma_f32 v50, -v97, v13, v50
	v_fma_f32 v50, -v98, v14, v50
	v_fma_f32 v50, -v99, v15, v50
	ds_read_b128 v[96:99], v64 offset:13744
	s_waitcnt lgkmcnt(11)
	v_fma_f32 v49, -v100, v16, v49
	v_fma_f32 v49, -v101, v17, v49
	v_fma_f32 v49, -v102, v18, v49
	v_fma_f32 v49, -v103, v19, v49
	ds_read_b128 v[100:103], v64 offset:13488
	s_waitcnt lgkmcnt(11)
	v_fma_f32 v50, -v104, v16, v50
	v_fma_f32 v50, -v105, v17, v50
	v_fma_f32 v50, -v106, v18, v50
	v_fma_f32 v50, -v107, v19, v50
	ds_read_b128 v[104:107], v64 offset:13760
	s_waitcnt lgkmcnt(11)
	v_fma_f32 v49, -v108, v20, v49
	v_fma_f32 v49, -v109, v21, v49
	v_fma_f32 v49, -v110, v22, v49
	v_fma_f32 v49, -v111, v23, v49
	ds_read_b128 v[108:111], v64 offset:13504
	s_waitcnt lgkmcnt(11)
	v_fma_f32 v50, -v112, v20, v50
	v_fma_f32 v50, -v113, v21, v50
	v_fma_f32 v50, -v114, v22, v50
	v_fma_f32 v50, -v115, v23, v50
	ds_read_b128 v[112:115], v64 offset:13776
	s_waitcnt lgkmcnt(11)
	v_fma_f32 v49, -v68, v24, v49
	v_fma_f32 v49, -v69, v25, v49
	v_fma_f32 v49, -v70, v26, v49
	v_fma_f32 v49, -v71, v27, v49
	ds_read_b128 v[68:71], v64 offset:13520
	s_waitcnt lgkmcnt(11)
	v_fma_f32 v50, -v72, v24, v50
	v_fma_f32 v50, -v73, v25, v50
	v_fma_f32 v50, -v74, v26, v50
	v_fma_f32 v50, -v75, v27, v50
	ds_read_b128 v[72:75], v64 offset:13792
	s_waitcnt lgkmcnt(11)
	v_fma_f32 v49, -v76, v28, v49
	v_fma_f32 v49, -v77, v29, v49
	v_fma_f32 v49, -v78, v30, v49
	v_fma_f32 v49, -v79, v31, v49
	ds_read_b128 v[76:79], v64 offset:13872
	s_waitcnt lgkmcnt(11)
	v_fma_f32 v50, -v80, v28, v50
	v_fma_f32 v50, -v81, v29, v50
	v_fma_f32 v50, -v82, v30, v50
	v_fma_f32 v50, -v83, v31, v50
	ds_read_b128 v[80:83], v64 offset:14144
	s_waitcnt lgkmcnt(11)
	v_fma_f32 v49, -v84, v32, v49
	v_fma_f32 v49, -v85, v33, v49
	v_fma_f32 v49, -v86, v34, v49
	v_fma_f32 v49, -v87, v35, v49
	ds_read_b128 v[84:87], v64 offset:13888
	s_waitcnt lgkmcnt(11)
	v_fma_f32 v50, -v88, v32, v50
	v_fma_f32 v50, -v89, v33, v50
	v_fma_f32 v50, -v90, v34, v50
	v_fma_f32 v50, -v91, v35, v50
	ds_read_b128 v[88:91], v64 offset:14160
	s_waitcnt lgkmcnt(11)
	v_fma_f32 v49, -v92, v36, v49
	v_fma_f32 v49, -v93, v37, v49
	v_fma_f32 v49, -v94, v38, v49
	v_fma_f32 v49, -v95, v39, v49
	ds_read_b128 v[92:95], v64 offset:13904
	s_waitcnt lgkmcnt(11)
	v_fma_f32 v50, -v96, v36, v50
	v_fma_f32 v50, -v97, v37, v50
	v_fma_f32 v50, -v98, v38, v50
	v_fma_f32 v50, -v99, v39, v50
	ds_read_b128 v[96:99], v64 offset:14176
	s_waitcnt lgkmcnt(11)
	v_fma_f32 v49, -v100, v40, v49
	v_fma_f32 v49, -v101, v41, v49
	v_fma_f32 v49, -v102, v42, v49
	v_fma_f32 v49, -v103, v43, v49
	ds_read_b128 v[100:103], v64 offset:13920
	s_waitcnt lgkmcnt(11)
	v_fma_f32 v50, -v104, v40, v50
	v_fma_f32 v50, -v105, v41, v50
	v_fma_f32 v50, -v106, v42, v50
	v_fma_f32 v50, -v107, v43, v50
	ds_read_b128 v[104:107], v64 offset:14192
	s_waitcnt lgkmcnt(11)
	v_fma_f32 v49, -v108, v44, v49
	v_fma_f32 v49, -v109, v45, v49
	v_fma_f32 v49, -v110, v46, v49
	v_fma_f32 v49, -v111, v47, v49
	ds_read_b128 v[108:111], v64 offset:13936
	s_waitcnt lgkmcnt(11)
	v_fma_f32 v50, -v112, v44, v50
	v_fma_f32 v50, -v113, v45, v50
	v_fma_f32 v50, -v114, v46, v50
	v_fma_f32 v50, -v115, v47, v50
	ds_read_b128 v[112:115], v64 offset:14208
	s_waitcnt lgkmcnt(11)
	v_fma_f32 v49, -v68, v48, v49
	ds_read_b128 v[68:71], v64 offset:13952
	s_waitcnt lgkmcnt(11)
	v_fma_f32 v50, -v72, v48, v50
	v_fma_f32 v50, -v73, v49, v50
	ds_read_b128 v[72:75], v64 offset:14224
	s_waitcnt lgkmcnt(11)
	v_fma_f32 v51, -v76, v153, v206
	v_fma_f32 v51, -v77, v1, v51
	v_fma_f32 v51, -v78, v2, v51
	v_fma_f32 v51, -v79, v3, v51
	ds_read_b128 v[76:79], v64 offset:13968
	s_waitcnt lgkmcnt(11)
	v_fma_f32 v52, -v80, v153, v207
	v_fma_f32 v52, -v81, v1, v52
	v_fma_f32 v52, -v82, v2, v52
	v_fma_f32 v52, -v83, v3, v52
	ds_read_b128 v[80:83], v64 offset:14240
	s_waitcnt lgkmcnt(11)
	v_fma_f32 v51, -v84, v4, v51
	v_fma_f32 v51, -v85, v5, v51
	v_fma_f32 v51, -v86, v6, v51
	v_fma_f32 v51, -v87, v7, v51
	ds_read_b128 v[84:87], v64 offset:13984
	s_waitcnt lgkmcnt(11)
	v_fma_f32 v52, -v88, v4, v52
	v_fma_f32 v52, -v89, v5, v52
	v_fma_f32 v52, -v90, v6, v52
	v_fma_f32 v52, -v91, v7, v52
	ds_read_b128 v[88:91], v64 offset:14256
	s_waitcnt lgkmcnt(11)
	v_fma_f32 v51, -v92, v8, v51
	v_fma_f32 v51, -v93, v9, v51
	v_fma_f32 v51, -v94, v10, v51
	v_fma_f32 v51, -v95, v11, v51
	ds_read_b128 v[92:95], v64 offset:14000
	s_waitcnt lgkmcnt(11)
	v_fma_f32 v52, -v96, v8, v52
	v_fma_f32 v52, -v97, v9, v52
	v_fma_f32 v52, -v98, v10, v52
	v_fma_f32 v52, -v99, v11, v52
	ds_read_b128 v[96:99], v64 offset:14272
	s_waitcnt lgkmcnt(11)
	v_fma_f32 v51, -v100, v12, v51
	v_fma_f32 v51, -v101, v13, v51
	v_fma_f32 v51, -v102, v14, v51
	v_fma_f32 v51, -v103, v15, v51
	ds_read_b128 v[100:103], v64 offset:14016
	s_waitcnt lgkmcnt(11)
	v_fma_f32 v52, -v104, v12, v52
	v_fma_f32 v52, -v105, v13, v52
	v_fma_f32 v52, -v106, v14, v52
	v_fma_f32 v52, -v107, v15, v52
	ds_read_b128 v[104:107], v64 offset:14288
	s_waitcnt lgkmcnt(11)
	v_fma_f32 v51, -v108, v16, v51
	v_fma_f32 v51, -v109, v17, v51
	v_fma_f32 v51, -v110, v18, v51
	v_fma_f32 v51, -v111, v19, v51
	ds_read_b128 v[108:111], v64 offset:14032
	s_waitcnt lgkmcnt(11)
	v_fma_f32 v52, -v112, v16, v52
	v_fma_f32 v52, -v113, v17, v52
	v_fma_f32 v52, -v114, v18, v52
	v_fma_f32 v52, -v115, v19, v52
	ds_read_b128 v[112:115], v64 offset:14304
	s_waitcnt lgkmcnt(11)
	v_fma_f32 v51, -v68, v20, v51
	v_fma_f32 v51, -v69, v21, v51
	v_fma_f32 v51, -v70, v22, v51
	v_fma_f32 v51, -v71, v23, v51
	ds_read_b128 v[68:71], v64 offset:14048
	s_waitcnt lgkmcnt(11)
	v_fma_f32 v52, -v72, v20, v52
	v_fma_f32 v52, -v73, v21, v52
	v_fma_f32 v52, -v74, v22, v52
	v_fma_f32 v52, -v75, v23, v52
	ds_read_b128 v[72:75], v64 offset:14320
	s_waitcnt lgkmcnt(11)
	v_fma_f32 v51, -v76, v24, v51
	v_fma_f32 v51, -v77, v25, v51
	v_fma_f32 v51, -v78, v26, v51
	v_fma_f32 v51, -v79, v27, v51
	ds_read_b128 v[76:79], v64 offset:14064
	s_waitcnt lgkmcnt(11)
	v_fma_f32 v52, -v80, v24, v52
	v_fma_f32 v52, -v81, v25, v52
	v_fma_f32 v52, -v82, v26, v52
	v_fma_f32 v52, -v83, v27, v52
	ds_read_b128 v[80:83], v64 offset:14336
	s_waitcnt lgkmcnt(11)
	v_fma_f32 v51, -v84, v28, v51
	v_fma_f32 v51, -v85, v29, v51
	v_fma_f32 v51, -v86, v30, v51
	v_fma_f32 v51, -v87, v31, v51
	ds_read_b128 v[84:87], v64 offset:14416
	s_waitcnt lgkmcnt(11)
	v_fma_f32 v52, -v88, v28, v52
	v_fma_f32 v52, -v89, v29, v52
	v_fma_f32 v52, -v90, v30, v52
	v_fma_f32 v52, -v91, v31, v52
	ds_read_b128 v[88:91], v64 offset:14688
	s_waitcnt lgkmcnt(11)
	v_fma_f32 v51, -v92, v32, v51
	v_fma_f32 v51, -v93, v33, v51
	v_fma_f32 v51, -v94, v34, v51
	v_fma_f32 v51, -v95, v35, v51
	ds_read_b128 v[92:95], v64 offset:14432
	s_waitcnt lgkmcnt(11)
	v_fma_f32 v52, -v96, v32, v52
	v_fma_f32 v52, -v97, v33, v52
	v_fma_f32 v52, -v98, v34, v52
	v_fma_f32 v52, -v99, v35, v52
	ds_read_b128 v[96:99], v64 offset:14704
	s_waitcnt lgkmcnt(11)
	v_fma_f32 v51, -v100, v36, v51
	v_fma_f32 v51, -v101, v37, v51
	v_fma_f32 v51, -v102, v38, v51
	v_fma_f32 v51, -v103, v39, v51
	ds_read_b128 v[100:103], v64 offset:14448
	s_waitcnt lgkmcnt(11)
	v_fma_f32 v52, -v104, v36, v52
	v_fma_f32 v52, -v105, v37, v52
	v_fma_f32 v52, -v106, v38, v52
	v_fma_f32 v52, -v107, v39, v52
	ds_read_b128 v[104:107], v64 offset:14720
	s_waitcnt lgkmcnt(11)
	v_fma_f32 v51, -v108, v40, v51
	v_fma_f32 v51, -v109, v41, v51
	v_fma_f32 v51, -v110, v42, v51
	v_fma_f32 v51, -v111, v43, v51
	ds_read_b128 v[108:111], v64 offset:14464
	s_waitcnt lgkmcnt(11)
	v_fma_f32 v52, -v112, v40, v52
	v_fma_f32 v52, -v113, v41, v52
	v_fma_f32 v52, -v114, v42, v52
	v_fma_f32 v52, -v115, v43, v52
	ds_read_b128 v[112:115], v64 offset:14736
	s_waitcnt lgkmcnt(11)
	v_fma_f32 v51, -v68, v44, v51
	v_fma_f32 v51, -v69, v45, v51
	v_fma_f32 v51, -v70, v46, v51
	v_fma_f32 v51, -v71, v47, v51
	ds_read_b128 v[68:71], v64 offset:14480
	s_waitcnt lgkmcnt(11)
	v_fma_f32 v52, -v72, v44, v52
	v_fma_f32 v52, -v73, v45, v52
	v_fma_f32 v52, -v74, v46, v52
	v_fma_f32 v52, -v75, v47, v52
	ds_read_b128 v[72:75], v64 offset:14752
	s_waitcnt lgkmcnt(11)
	v_fma_f32 v51, -v76, v48, v51
	v_fma_f32 v51, -v77, v49, v51
	v_fma_f32 v51, -v78, v50, v51
	ds_read_b128 v[76:79], v64 offset:14496
	s_waitcnt lgkmcnt(11)
	v_fma_f32 v52, -v80, v48, v52
	v_fma_f32 v52, -v81, v49, v52
	v_fma_f32 v52, -v82, v50, v52
	v_fma_f32 v52, -v83, v51, v52
	ds_read_b128 v[80:83], v64 offset:14768
	s_waitcnt lgkmcnt(11)
	v_fma_f32 v53, -v84, v153, v208
	v_fma_f32 v53, -v85, v1, v53
	v_fma_f32 v53, -v86, v2, v53
	v_fma_f32 v53, -v87, v3, v53
	ds_read_b128 v[84:87], v64 offset:14512
	s_waitcnt lgkmcnt(11)
	v_fma_f32 v54, -v88, v153, v209
	v_fma_f32 v54, -v89, v1, v54
	v_fma_f32 v54, -v90, v2, v54
	v_fma_f32 v54, -v91, v3, v54
	ds_read_b128 v[88:91], v64 offset:14784
	s_waitcnt lgkmcnt(11)
	v_fma_f32 v53, -v92, v4, v53
	v_fma_f32 v53, -v93, v5, v53
	v_fma_f32 v53, -v94, v6, v53
	v_fma_f32 v53, -v95, v7, v53
	ds_read_b128 v[92:95], v64 offset:14528
	s_waitcnt lgkmcnt(11)
	v_fma_f32 v54, -v96, v4, v54
	v_fma_f32 v54, -v97, v5, v54
	v_fma_f32 v54, -v98, v6, v54
	v_fma_f32 v54, -v99, v7, v54
	ds_read_b128 v[96:99], v64 offset:14800
	s_waitcnt lgkmcnt(11)
	v_fma_f32 v53, -v100, v8, v53
	v_fma_f32 v53, -v101, v9, v53
	v_fma_f32 v53, -v102, v10, v53
	v_fma_f32 v53, -v103, v11, v53
	ds_read_b128 v[100:103], v64 offset:14544
	s_waitcnt lgkmcnt(11)
	v_fma_f32 v54, -v104, v8, v54
	v_fma_f32 v54, -v105, v9, v54
	v_fma_f32 v54, -v106, v10, v54
	v_fma_f32 v54, -v107, v11, v54
	ds_read_b128 v[104:107], v64 offset:14816
	s_waitcnt lgkmcnt(11)
	v_fma_f32 v53, -v108, v12, v53
	v_fma_f32 v53, -v109, v13, v53
	v_fma_f32 v53, -v110, v14, v53
	v_fma_f32 v53, -v111, v15, v53
	ds_read_b128 v[108:111], v64 offset:14560
	s_waitcnt lgkmcnt(11)
	v_fma_f32 v54, -v112, v12, v54
	v_fma_f32 v54, -v113, v13, v54
	v_fma_f32 v54, -v114, v14, v54
	v_fma_f32 v54, -v115, v15, v54
	ds_read_b128 v[112:115], v64 offset:14832
	s_waitcnt lgkmcnt(11)
	v_fma_f32 v53, -v68, v16, v53
	v_fma_f32 v53, -v69, v17, v53
	v_fma_f32 v53, -v70, v18, v53
	v_fma_f32 v53, -v71, v19, v53
	ds_read_b128 v[68:71], v64 offset:14576
	s_waitcnt lgkmcnt(11)
	v_fma_f32 v54, -v72, v16, v54
	v_fma_f32 v54, -v73, v17, v54
	v_fma_f32 v54, -v74, v18, v54
	v_fma_f32 v54, -v75, v19, v54
	ds_read_b128 v[72:75], v64 offset:14848
	s_waitcnt lgkmcnt(11)
	v_fma_f32 v53, -v76, v20, v53
	v_fma_f32 v53, -v77, v21, v53
	v_fma_f32 v53, -v78, v22, v53
	v_fma_f32 v53, -v79, v23, v53
	ds_read_b128 v[76:79], v64 offset:14592
	s_waitcnt lgkmcnt(11)
	v_fma_f32 v54, -v80, v20, v54
	v_fma_f32 v54, -v81, v21, v54
	v_fma_f32 v54, -v82, v22, v54
	v_fma_f32 v54, -v83, v23, v54
	ds_read_b128 v[80:83], v64 offset:14864
	s_waitcnt lgkmcnt(11)
	v_fma_f32 v53, -v84, v24, v53
	v_fma_f32 v53, -v85, v25, v53
	v_fma_f32 v53, -v86, v26, v53
	v_fma_f32 v53, -v87, v27, v53
	ds_read_b128 v[84:87], v64 offset:14608
	s_waitcnt lgkmcnt(11)
	v_fma_f32 v54, -v88, v24, v54
	v_fma_f32 v54, -v89, v25, v54
	v_fma_f32 v54, -v90, v26, v54
	v_fma_f32 v54, -v91, v27, v54
	ds_read_b128 v[88:91], v64 offset:14880
	s_waitcnt lgkmcnt(11)
	v_fma_f32 v53, -v92, v28, v53
	v_fma_f32 v53, -v93, v29, v53
	v_fma_f32 v53, -v94, v30, v53
	v_fma_f32 v53, -v95, v31, v53
	ds_read_b128 v[92:95], v64 offset:14624
	s_waitcnt lgkmcnt(11)
	v_fma_f32 v54, -v96, v28, v54
	v_fma_f32 v54, -v97, v29, v54
	v_fma_f32 v54, -v98, v30, v54
	v_fma_f32 v54, -v99, v31, v54
	ds_read_b128 v[96:99], v64 offset:14896
	s_waitcnt lgkmcnt(11)
	v_fma_f32 v53, -v100, v32, v53
	v_fma_f32 v53, -v101, v33, v53
	v_fma_f32 v53, -v102, v34, v53
	v_fma_f32 v53, -v103, v35, v53
	ds_read_b128 v[100:103], v64 offset:14960
	s_waitcnt lgkmcnt(11)
	v_fma_f32 v54, -v104, v32, v54
	v_fma_f32 v54, -v105, v33, v54
	v_fma_f32 v54, -v106, v34, v54
	v_fma_f32 v54, -v107, v35, v54
	ds_read_b128 v[104:107], v64 offset:15232
	s_waitcnt lgkmcnt(11)
	v_fma_f32 v53, -v108, v36, v53
	v_fma_f32 v53, -v109, v37, v53
	v_fma_f32 v53, -v110, v38, v53
	v_fma_f32 v53, -v111, v39, v53
	ds_read_b128 v[108:111], v64 offset:14976
	s_waitcnt lgkmcnt(11)
	v_fma_f32 v54, -v112, v36, v54
	v_fma_f32 v54, -v113, v37, v54
	v_fma_f32 v54, -v114, v38, v54
	v_fma_f32 v54, -v115, v39, v54
	ds_read_b128 v[112:115], v64 offset:15248
	s_waitcnt lgkmcnt(11)
	v_fma_f32 v53, -v68, v40, v53
	v_fma_f32 v53, -v69, v41, v53
	v_fma_f32 v53, -v70, v42, v53
	v_fma_f32 v53, -v71, v43, v53
	ds_read_b128 v[68:71], v64 offset:14992
	s_waitcnt lgkmcnt(11)
	v_fma_f32 v54, -v72, v40, v54
	v_fma_f32 v54, -v73, v41, v54
	v_fma_f32 v54, -v74, v42, v54
	v_fma_f32 v54, -v75, v43, v54
	ds_read_b128 v[72:75], v64 offset:15264
	s_waitcnt lgkmcnt(11)
	v_fma_f32 v53, -v76, v44, v53
	v_fma_f32 v53, -v77, v45, v53
	v_fma_f32 v53, -v78, v46, v53
	v_fma_f32 v53, -v79, v47, v53
	ds_read_b128 v[76:79], v64 offset:15008
	s_waitcnt lgkmcnt(11)
	v_fma_f32 v54, -v80, v44, v54
	v_fma_f32 v54, -v81, v45, v54
	v_fma_f32 v54, -v82, v46, v54
	v_fma_f32 v54, -v83, v47, v54
	ds_read_b128 v[80:83], v64 offset:15280
	s_waitcnt lgkmcnt(11)
	v_fma_f32 v53, -v84, v48, v53
	v_fma_f32 v53, -v85, v49, v53
	v_fma_f32 v53, -v86, v50, v53
	v_fma_f32 v53, -v87, v51, v53
	ds_read_b128 v[84:87], v64 offset:15024
	s_waitcnt lgkmcnt(11)
	v_fma_f32 v54, -v88, v48, v54
	v_fma_f32 v54, -v89, v49, v54
	v_fma_f32 v54, -v90, v50, v54
	v_fma_f32 v54, -v91, v51, v54
	ds_read_b128 v[88:91], v64 offset:15296
	s_waitcnt lgkmcnt(11)
	v_fma_f32 v53, -v92, v52, v53
	ds_read_b128 v[92:95], v64 offset:15040
	s_waitcnt lgkmcnt(11)
	v_fma_f32 v54, -v96, v52, v54
	v_fma_f32 v54, -v97, v53, v54
	ds_read_b128 v[96:99], v64 offset:15312
	s_waitcnt lgkmcnt(11)
	v_fma_f32 v55, -v100, v153, v210
	v_fma_f32 v55, -v101, v1, v55
	v_fma_f32 v55, -v102, v2, v55
	v_fma_f32 v55, -v103, v3, v55
	ds_read_b128 v[100:103], v64 offset:15056
	s_waitcnt lgkmcnt(11)
	v_fma_f32 v56, -v104, v153, v211
	v_fma_f32 v56, -v105, v1, v56
	v_fma_f32 v56, -v106, v2, v56
	v_fma_f32 v56, -v107, v3, v56
	ds_read_b128 v[104:107], v64 offset:15328
	s_waitcnt lgkmcnt(11)
	v_fma_f32 v55, -v108, v4, v55
	v_fma_f32 v55, -v109, v5, v55
	v_fma_f32 v55, -v110, v6, v55
	v_fma_f32 v55, -v111, v7, v55
	ds_read_b128 v[108:111], v64 offset:15072
	s_waitcnt lgkmcnt(11)
	v_fma_f32 v56, -v112, v4, v56
	v_fma_f32 v56, -v113, v5, v56
	v_fma_f32 v56, -v114, v6, v56
	v_fma_f32 v56, -v115, v7, v56
	ds_read_b128 v[112:115], v64 offset:15344
	s_waitcnt lgkmcnt(11)
	v_fma_f32 v55, -v68, v8, v55
	v_fma_f32 v55, -v69, v9, v55
	v_fma_f32 v55, -v70, v10, v55
	v_fma_f32 v55, -v71, v11, v55
	ds_read_b128 v[68:71], v64 offset:15088
	s_waitcnt lgkmcnt(11)
	v_fma_f32 v56, -v72, v8, v56
	v_fma_f32 v56, -v73, v9, v56
	v_fma_f32 v56, -v74, v10, v56
	v_fma_f32 v56, -v75, v11, v56
	ds_read_b128 v[72:75], v64 offset:15360
	s_waitcnt lgkmcnt(11)
	v_fma_f32 v55, -v76, v12, v55
	v_fma_f32 v55, -v77, v13, v55
	v_fma_f32 v55, -v78, v14, v55
	v_fma_f32 v55, -v79, v15, v55
	ds_read_b128 v[76:79], v64 offset:15104
	s_waitcnt lgkmcnt(11)
	v_fma_f32 v56, -v80, v12, v56
	v_fma_f32 v56, -v81, v13, v56
	v_fma_f32 v56, -v82, v14, v56
	v_fma_f32 v56, -v83, v15, v56
	ds_read_b128 v[80:83], v64 offset:15376
	s_waitcnt lgkmcnt(11)
	v_fma_f32 v55, -v84, v16, v55
	v_fma_f32 v55, -v85, v17, v55
	v_fma_f32 v55, -v86, v18, v55
	v_fma_f32 v55, -v87, v19, v55
	ds_read_b128 v[84:87], v64 offset:15120
	s_waitcnt lgkmcnt(11)
	v_fma_f32 v56, -v88, v16, v56
	v_fma_f32 v56, -v89, v17, v56
	v_fma_f32 v56, -v90, v18, v56
	v_fma_f32 v56, -v91, v19, v56
	ds_read_b128 v[88:91], v64 offset:15392
	s_waitcnt lgkmcnt(11)
	v_fma_f32 v55, -v92, v20, v55
	v_fma_f32 v55, -v93, v21, v55
	v_fma_f32 v55, -v94, v22, v55
	v_fma_f32 v55, -v95, v23, v55
	ds_read_b128 v[92:95], v64 offset:15136
	s_waitcnt lgkmcnt(11)
	v_fma_f32 v56, -v96, v20, v56
	v_fma_f32 v56, -v97, v21, v56
	v_fma_f32 v56, -v98, v22, v56
	v_fma_f32 v56, -v99, v23, v56
	ds_read_b128 v[96:99], v64 offset:15408
	s_waitcnt lgkmcnt(11)
	v_fma_f32 v55, -v100, v24, v55
	v_fma_f32 v55, -v101, v25, v55
	v_fma_f32 v55, -v102, v26, v55
	v_fma_f32 v55, -v103, v27, v55
	ds_read_b128 v[100:103], v64 offset:15152
	s_waitcnt lgkmcnt(11)
	v_fma_f32 v56, -v104, v24, v56
	v_fma_f32 v56, -v105, v25, v56
	v_fma_f32 v56, -v106, v26, v56
	v_fma_f32 v56, -v107, v27, v56
	ds_read_b128 v[104:107], v64 offset:15424
	s_waitcnt lgkmcnt(11)
	v_fma_f32 v55, -v108, v28, v55
	v_fma_f32 v55, -v109, v29, v55
	v_fma_f32 v55, -v110, v30, v55
	v_fma_f32 v55, -v111, v31, v55
	ds_read_b128 v[108:111], v64 offset:15168
	s_waitcnt lgkmcnt(11)
	v_fma_f32 v56, -v112, v28, v56
	v_fma_f32 v56, -v113, v29, v56
	v_fma_f32 v56, -v114, v30, v56
	v_fma_f32 v56, -v115, v31, v56
	ds_read_b128 v[112:115], v64 offset:15440
	s_waitcnt lgkmcnt(11)
	v_fma_f32 v55, -v68, v32, v55
	v_fma_f32 v55, -v69, v33, v55
	v_fma_f32 v55, -v70, v34, v55
	v_fma_f32 v55, -v71, v35, v55
	ds_read_b128 v[68:71], v64 offset:15504
	s_waitcnt lgkmcnt(11)
	v_fma_f32 v56, -v72, v32, v56
	v_fma_f32 v56, -v73, v33, v56
	v_fma_f32 v56, -v74, v34, v56
	v_fma_f32 v56, -v75, v35, v56
	ds_read_b128 v[72:75], v64 offset:15776
	s_waitcnt lgkmcnt(11)
	v_fma_f32 v55, -v76, v36, v55
	v_fma_f32 v55, -v77, v37, v55
	v_fma_f32 v55, -v78, v38, v55
	v_fma_f32 v55, -v79, v39, v55
	ds_read_b128 v[76:79], v64 offset:15520
	s_waitcnt lgkmcnt(11)
	v_fma_f32 v56, -v80, v36, v56
	v_fma_f32 v56, -v81, v37, v56
	v_fma_f32 v56, -v82, v38, v56
	v_fma_f32 v56, -v83, v39, v56
	ds_read_b128 v[80:83], v64 offset:15792
	s_waitcnt lgkmcnt(11)
	v_fma_f32 v55, -v84, v40, v55
	v_fma_f32 v55, -v85, v41, v55
	v_fma_f32 v55, -v86, v42, v55
	v_fma_f32 v55, -v87, v43, v55
	ds_read_b128 v[84:87], v64 offset:15536
	s_waitcnt lgkmcnt(11)
	v_fma_f32 v56, -v88, v40, v56
	v_fma_f32 v56, -v89, v41, v56
	v_fma_f32 v56, -v90, v42, v56
	v_fma_f32 v56, -v91, v43, v56
	ds_read_b128 v[88:91], v64 offset:15808
	s_waitcnt lgkmcnt(11)
	v_fma_f32 v55, -v92, v44, v55
	v_fma_f32 v55, -v93, v45, v55
	v_fma_f32 v55, -v94, v46, v55
	v_fma_f32 v55, -v95, v47, v55
	ds_read_b128 v[92:95], v64 offset:15552
	s_waitcnt lgkmcnt(11)
	v_fma_f32 v56, -v96, v44, v56
	v_fma_f32 v56, -v97, v45, v56
	v_fma_f32 v56, -v98, v46, v56
	v_fma_f32 v56, -v99, v47, v56
	ds_read_b128 v[96:99], v64 offset:15824
	s_waitcnt lgkmcnt(11)
	v_fma_f32 v55, -v100, v48, v55
	v_fma_f32 v55, -v101, v49, v55
	v_fma_f32 v55, -v102, v50, v55
	v_fma_f32 v55, -v103, v51, v55
	ds_read_b128 v[100:103], v64 offset:15568
	s_waitcnt lgkmcnt(11)
	v_fma_f32 v56, -v104, v48, v56
	v_fma_f32 v56, -v105, v49, v56
	v_fma_f32 v56, -v106, v50, v56
	v_fma_f32 v56, -v107, v51, v56
	ds_read_b128 v[104:107], v64 offset:15840
	s_waitcnt lgkmcnt(11)
	v_fma_f32 v55, -v108, v52, v55
	v_fma_f32 v55, -v109, v53, v55
	v_fma_f32 v55, -v110, v54, v55
	ds_read_b128 v[108:111], v64 offset:15584
	s_waitcnt lgkmcnt(11)
	v_fma_f32 v56, -v112, v52, v56
	v_fma_f32 v56, -v113, v53, v56
	v_fma_f32 v56, -v114, v54, v56
	v_fma_f32 v56, -v115, v55, v56
	ds_read_b128 v[112:115], v64 offset:15856
	s_waitcnt lgkmcnt(11)
	v_fma_f32 v57, -v68, v153, v212
	v_fma_f32 v57, -v69, v1, v57
	v_fma_f32 v57, -v70, v2, v57
	v_fma_f32 v57, -v71, v3, v57
	ds_read_b128 v[68:71], v64 offset:15600
	s_waitcnt lgkmcnt(11)
	v_fma_f32 v58, -v72, v153, v213
	v_fma_f32 v58, -v73, v1, v58
	v_fma_f32 v58, -v74, v2, v58
	v_fma_f32 v58, -v75, v3, v58
	ds_read_b128 v[72:75], v64 offset:15872
	s_waitcnt lgkmcnt(11)
	v_fma_f32 v57, -v76, v4, v57
	v_fma_f32 v57, -v77, v5, v57
	v_fma_f32 v57, -v78, v6, v57
	v_fma_f32 v57, -v79, v7, v57
	ds_read_b128 v[76:79], v64 offset:15616
	s_waitcnt lgkmcnt(11)
	v_fma_f32 v58, -v80, v4, v58
	v_fma_f32 v58, -v81, v5, v58
	v_fma_f32 v58, -v82, v6, v58
	v_fma_f32 v58, -v83, v7, v58
	ds_read_b128 v[80:83], v64 offset:15888
	s_waitcnt lgkmcnt(11)
	v_fma_f32 v57, -v84, v8, v57
	v_fma_f32 v57, -v85, v9, v57
	v_fma_f32 v57, -v86, v10, v57
	v_fma_f32 v57, -v87, v11, v57
	ds_read_b128 v[84:87], v64 offset:15632
	s_waitcnt lgkmcnt(11)
	v_fma_f32 v58, -v88, v8, v58
	v_fma_f32 v58, -v89, v9, v58
	v_fma_f32 v58, -v90, v10, v58
	v_fma_f32 v58, -v91, v11, v58
	ds_read_b128 v[88:91], v64 offset:15904
	s_waitcnt lgkmcnt(11)
	v_fma_f32 v57, -v92, v12, v57
	v_fma_f32 v57, -v93, v13, v57
	v_fma_f32 v57, -v94, v14, v57
	v_fma_f32 v57, -v95, v15, v57
	ds_read_b128 v[92:95], v64 offset:15648
	s_waitcnt lgkmcnt(11)
	v_fma_f32 v58, -v96, v12, v58
	v_fma_f32 v58, -v97, v13, v58
	v_fma_f32 v58, -v98, v14, v58
	v_fma_f32 v58, -v99, v15, v58
	ds_read_b128 v[96:99], v64 offset:15920
	s_waitcnt lgkmcnt(11)
	v_fma_f32 v57, -v100, v16, v57
	v_fma_f32 v57, -v101, v17, v57
	v_fma_f32 v57, -v102, v18, v57
	v_fma_f32 v57, -v103, v19, v57
	ds_read_b128 v[100:103], v64 offset:15664
	s_waitcnt lgkmcnt(11)
	v_fma_f32 v58, -v104, v16, v58
	v_fma_f32 v58, -v105, v17, v58
	v_fma_f32 v58, -v106, v18, v58
	v_fma_f32 v58, -v107, v19, v58
	ds_read_b128 v[104:107], v64 offset:15936
	s_waitcnt lgkmcnt(11)
	v_fma_f32 v57, -v108, v20, v57
	v_fma_f32 v57, -v109, v21, v57
	v_fma_f32 v57, -v110, v22, v57
	v_fma_f32 v57, -v111, v23, v57
	ds_read_b128 v[108:111], v64 offset:15680
	s_waitcnt lgkmcnt(11)
	v_fma_f32 v58, -v112, v20, v58
	v_fma_f32 v58, -v113, v21, v58
	v_fma_f32 v58, -v114, v22, v58
	v_fma_f32 v58, -v115, v23, v58
	ds_read_b128 v[112:115], v64 offset:15952
	s_waitcnt lgkmcnt(11)
	v_fma_f32 v57, -v68, v24, v57
	v_fma_f32 v57, -v69, v25, v57
	v_fma_f32 v57, -v70, v26, v57
	v_fma_f32 v57, -v71, v27, v57
	ds_read_b128 v[68:71], v64 offset:15696
	s_waitcnt lgkmcnt(11)
	v_fma_f32 v58, -v72, v24, v58
	v_fma_f32 v58, -v73, v25, v58
	v_fma_f32 v58, -v74, v26, v58
	v_fma_f32 v58, -v75, v27, v58
	ds_read_b128 v[72:75], v64 offset:15968
	s_waitcnt lgkmcnt(11)
	v_fma_f32 v57, -v76, v28, v57
	v_fma_f32 v57, -v77, v29, v57
	v_fma_f32 v57, -v78, v30, v57
	v_fma_f32 v57, -v79, v31, v57
	ds_read_b128 v[76:79], v64 offset:15712
	s_waitcnt lgkmcnt(11)
	v_fma_f32 v58, -v80, v28, v58
	v_fma_f32 v58, -v81, v29, v58
	v_fma_f32 v58, -v82, v30, v58
	v_fma_f32 v58, -v83, v31, v58
	ds_read_b128 v[80:83], v64 offset:15984
	s_waitcnt lgkmcnt(11)
	v_fma_f32 v57, -v84, v32, v57
	v_fma_f32 v57, -v85, v33, v57
	v_fma_f32 v57, -v86, v34, v57
	v_fma_f32 v57, -v87, v35, v57
	ds_read_b128 v[84:87], v64 offset:15728
	s_waitcnt lgkmcnt(11)
	v_fma_f32 v58, -v88, v32, v58
	v_fma_f32 v58, -v89, v33, v58
	v_fma_f32 v58, -v90, v34, v58
	v_fma_f32 v58, -v91, v35, v58
	ds_read_b128 v[88:91], v64 offset:16000
	s_waitcnt lgkmcnt(11)
	v_fma_f32 v57, -v92, v36, v57
	v_fma_f32 v57, -v93, v37, v57
	v_fma_f32 v57, -v94, v38, v57
	v_fma_f32 v57, -v95, v39, v57
	ds_read_b128 v[92:95], v64 offset:16048
	s_waitcnt lgkmcnt(11)
	v_fma_f32 v58, -v96, v36, v58
	v_fma_f32 v58, -v97, v37, v58
	v_fma_f32 v58, -v98, v38, v58
	v_fma_f32 v58, -v99, v39, v58
	ds_read_b128 v[96:99], v64 offset:16320
	s_waitcnt lgkmcnt(11)
	v_fma_f32 v57, -v100, v40, v57
	v_fma_f32 v57, -v101, v41, v57
	v_fma_f32 v57, -v102, v42, v57
	v_fma_f32 v57, -v103, v43, v57
	ds_read_b128 v[100:103], v64 offset:16064
	s_waitcnt lgkmcnt(11)
	v_fma_f32 v58, -v104, v40, v58
	v_fma_f32 v58, -v105, v41, v58
	v_fma_f32 v58, -v106, v42, v58
	v_fma_f32 v58, -v107, v43, v58
	ds_read_b128 v[104:107], v64 offset:16336
	s_waitcnt lgkmcnt(11)
	v_fma_f32 v57, -v108, v44, v57
	v_fma_f32 v57, -v109, v45, v57
	v_fma_f32 v57, -v110, v46, v57
	v_fma_f32 v57, -v111, v47, v57
	ds_read_b128 v[108:111], v64 offset:16080
	s_waitcnt lgkmcnt(11)
	v_fma_f32 v58, -v112, v44, v58
	v_fma_f32 v58, -v113, v45, v58
	v_fma_f32 v58, -v114, v46, v58
	v_fma_f32 v58, -v115, v47, v58
	ds_read_b128 v[112:115], v64 offset:16352
	s_waitcnt lgkmcnt(11)
	v_fma_f32 v57, -v68, v48, v57
	v_fma_f32 v57, -v69, v49, v57
	v_fma_f32 v57, -v70, v50, v57
	v_fma_f32 v57, -v71, v51, v57
	ds_read_b128 v[68:71], v64 offset:16096
	s_waitcnt lgkmcnt(11)
	v_fma_f32 v58, -v72, v48, v58
	v_fma_f32 v58, -v73, v49, v58
	v_fma_f32 v58, -v74, v50, v58
	v_fma_f32 v58, -v75, v51, v58
	ds_read_b128 v[72:75], v64 offset:16368
	s_waitcnt lgkmcnt(11)
	v_fma_f32 v57, -v76, v52, v57
	v_fma_f32 v57, -v77, v53, v57
	v_fma_f32 v57, -v78, v54, v57
	v_fma_f32 v57, -v79, v55, v57
	ds_read_b128 v[76:79], v64 offset:16112
	s_waitcnt lgkmcnt(11)
	v_fma_f32 v58, -v80, v52, v58
	v_fma_f32 v58, -v81, v53, v58
	v_fma_f32 v58, -v82, v54, v58
	v_fma_f32 v58, -v83, v55, v58
	ds_read_b128 v[80:83], v64 offset:16384
	s_waitcnt lgkmcnt(11)
	v_fma_f32 v57, -v84, v56, v57
	ds_read_b128 v[84:87], v64 offset:16128
	s_waitcnt lgkmcnt(11)
	v_fma_f32 v58, -v88, v56, v58
	v_fma_f32 v58, -v89, v57, v58
	ds_read_b128 v[88:91], v64 offset:16400
	s_waitcnt lgkmcnt(11)
	v_fma_f32 v59, -v92, v153, v214
	v_fma_f32 v59, -v93, v1, v59
	v_fma_f32 v59, -v94, v2, v59
	v_fma_f32 v59, -v95, v3, v59
	ds_read_b128 v[92:95], v64 offset:16144
	s_waitcnt lgkmcnt(11)
	v_fma_f32 v60, -v96, v153, v215
	v_fma_f32 v60, -v97, v1, v60
	v_fma_f32 v60, -v98, v2, v60
	v_fma_f32 v60, -v99, v3, v60
	ds_read_b128 v[96:99], v64 offset:16416
	s_waitcnt lgkmcnt(11)
	v_fma_f32 v59, -v100, v4, v59
	v_fma_f32 v59, -v101, v5, v59
	v_fma_f32 v59, -v102, v6, v59
	v_fma_f32 v59, -v103, v7, v59
	ds_read_b128 v[100:103], v64 offset:16160
	s_waitcnt lgkmcnt(11)
	v_fma_f32 v60, -v104, v4, v60
	v_fma_f32 v60, -v105, v5, v60
	v_fma_f32 v60, -v106, v6, v60
	v_fma_f32 v60, -v107, v7, v60
	ds_read_b128 v[104:107], v64 offset:16432
	s_waitcnt lgkmcnt(11)
	v_fma_f32 v59, -v108, v8, v59
	v_fma_f32 v59, -v109, v9, v59
	v_fma_f32 v59, -v110, v10, v59
	v_fma_f32 v59, -v111, v11, v59
	ds_read_b128 v[108:111], v64 offset:16176
	s_waitcnt lgkmcnt(11)
	v_fma_f32 v60, -v112, v8, v60
	v_fma_f32 v60, -v113, v9, v60
	v_fma_f32 v60, -v114, v10, v60
	v_fma_f32 v60, -v115, v11, v60
	ds_read_b128 v[112:115], v64 offset:16448
	s_waitcnt lgkmcnt(11)
	v_fma_f32 v59, -v68, v12, v59
	v_fma_f32 v59, -v69, v13, v59
	v_fma_f32 v59, -v70, v14, v59
	v_fma_f32 v59, -v71, v15, v59
	ds_read_b128 v[68:71], v64 offset:16192
	s_waitcnt lgkmcnt(11)
	v_fma_f32 v60, -v72, v12, v60
	v_fma_f32 v60, -v73, v13, v60
	v_fma_f32 v60, -v74, v14, v60
	v_fma_f32 v60, -v75, v15, v60
	ds_read_b128 v[72:75], v64 offset:16464
	s_waitcnt lgkmcnt(11)
	v_fma_f32 v59, -v76, v16, v59
	v_fma_f32 v59, -v77, v17, v59
	v_fma_f32 v59, -v78, v18, v59
	v_fma_f32 v59, -v79, v19, v59
	ds_read_b128 v[76:79], v64 offset:16208
	s_waitcnt lgkmcnt(11)
	v_fma_f32 v60, -v80, v16, v60
	v_fma_f32 v60, -v81, v17, v60
	v_fma_f32 v60, -v82, v18, v60
	v_fma_f32 v60, -v83, v19, v60
	ds_read_b128 v[80:83], v64 offset:16480
	s_waitcnt lgkmcnt(11)
	v_fma_f32 v59, -v84, v20, v59
	v_fma_f32 v59, -v85, v21, v59
	v_fma_f32 v59, -v86, v22, v59
	v_fma_f32 v59, -v87, v23, v59
	ds_read_b128 v[84:87], v64 offset:16224
	s_waitcnt lgkmcnt(11)
	v_fma_f32 v60, -v88, v20, v60
	v_fma_f32 v60, -v89, v21, v60
	v_fma_f32 v60, -v90, v22, v60
	v_fma_f32 v60, -v91, v23, v60
	ds_read_b128 v[88:91], v64 offset:16496
	s_waitcnt lgkmcnt(11)
	v_fma_f32 v59, -v92, v24, v59
	v_fma_f32 v59, -v93, v25, v59
	v_fma_f32 v59, -v94, v26, v59
	v_fma_f32 v59, -v95, v27, v59
	ds_read_b128 v[92:95], v64 offset:16240
	s_waitcnt lgkmcnt(11)
	v_fma_f32 v60, -v96, v24, v60
	v_fma_f32 v60, -v97, v25, v60
	v_fma_f32 v60, -v98, v26, v60
	v_fma_f32 v60, -v99, v27, v60
	ds_read_b128 v[96:99], v64 offset:16512
	s_waitcnt lgkmcnt(11)
	v_fma_f32 v59, -v100, v28, v59
	v_fma_f32 v59, -v101, v29, v59
	v_fma_f32 v59, -v102, v30, v59
	v_fma_f32 v59, -v103, v31, v59
	ds_read_b128 v[100:103], v64 offset:16256
	s_waitcnt lgkmcnt(11)
	v_fma_f32 v60, -v104, v28, v60
	v_fma_f32 v60, -v105, v29, v60
	v_fma_f32 v60, -v106, v30, v60
	v_fma_f32 v60, -v107, v31, v60
	ds_read_b128 v[104:107], v64 offset:16528
	s_waitcnt lgkmcnt(11)
	v_fma_f32 v59, -v108, v32, v59
	v_fma_f32 v59, -v109, v33, v59
	v_fma_f32 v59, -v110, v34, v59
	v_fma_f32 v59, -v111, v35, v59
	ds_read_b128 v[108:111], v64 offset:16272
	s_waitcnt lgkmcnt(11)
	v_fma_f32 v60, -v112, v32, v60
	v_fma_f32 v60, -v113, v33, v60
	v_fma_f32 v60, -v114, v34, v60
	v_fma_f32 v60, -v115, v35, v60
	ds_read_b128 v[112:115], v64 offset:16544
	s_waitcnt lgkmcnt(11)
	v_fma_f32 v59, -v68, v36, v59
	v_fma_f32 v59, -v69, v37, v59
	v_fma_f32 v59, -v70, v38, v59
	v_fma_f32 v59, -v71, v39, v59
	ds_read_b128 v[68:71], v64 offset:16592
	s_waitcnt lgkmcnt(11)
	v_fma_f32 v60, -v72, v36, v60
	v_fma_f32 v60, -v73, v37, v60
	v_fma_f32 v60, -v74, v38, v60
	v_fma_f32 v60, -v75, v39, v60
	ds_read_b128 v[72:75], v64 offset:16864
	s_waitcnt lgkmcnt(11)
	v_fma_f32 v59, -v76, v40, v59
	v_fma_f32 v59, -v77, v41, v59
	v_fma_f32 v59, -v78, v42, v59
	v_fma_f32 v59, -v79, v43, v59
	ds_read_b128 v[76:79], v64 offset:16608
	s_waitcnt lgkmcnt(11)
	v_fma_f32 v60, -v80, v40, v60
	v_fma_f32 v60, -v81, v41, v60
	v_fma_f32 v60, -v82, v42, v60
	v_fma_f32 v60, -v83, v43, v60
	ds_read_b128 v[80:83], v64 offset:16880
	s_waitcnt lgkmcnt(11)
	v_fma_f32 v59, -v84, v44, v59
	v_fma_f32 v59, -v85, v45, v59
	v_fma_f32 v59, -v86, v46, v59
	v_fma_f32 v59, -v87, v47, v59
	ds_read_b128 v[84:87], v64 offset:16624
	s_waitcnt lgkmcnt(11)
	v_fma_f32 v60, -v88, v44, v60
	v_fma_f32 v60, -v89, v45, v60
	v_fma_f32 v60, -v90, v46, v60
	v_fma_f32 v60, -v91, v47, v60
	ds_read_b128 v[88:91], v64 offset:16896
	s_waitcnt lgkmcnt(11)
	v_fma_f32 v59, -v92, v48, v59
	v_fma_f32 v59, -v93, v49, v59
	v_fma_f32 v59, -v94, v50, v59
	v_fma_f32 v59, -v95, v51, v59
	ds_read_b128 v[92:95], v64 offset:16640
	s_waitcnt lgkmcnt(11)
	v_fma_f32 v60, -v96, v48, v60
	v_fma_f32 v60, -v97, v49, v60
	v_fma_f32 v60, -v98, v50, v60
	v_fma_f32 v60, -v99, v51, v60
	ds_read_b128 v[96:99], v64 offset:16912
	s_waitcnt lgkmcnt(11)
	v_fma_f32 v59, -v100, v52, v59
	v_fma_f32 v59, -v101, v53, v59
	v_fma_f32 v59, -v102, v54, v59
	v_fma_f32 v59, -v103, v55, v59
	ds_read_b128 v[100:103], v64 offset:16656
	s_waitcnt lgkmcnt(11)
	v_fma_f32 v60, -v104, v52, v60
	v_fma_f32 v60, -v105, v53, v60
	v_fma_f32 v60, -v106, v54, v60
	v_fma_f32 v60, -v107, v55, v60
	ds_read_b128 v[104:107], v64 offset:16928
	s_waitcnt lgkmcnt(11)
	v_fma_f32 v59, -v108, v56, v59
	v_fma_f32 v59, -v109, v57, v59
	v_fma_f32 v59, -v110, v58, v59
	ds_read_b128 v[108:111], v64 offset:16672
	s_waitcnt lgkmcnt(11)
	v_fma_f32 v60, -v112, v56, v60
	v_fma_f32 v60, -v113, v57, v60
	v_fma_f32 v60, -v114, v58, v60
	v_fma_f32 v60, -v115, v59, v60
	ds_read_b128 v[112:115], v64 offset:16944
	s_waitcnt lgkmcnt(11)
	v_fma_f32 v61, -v68, v153, v216
	v_fma_f32 v61, -v69, v1, v61
	v_fma_f32 v61, -v70, v2, v61
	v_fma_f32 v61, -v71, v3, v61
	ds_read_b128 v[68:71], v64 offset:16688
	s_waitcnt lgkmcnt(11)
	v_fma_f32 v62, -v72, v153, v217
	v_fma_f32 v62, -v73, v1, v62
	v_fma_f32 v62, -v74, v2, v62
	v_fma_f32 v62, -v75, v3, v62
	ds_read_b128 v[72:75], v64 offset:16960
	s_waitcnt lgkmcnt(11)
	v_fma_f32 v61, -v76, v4, v61
	v_fma_f32 v61, -v77, v5, v61
	v_fma_f32 v61, -v78, v6, v61
	v_fma_f32 v61, -v79, v7, v61
	ds_read_b128 v[76:79], v64 offset:16704
	s_waitcnt lgkmcnt(11)
	v_fma_f32 v62, -v80, v4, v62
	v_fma_f32 v62, -v81, v5, v62
	v_fma_f32 v62, -v82, v6, v62
	v_fma_f32 v62, -v83, v7, v62
	ds_read_b128 v[80:83], v64 offset:16976
	s_waitcnt lgkmcnt(11)
	v_fma_f32 v61, -v84, v8, v61
	v_fma_f32 v61, -v85, v9, v61
	v_fma_f32 v61, -v86, v10, v61
	v_fma_f32 v61, -v87, v11, v61
	ds_read_b128 v[84:87], v64 offset:16720
	s_waitcnt lgkmcnt(11)
	v_fma_f32 v62, -v88, v8, v62
	v_fma_f32 v62, -v89, v9, v62
	v_fma_f32 v62, -v90, v10, v62
	v_fma_f32 v62, -v91, v11, v62
	ds_read_b128 v[88:91], v64 offset:16992
	s_waitcnt lgkmcnt(11)
	v_fma_f32 v61, -v92, v12, v61
	v_fma_f32 v61, -v93, v13, v61
	v_fma_f32 v61, -v94, v14, v61
	v_fma_f32 v61, -v95, v15, v61
	ds_read_b128 v[92:95], v64 offset:16736
	s_waitcnt lgkmcnt(11)
	v_fma_f32 v62, -v96, v12, v62
	v_fma_f32 v62, -v97, v13, v62
	v_fma_f32 v62, -v98, v14, v62
	v_fma_f32 v62, -v99, v15, v62
	ds_read_b128 v[96:99], v64 offset:17008
	s_waitcnt lgkmcnt(11)
	v_fma_f32 v61, -v100, v16, v61
	v_fma_f32 v61, -v101, v17, v61
	v_fma_f32 v61, -v102, v18, v61
	v_fma_f32 v61, -v103, v19, v61
	ds_read_b128 v[100:103], v64 offset:16752
	s_waitcnt lgkmcnt(11)
	v_fma_f32 v62, -v104, v16, v62
	v_fma_f32 v62, -v105, v17, v62
	v_fma_f32 v62, -v106, v18, v62
	v_fma_f32 v62, -v107, v19, v62
	ds_read_b128 v[104:107], v64 offset:17024
	s_waitcnt lgkmcnt(11)
	v_fma_f32 v61, -v108, v20, v61
	v_fma_f32 v61, -v109, v21, v61
	v_fma_f32 v61, -v110, v22, v61
	v_fma_f32 v61, -v111, v23, v61
	ds_read_b128 v[108:111], v64 offset:16768
	s_waitcnt lgkmcnt(11)
	v_fma_f32 v62, -v112, v20, v62
	v_fma_f32 v62, -v113, v21, v62
	v_fma_f32 v62, -v114, v22, v62
	v_fma_f32 v62, -v115, v23, v62
	ds_read_b128 v[112:115], v64 offset:17040
	s_waitcnt lgkmcnt(11)
	v_fma_f32 v61, -v68, v24, v61
	v_fma_f32 v61, -v69, v25, v61
	v_fma_f32 v61, -v70, v26, v61
	v_fma_f32 v61, -v71, v27, v61
	ds_read_b128 v[68:71], v64 offset:16784
	s_waitcnt lgkmcnt(11)
	v_fma_f32 v62, -v72, v24, v62
	v_fma_f32 v62, -v73, v25, v62
	v_fma_f32 v62, -v74, v26, v62
	v_fma_f32 v62, -v75, v27, v62
	ds_read_b128 v[72:75], v64 offset:17056
	s_waitcnt lgkmcnt(11)
	v_fma_f32 v61, -v76, v28, v61
	v_fma_f32 v61, -v77, v29, v61
	v_fma_f32 v61, -v78, v30, v61
	v_fma_f32 v61, -v79, v31, v61
	ds_read_b128 v[76:79], v64 offset:16800
	s_waitcnt lgkmcnt(11)
	v_fma_f32 v62, -v80, v28, v62
	v_fma_f32 v62, -v81, v29, v62
	v_fma_f32 v62, -v82, v30, v62
	v_fma_f32 v62, -v83, v31, v62
	ds_read_b128 v[80:83], v64 offset:17072
	s_waitcnt lgkmcnt(11)
	v_fma_f32 v61, -v84, v32, v61
	v_fma_f32 v61, -v85, v33, v61
	v_fma_f32 v61, -v86, v34, v61
	v_fma_f32 v61, -v87, v35, v61
	ds_read_b128 v[84:87], v64 offset:16816
	s_waitcnt lgkmcnt(11)
	v_fma_f32 v62, -v88, v32, v62
	v_fma_f32 v62, -v89, v33, v62
	v_fma_f32 v62, -v90, v34, v62
	v_fma_f32 v62, -v91, v35, v62
	ds_read_b128 v[88:91], v64 offset:17088
	s_waitcnt lgkmcnt(11)
	v_fma_f32 v61, -v92, v36, v61
	v_fma_f32 v61, -v93, v37, v61
	v_fma_f32 v61, -v94, v38, v61
	v_fma_f32 v61, -v95, v39, v61
	ds_read_b128 v[92:95], v64 offset:16832
	s_waitcnt lgkmcnt(11)
	v_fma_f32 v62, -v96, v36, v62
	v_fma_f32 v62, -v97, v37, v62
	v_fma_f32 v62, -v98, v38, v62
	v_fma_f32 v62, -v99, v39, v62
	ds_read_b128 v[96:99], v64 offset:17104
	s_waitcnt lgkmcnt(11)
	v_fma_f32 v61, -v100, v40, v61
	v_fma_f32 v61, -v101, v41, v61
	v_fma_f32 v61, -v102, v42, v61
	v_fma_f32 v61, -v103, v43, v61
	ds_read_b128 v[100:103], v64 offset:17136
	s_waitcnt lgkmcnt(11)
	v_fma_f32 v62, -v104, v40, v62
	v_fma_f32 v62, -v105, v41, v62
	v_fma_f32 v62, -v106, v42, v62
	v_fma_f32 v62, -v107, v43, v62
	ds_read_b128 v[104:107], v64 offset:17152
	s_waitcnt lgkmcnt(11)
	v_fma_f32 v61, -v108, v44, v61
	v_fma_f32 v61, -v109, v45, v61
	v_fma_f32 v61, -v110, v46, v61
	v_fma_f32 v61, -v111, v47, v61
	ds_read_b128 v[108:111], v64 offset:17168
	s_waitcnt lgkmcnt(11)
	v_fma_f32 v62, -v112, v44, v62
	v_fma_f32 v62, -v113, v45, v62
	v_fma_f32 v62, -v114, v46, v62
	v_fma_f32 v62, -v115, v47, v62
	ds_read_b128 v[112:115], v64 offset:17184
	s_waitcnt lgkmcnt(11)
	v_fma_f32 v61, -v68, v48, v61
	v_fma_f32 v61, -v69, v49, v61
	v_fma_f32 v61, -v70, v50, v61
	v_fma_f32 v61, -v71, v51, v61
	ds_read_b128 v[68:71], v64 offset:17200
	s_waitcnt lgkmcnt(11)
	v_fma_f32 v62, -v72, v48, v62
	v_fma_f32 v62, -v73, v49, v62
	v_fma_f32 v62, -v74, v50, v62
	v_fma_f32 v62, -v75, v51, v62
	ds_read_b128 v[72:75], v64 offset:17216
	s_waitcnt lgkmcnt(11)
	v_fma_f32 v61, -v76, v52, v61
	v_fma_f32 v61, -v77, v53, v61
	v_fma_f32 v61, -v78, v54, v61
	v_fma_f32 v61, -v79, v55, v61
	ds_read_b128 v[76:79], v64 offset:17232
	s_waitcnt lgkmcnt(11)
	v_fma_f32 v62, -v80, v52, v62
	v_fma_f32 v62, -v81, v53, v62
	v_fma_f32 v62, -v82, v54, v62
	v_fma_f32 v62, -v83, v55, v62
	ds_read_b128 v[80:83], v64 offset:17248
	s_waitcnt lgkmcnt(11)
	v_fma_f32 v61, -v84, v56, v61
	v_fma_f32 v61, -v85, v57, v61
	v_fma_f32 v61, -v86, v58, v61
	v_fma_f32 v61, -v87, v59, v61
	ds_read_b128 v[84:87], v64 offset:17264
	s_waitcnt lgkmcnt(11)
	v_fma_f32 v62, -v88, v56, v62
	v_fma_f32 v62, -v89, v57, v62
	v_fma_f32 v62, -v90, v58, v62
	v_fma_f32 v62, -v91, v59, v62
	ds_read_b128 v[88:91], v64 offset:17280
	s_waitcnt lgkmcnt(11)
	v_fma_f32 v61, -v92, v60, v61
	ds_read_b128 v[92:95], v64 offset:17296
	s_waitcnt lgkmcnt(11)
	v_fma_f32 v62, -v96, v60, v62
	v_fma_f32 v62, -v97, v61, v62
	ds_read_b128 v[96:99], v64 offset:17312
	s_waitcnt lgkmcnt(11)
	v_fma_f32 v63, -v100, v153, v218
	v_fma_f32 v63, -v101, v1, v63
	v_fma_f32 v63, -v102, v2, v63
	v_fma_f32 v63, -v103, v3, v63
	ds_read_b128 v[100:103], v64 offset:17328
	s_waitcnt lgkmcnt(11)
	v_fma_f32 v63, -v104, v4, v63
	v_fma_f32 v63, -v105, v5, v63
	v_fma_f32 v63, -v106, v6, v63
	v_fma_f32 v63, -v107, v7, v63
	ds_read_b128 v[104:107], v64 offset:17344
	s_waitcnt lgkmcnt(11)
	v_fma_f32 v63, -v108, v8, v63
	v_fma_f32 v63, -v109, v9, v63
	v_fma_f32 v63, -v110, v10, v63
	v_fma_f32 v63, -v111, v11, v63
	ds_read_b128 v[108:111], v64 offset:17360
	s_waitcnt lgkmcnt(11)
	v_fma_f32 v63, -v112, v12, v63
	v_fma_f32 v63, -v113, v13, v63
	v_fma_f32 v63, -v114, v14, v63
	v_fma_f32 v63, -v115, v15, v63
	ds_read_b128 v[112:115], v64 offset:17376
	s_waitcnt lgkmcnt(11)
	v_fma_f32 v63, -v68, v16, v63
	v_fma_f32 v63, -v69, v17, v63
	v_fma_f32 v63, -v70, v18, v63
	v_fma_f32 v63, -v71, v19, v63
	s_waitcnt lgkmcnt(10)
	v_fma_f32 v63, -v72, v20, v63
	v_fma_f32 v63, -v73, v21, v63
	v_fma_f32 v63, -v74, v22, v63
	v_fma_f32 v63, -v75, v23, v63
	s_waitcnt lgkmcnt(9)
	v_fma_f32 v63, -v76, v24, v63
	v_fma_f32 v63, -v77, v25, v63
	v_fma_f32 v63, -v78, v26, v63
	v_fma_f32 v63, -v79, v27, v63
	s_waitcnt lgkmcnt(8)
	v_fma_f32 v63, -v80, v28, v63
	v_fma_f32 v63, -v81, v29, v63
	v_fma_f32 v63, -v82, v30, v63
	v_fma_f32 v63, -v83, v31, v63
	s_waitcnt lgkmcnt(7)
	v_fma_f32 v63, -v84, v32, v63
	v_fma_f32 v63, -v85, v33, v63
	v_fma_f32 v63, -v86, v34, v63
	v_fma_f32 v63, -v87, v35, v63
	s_waitcnt lgkmcnt(6)
	v_fma_f32 v63, -v88, v36, v63
	v_fma_f32 v63, -v89, v37, v63
	v_fma_f32 v63, -v90, v38, v63
	v_fma_f32 v63, -v91, v39, v63
	s_waitcnt lgkmcnt(5)
	v_fma_f32 v63, -v92, v40, v63
	v_fma_f32 v63, -v93, v41, v63
	v_fma_f32 v63, -v94, v42, v63
	v_fma_f32 v63, -v95, v43, v63
	s_waitcnt lgkmcnt(4)
	v_fma_f32 v63, -v96, v44, v63
	v_fma_f32 v63, -v97, v45, v63
	v_fma_f32 v63, -v98, v46, v63
	v_fma_f32 v63, -v99, v47, v63
	s_waitcnt lgkmcnt(3)
	v_fma_f32 v63, -v100, v48, v63
	v_fma_f32 v63, -v101, v49, v63
	v_fma_f32 v63, -v102, v50, v63
	v_fma_f32 v63, -v103, v51, v63
	s_waitcnt lgkmcnt(2)
	v_fma_f32 v63, -v104, v52, v63
	v_fma_f32 v63, -v105, v53, v63
	v_fma_f32 v63, -v106, v54, v63
	v_fma_f32 v63, -v107, v55, v63
	s_waitcnt lgkmcnt(1)
	v_fma_f32 v63, -v108, v56, v63
	v_fma_f32 v63, -v109, v57, v63
	v_fma_f32 v63, -v110, v58, v63
	v_fma_f32 v63, -v111, v59, v63
	s_waitcnt lgkmcnt(0)
	v_fma_f32 v63, -v112, v60, v63
	v_fma_f32 v63, -v113, v61, v63
	v_fma_f32 v63, -v114, v62, v63
	ds_write_b16 v150, v219
	v_cvt_pk_bf16_f32 v0, v1, s0
	ds_write_b16 v150, v0 offset:128
	v_cvt_pk_bf16_f32 v0, v2, s0
	ds_write_b16 v150, v0 offset:256
	v_cvt_pk_bf16_f32 v0, v3, s0
	ds_write_b16 v150, v0 offset:384
	v_cvt_pk_bf16_f32 v0, v4, s0
	ds_write_b16 v150, v0 offset:512
	v_cvt_pk_bf16_f32 v0, v5, s0
	ds_write_b16 v150, v0 offset:640
	v_cvt_pk_bf16_f32 v0, v6, s0
	ds_write_b16 v150, v0 offset:768
	v_cvt_pk_bf16_f32 v0, v7, s0
	ds_write_b16 v150, v0 offset:896
	v_cvt_pk_bf16_f32 v0, v8, s0
	ds_write_b16 v150, v0 offset:1024
	v_cvt_pk_bf16_f32 v0, v9, s0
	ds_write_b16 v150, v0 offset:1152
	v_cvt_pk_bf16_f32 v0, v10, s0
	ds_write_b16 v150, v0 offset:1280
	v_cvt_pk_bf16_f32 v0, v11, s0
	ds_write_b16 v150, v0 offset:1408
	v_cvt_pk_bf16_f32 v0, v12, s0
	ds_write_b16 v150, v0 offset:1536
	v_cvt_pk_bf16_f32 v0, v13, s0
	ds_write_b16 v150, v0 offset:1664
	v_cvt_pk_bf16_f32 v0, v14, s0
	ds_write_b16 v150, v0 offset:1792
	v_cvt_pk_bf16_f32 v0, v15, s0
	ds_write_b16 v150, v0 offset:1920
	v_cvt_pk_bf16_f32 v0, v16, s0
	ds_write_b16 v150, v0 offset:2048
	v_cvt_pk_bf16_f32 v0, v17, s0
	ds_write_b16 v150, v0 offset:2176
	v_cvt_pk_bf16_f32 v0, v18, s0
	ds_write_b16 v150, v0 offset:2304
	v_cvt_pk_bf16_f32 v0, v19, s0
	ds_write_b16 v150, v0 offset:2432
	v_cvt_pk_bf16_f32 v0, v20, s0
	ds_write_b16 v150, v0 offset:2560
	v_cvt_pk_bf16_f32 v0, v21, s0
	ds_write_b16 v150, v0 offset:2688
	v_cvt_pk_bf16_f32 v0, v22, s0
	ds_write_b16 v150, v0 offset:2816
	v_cvt_pk_bf16_f32 v0, v23, s0
	ds_write_b16 v150, v0 offset:2944
	v_cvt_pk_bf16_f32 v0, v24, s0
	ds_write_b16 v150, v0 offset:3072
	v_cvt_pk_bf16_f32 v0, v25, s0
	ds_write_b16 v150, v0 offset:3200
	v_cvt_pk_bf16_f32 v0, v26, s0
	ds_write_b16 v150, v0 offset:3328
	v_cvt_pk_bf16_f32 v0, v27, s0
	ds_write_b16 v150, v0 offset:3456
	v_cvt_pk_bf16_f32 v0, v28, s0
	ds_write_b16 v150, v0 offset:3584
	v_cvt_pk_bf16_f32 v0, v29, s0
	ds_write_b16 v150, v0 offset:3712
	v_cvt_pk_bf16_f32 v0, v30, s0
	ds_write_b16 v150, v0 offset:3840
	v_cvt_pk_bf16_f32 v0, v31, s0
	ds_write_b16 v150, v0 offset:3968
	v_cvt_pk_bf16_f32 v0, v32, s0
	ds_write_b16 v150, v0 offset:4096
	v_cvt_pk_bf16_f32 v0, v33, s0
	ds_write_b16 v150, v0 offset:4224
	v_cvt_pk_bf16_f32 v0, v34, s0
	ds_write_b16 v150, v0 offset:4352
	v_cvt_pk_bf16_f32 v0, v35, s0
	ds_write_b16 v150, v0 offset:4480
	v_cvt_pk_bf16_f32 v0, v36, s0
	ds_write_b16 v150, v0 offset:4608
	v_cvt_pk_bf16_f32 v0, v37, s0
	ds_write_b16 v150, v0 offset:4736
	v_cvt_pk_bf16_f32 v0, v38, s0
	ds_write_b16 v150, v0 offset:4864
	v_cvt_pk_bf16_f32 v0, v39, s0
	ds_write_b16 v150, v0 offset:4992
	v_cvt_pk_bf16_f32 v0, v40, s0
	ds_write_b16 v150, v0 offset:5120
	v_cvt_pk_bf16_f32 v0, v41, s0
	ds_write_b16 v150, v0 offset:5248
	v_cvt_pk_bf16_f32 v0, v42, s0
	ds_write_b16 v150, v0 offset:5376
	v_cvt_pk_bf16_f32 v0, v43, s0
	ds_write_b16 v150, v0 offset:5504
	v_cvt_pk_bf16_f32 v0, v44, s0
	ds_write_b16 v150, v0 offset:5632
	v_cvt_pk_bf16_f32 v0, v45, s0
	ds_write_b16 v150, v0 offset:5760
	v_cvt_pk_bf16_f32 v0, v46, s0
	ds_write_b16 v150, v0 offset:5888
	v_cvt_pk_bf16_f32 v0, v47, s0
	ds_write_b16 v150, v0 offset:6016
	v_cvt_pk_bf16_f32 v0, v48, s0
	ds_write_b16 v150, v0 offset:6144
	v_cvt_pk_bf16_f32 v0, v49, s0
	ds_write_b16 v150, v0 offset:6272
	v_cvt_pk_bf16_f32 v0, v50, s0
	ds_write_b16 v150, v0 offset:6400
	v_cvt_pk_bf16_f32 v0, v51, s0
	ds_write_b16 v150, v0 offset:6528
	v_cvt_pk_bf16_f32 v0, v52, s0
	ds_write_b16 v150, v0 offset:6656
	v_cvt_pk_bf16_f32 v0, v53, s0
	ds_write_b16 v150, v0 offset:6784
	v_cvt_pk_bf16_f32 v0, v54, s0
	ds_write_b16 v150, v0 offset:6912
	v_cvt_pk_bf16_f32 v0, v55, s0
	ds_write_b16 v150, v0 offset:7040
	v_cvt_pk_bf16_f32 v0, v56, s0
	ds_write_b16 v150, v0 offset:7168
	v_cvt_pk_bf16_f32 v0, v57, s0
	ds_write_b16 v150, v0 offset:7296
	v_cvt_pk_bf16_f32 v0, v58, s0
	ds_write_b16 v150, v0 offset:7424
	v_cvt_pk_bf16_f32 v0, v59, s0
	ds_write_b16 v150, v0 offset:7552
	v_cvt_pk_bf16_f32 v0, v60, s0
	ds_write_b16 v150, v0 offset:7680
	v_cvt_pk_bf16_f32 v0, v61, s0
	ds_write_b16 v150, v0 offset:7808
	v_cvt_pk_bf16_f32 v0, v62, s0
	ds_write_b16 v150, v0 offset:7936
	v_cvt_pk_bf16_f32 v0, v63, s0
	ds_write_b16 v150, v0 offset:8064
	v_lshl_add_u64 v[0:1], v[126:127], 0, s[0:1]
.LBB0_645:
	v_add_u32_e32 v8, s3, v221
	ds_read_b128 v[2:5], v8
	v_add_co_u32_e32 v6, vcc, 0xffff5000, v0
	s_addk_i32 s3, 0x800
	s_nop 0
	v_addc_co_u32_e32 v7, vcc, -1, v1, vcc
	s_waitcnt lgkmcnt(0)
	global_store_dwordx4 v[6:7], v[2:5], off
	ds_read_b128 v[2:5], v8 offset:1024
	s_cmpk_lg_i32 s3, 0x2000
	s_waitcnt lgkmcnt(0)
	global_store_dwordx4 v[0:1], v[2:5], off
	v_lshl_add_u64 v[0:1], v[0:1], 0, s[72:73]
	s_cbranch_scc1 .LBB0_645
	s_waitcnt lgkmcnt(0)
	v_mov_b32_e32 v0, s63
	ds_read_b32 v52, v0 offset:17660
	s_lshl_b32 s3, s13, 14
	s_lshl_b64 s[6:7], s[78:79], 19
	s_or_b32 s6, s6, s3
	v_lshl_add_u64 v[40:41], v[128:129], 0, s[6:7]
	v_lshl_add_u64 v[42:43], v[130:131], 0, s[6:7]
	v_lshl_add_u64 v[44:45], v[132:133], 0, s[6:7]
	s_mov_b64 s[78:79], 0
	s_mov_b32 s3, 0
	v_mov_b32_e32 v53, v223
	v_mov_b32_e32 v54, v222
	s_mov_b32 s6, 0

.LBB0_982:
	s_cmp_lt_i32 s38, 3
	s_cbranch_scc1 .LBB0_1008
	s_cmp_lt_i32 s38, 4
	s_cbranch_scc1 .LBB0_989
	s_cmp_lg_u32 s38, 4
	s_cbranch_scc0 .LBB0_986
	v_readlane_b32 s82, v254, 6
	v_readlane_b32 s83, v254, 7
	v_add_u32_e32 v148, s10, v155
	v_lshl_or_b32 v146, s44, 8, v157
	v_ashrrev_i32_e32 v149, 31, v148
	v_ashrrev_i32_e32 v147, 31, v146
	v_lshlrev_b64 v[144:145], 10, v[148:149]
	v_lshl_add_u64 v[144:145], v[144:145], 0, v[146:147]
	v_readlane_b32 s76, v254, 0
	v_readlane_b32 s77, v254, 1
	v_readlane_b32 s78, v254, 2
	v_readlane_b32 s79, v254, 3
	v_readlane_b32 s80, v254, 4
	v_readlane_b32 s81, v254, 5
	v_lshl_add_u64 v[146:147], v[144:145], 1, s[96:97]
	v_lshl_add_u64 v[148:149], v[144:145], 2, s[82:83]
	global_load_dwordx2 v[160:161], v[146:147], off
	global_load_dwordx2 v[162:163], v[146:147], off offset:32
	global_load_dwordx2 v[164:165], v[146:147], off offset:256
	global_load_dwordx2 v[166:167], v[146:147], off offset:288
	s_mov_b64 s[8:9], 0x8000
	v_lshl_add_u64 v[150:151], v[146:147], 0, s[8:9]
	global_load_dwordx2 v[168:169], v[150:151], off
	global_load_dwordx2 v[170:171], v[150:151], off offset:32
	global_load_dwordx2 v[172:173], v[150:151], off offset:256
	global_load_dwordx2 v[174:175], v[150:151], off offset:288
	s_mov_b64 s[8:9], 0x10000
	v_lshl_add_u64 v[150:151], v[146:147], 0, s[8:9]
	global_load_dwordx2 v[176:177], v[150:151], off
	global_load_dwordx2 v[178:179], v[150:151], off offset:32
	global_load_dwordx2 v[180:181], v[150:151], off offset:256
	global_load_dwordx2 v[182:183], v[150:151], off offset:288
	s_mov_b64 s[8:9], 0x18000
	v_lshl_add_u64 v[150:151], v[146:147], 0, s[8:9]
	global_load_dwordx2 v[184:185], v[150:151], off
	global_load_dwordx2 v[186:187], v[150:151], off offset:32
	global_load_dwordx2 v[188:189], v[150:151], off offset:256
	global_load_dwordx2 v[190:191], v[150:151], off offset:288
	s_waitcnt vmcnt(15)
	v_lshlrev_b32_e32 v202, 16, v160
	v_and_b32_e32 v203, 0xffff0000, v160
	v_lshlrev_b32_e32 v204, 16, v161
	v_and_b32_e32 v205, 0xffff0000, v161
	v_pk_add_f32 v[194:195], v[128:129], v[204:205]
	v_pk_add_f32 v[192:193], v[126:127], v[202:203]
	global_store_dwordx4 v[148:149], v[192:195], off
	s_waitcnt vmcnt(15)
	v_lshlrev_b32_e32 v206, 16, v162
	v_and_b32_e32 v207, 0xffff0000, v162
	v_lshlrev_b32_e32 v208, 16, v163
	v_and_b32_e32 v209, 0xffff0000, v163
	v_pk_add_f32 v[198:199], v[124:125], v[208:209]
	v_pk_add_f32 v[196:197], v[122:123], v[206:207]
	global_store_dwordx4 v[148:149], v[196:199], off offset:64
	s_waitcnt vmcnt(15)
	v_lshlrev_b32_e32 v202, 16, v164
	v_and_b32_e32 v203, 0xffff0000, v164
	v_lshlrev_b32_e32 v204, 16, v165
	v_and_b32_e32 v205, 0xffff0000, v165
	v_pk_add_f32 v[194:195], v[120:121], v[204:205]
	v_pk_add_f32 v[192:193], v[118:119], v[202:203]
	global_store_dwordx4 v[148:149], v[192:195], off offset:512
	s_waitcnt vmcnt(15)
	v_lshlrev_b32_e32 v206, 16, v166
	v_and_b32_e32 v207, 0xffff0000, v166
	v_lshlrev_b32_e32 v208, 16, v167
	v_and_b32_e32 v209, 0xffff0000, v167
	v_pk_add_f32 v[198:199], v[116:117], v[208:209]
	v_pk_add_f32 v[196:197], v[114:115], v[206:207]
	global_store_dwordx4 v[148:149], v[196:199], off offset:576
	s_mov_b64 s[8:9], 0x10000
	v_lshl_add_u64 v[150:151], v[148:149], 0, s[8:9]
	s_waitcnt vmcnt(15)
	v_lshlrev_b32_e32 v202, 16, v168
	v_and_b32_e32 v203, 0xffff0000, v168
	v_lshlrev_b32_e32 v204, 16, v169
	v_and_b32_e32 v205, 0xffff0000, v169
	v_pk_add_f32 v[194:195], v[112:113], v[204:205]
	v_pk_add_f32 v[192:193], v[110:111], v[202:203]
	global_store_dwordx4 v[150:151], v[192:195], off
	s_waitcnt vmcnt(15)
	v_lshlrev_b32_e32 v206, 16, v170
	v_and_b32_e32 v207, 0xffff0000, v170
	v_lshlrev_b32_e32 v208, 16, v171
	v_and_b32_e32 v209, 0xffff0000, v171
	v_pk_add_f32 v[198:199], v[108:109], v[208:209]
	v_pk_add_f32 v[196:197], v[106:107], v[206:207]
	global_store_dwordx4 v[150:151], v[196:199], off offset:64
	s_waitcnt vmcnt(15)
	v_lshlrev_b32_e32 v202, 16, v172
	v_and_b32_e32 v203, 0xffff0000, v172
	v_lshlrev_b32_e32 v204, 16, v173
	v_and_b32_e32 v205, 0xffff0000, v173
	v_pk_add_f32 v[194:195], v[104:105], v[204:205]
	v_pk_add_f32 v[192:193], v[102:103], v[202:203]
	global_store_dwordx4 v[150:151], v[192:195], off offset:512
	s_waitcnt vmcnt(15)
	v_lshlrev_b32_e32 v206, 16, v174
	v_and_b32_e32 v207, 0xffff0000, v174
	v_lshlrev_b32_e32 v208, 16, v175
	v_and_b32_e32 v209, 0xffff0000, v175
	v_pk_add_f32 v[198:199], v[100:101], v[208:209]
	v_pk_add_f32 v[196:197], v[98:99], v[206:207]
	global_store_dwordx4 v[150:151], v[196:199], off offset:576
	s_mov_b64 s[8:9], 0x20000
	v_lshl_add_u64 v[150:151], v[148:149], 0, s[8:9]
	s_waitcnt vmcnt(15)
	v_lshlrev_b32_e32 v202, 16, v176
	v_and_b32_e32 v203, 0xffff0000, v176
	v_lshlrev_b32_e32 v204, 16, v177
	v_and_b32_e32 v205, 0xffff0000, v177
	v_pk_add_f32 v[194:195], v[96:97], v[204:205]
	v_pk_add_f32 v[192:193], v[94:95], v[202:203]
	global_store_dwordx4 v[150:151], v[192:195], off
	s_waitcnt vmcnt(15)
	v_lshlrev_b32_e32 v206, 16, v178
	v_and_b32_e32 v207, 0xffff0000, v178
	v_lshlrev_b32_e32 v208, 16, v179
	v_and_b32_e32 v209, 0xffff0000, v179
	v_pk_add_f32 v[198:199], v[92:93], v[208:209]
	v_pk_add_f32 v[196:197], v[90:91], v[206:207]
	global_store_dwordx4 v[150:151], v[196:199], off offset:64
	s_waitcnt vmcnt(15)
	v_lshlrev_b32_e32 v202, 16, v180
	v_and_b32_e32 v203, 0xffff0000, v180
	v_lshlrev_b32_e32 v204, 16, v181
	v_and_b32_e32 v205, 0xffff0000, v181
	v_pk_add_f32 v[194:195], v[88:89], v[204:205]
	v_pk_add_f32 v[192:193], v[86:87], v[202:203]
	global_store_dwordx4 v[150:151], v[192:195], off offset:512
	s_waitcnt vmcnt(15)
	v_lshlrev_b32_e32 v206, 16, v182
	v_and_b32_e32 v207, 0xffff0000, v182
	v_lshlrev_b32_e32 v208, 16, v183
	v_and_b32_e32 v209, 0xffff0000, v183
	v_pk_add_f32 v[198:199], v[84:85], v[208:209]
	v_pk_add_f32 v[196:197], v[82:83], v[206:207]
	global_store_dwordx4 v[150:151], v[196:199], off offset:576
	s_mov_b64 s[8:9], 0x30000
	v_lshl_add_u64 v[150:151], v[148:149], 0, s[8:9]
	s_waitcnt vmcnt(15)
	v_lshlrev_b32_e32 v202, 16, v184
	v_and_b32_e32 v203, 0xffff0000, v184
	v_lshlrev_b32_e32 v204, 16, v185
	v_and_b32_e32 v205, 0xffff0000, v185
	v_pk_add_f32 v[194:195], v[80:81], v[204:205]
	v_pk_add_f32 v[192:193], v[78:79], v[202:203]
	global_store_dwordx4 v[150:151], v[192:195], off
	s_waitcnt vmcnt(15)
	v_lshlrev_b32_e32 v206, 16, v186
	v_and_b32_e32 v207, 0xffff0000, v186
	v_lshlrev_b32_e32 v208, 16, v187
	v_and_b32_e32 v209, 0xffff0000, v187
	v_pk_add_f32 v[198:199], v[76:77], v[208:209]
	v_pk_add_f32 v[196:197], v[74:75], v[206:207]
	global_store_dwordx4 v[150:151], v[196:199], off offset:64
	s_waitcnt vmcnt(15)
	v_lshlrev_b32_e32 v202, 16, v188
	v_and_b32_e32 v203, 0xffff0000, v188
	v_lshlrev_b32_e32 v204, 16, v189
	v_and_b32_e32 v205, 0xffff0000, v189
	v_pk_add_f32 v[194:195], v[72:73], v[204:205]
	v_pk_add_f32 v[192:193], v[70:71], v[202:203]
	global_store_dwordx4 v[150:151], v[192:195], off offset:512
	s_waitcnt vmcnt(15)
	v_lshlrev_b32_e32 v206, 16, v190
	v_and_b32_e32 v207, 0xffff0000, v190
	v_lshlrev_b32_e32 v208, 16, v191
	v_and_b32_e32 v209, 0xffff0000, v191
	v_pk_add_f32 v[198:199], v[68:69], v[208:209]
	v_pk_add_f32 v[196:197], v[66:67], v[206:207]
	global_store_dwordx4 v[150:151], v[196:199], off offset:576
	s_mov_b64 s[8:9], 0x40000
	v_lshl_add_u64 v[150:151], v[146:147], 0, s[8:9]
	global_load_dwordx2 v[160:161], v[150:151], off
	global_load_dwordx2 v[162:163], v[150:151], off offset:32
	global_load_dwordx2 v[164:165], v[150:151], off offset:256
	global_load_dwordx2 v[166:167], v[150:151], off offset:288
	s_mov_b64 s[8:9], 0x48000
	v_lshl_add_u64 v[150:151], v[146:147], 0, s[8:9]
	global_load_dwordx2 v[168:169], v[150:151], off
	global_load_dwordx2 v[170:171], v[150:151], off offset:32
	global_load_dwordx2 v[172:173], v[150:151], off offset:256
	global_load_dwordx2 v[174:175], v[150:151], off offset:288
	s_mov_b64 s[8:9], 0x50000
	v_lshl_add_u64 v[150:151], v[146:147], 0, s[8:9]
	global_load_dwordx2 v[176:177], v[150:151], off
	global_load_dwordx2 v[178:179], v[150:151], off offset:32
	global_load_dwordx2 v[180:181], v[150:151], off offset:256
	global_load_dwordx2 v[182:183], v[150:151], off offset:288
	s_mov_b64 s[8:9], 0x58000
	v_lshl_add_u64 v[150:151], v[146:147], 0, s[8:9]
	global_load_dwordx2 v[184:185], v[150:151], off
	global_load_dwordx2 v[186:187], v[150:151], off offset:32
	global_load_dwordx2 v[188:189], v[150:151], off offset:256
	global_load_dwordx2 v[190:191], v[150:151], off offset:288
	s_mov_b64 s[8:9], 0x80000
	v_lshl_add_u64 v[150:151], v[148:149], 0, s[8:9]
	s_waitcnt vmcnt(15)
	v_lshlrev_b32_e32 v202, 16, v160
	v_and_b32_e32 v203, 0xffff0000, v160
	v_lshlrev_b32_e32 v204, 16, v161
	v_and_b32_e32 v205, 0xffff0000, v161
	v_pk_add_f32 v[194:195], v[64:65], v[204:205]
	v_pk_add_f32 v[192:193], v[62:63], v[202:203]
	global_store_dwordx4 v[150:151], v[192:195], off
	s_waitcnt vmcnt(15)
	v_lshlrev_b32_e32 v206, 16, v162
	v_and_b32_e32 v207, 0xffff0000, v162
	v_lshlrev_b32_e32 v208, 16, v163
	v_and_b32_e32 v209, 0xffff0000, v163
	v_pk_add_f32 v[198:199], v[60:61], v[208:209]
	v_pk_add_f32 v[196:197], v[58:59], v[206:207]
	global_store_dwordx4 v[150:151], v[196:199], off offset:64
	s_waitcnt vmcnt(15)
	v_lshlrev_b32_e32 v202, 16, v164
	v_and_b32_e32 v203, 0xffff0000, v164
	v_lshlrev_b32_e32 v204, 16, v165
	v_and_b32_e32 v205, 0xffff0000, v165
	v_pk_add_f32 v[194:195], v[56:57], v[204:205]
	v_pk_add_f32 v[192:193], v[54:55], v[202:203]
	global_store_dwordx4 v[150:151], v[192:195], off offset:512
	s_waitcnt vmcnt(15)
	v_lshlrev_b32_e32 v206, 16, v166
	v_and_b32_e32 v207, 0xffff0000, v166
	v_lshlrev_b32_e32 v208, 16, v167
	v_and_b32_e32 v209, 0xffff0000, v167
	v_pk_add_f32 v[198:199], v[52:53], v[208:209]
	v_pk_add_f32 v[196:197], v[50:51], v[206:207]
	global_store_dwordx4 v[150:151], v[196:199], off offset:576
	s_mov_b64 s[8:9], 0x90000
	v_lshl_add_u64 v[150:151], v[148:149], 0, s[8:9]
	s_waitcnt vmcnt(15)
	v_lshlrev_b32_e32 v202, 16, v168
	v_and_b32_e32 v203, 0xffff0000, v168
	v_lshlrev_b32_e32 v204, 16, v169
	v_and_b32_e32 v205, 0xffff0000, v169
	v_pk_add_f32 v[194:195], v[48:49], v[204:205]
	v_pk_add_f32 v[192:193], v[46:47], v[202:203]
	global_store_dwordx4 v[150:151], v[192:195], off
	s_waitcnt vmcnt(15)
	v_lshlrev_b32_e32 v206, 16, v170
	v_and_b32_e32 v207, 0xffff0000, v170
	v_lshlrev_b32_e32 v208, 16, v171
	v_and_b32_e32 v209, 0xffff0000, v171
	v_pk_add_f32 v[198:199], v[44:45], v[208:209]
	v_pk_add_f32 v[196:197], v[42:43], v[206:207]
	global_store_dwordx4 v[150:151], v[196:199], off offset:64
	s_waitcnt vmcnt(15)
	v_lshlrev_b32_e32 v202, 16, v172
	v_and_b32_e32 v203, 0xffff0000, v172
	v_lshlrev_b32_e32 v204, 16, v173
	v_and_b32_e32 v205, 0xffff0000, v173
	v_pk_add_f32 v[194:195], v[40:41], v[204:205]
	v_pk_add_f32 v[192:193], v[38:39], v[202:203]
	global_store_dwordx4 v[150:151], v[192:195], off offset:512
	s_waitcnt vmcnt(15)
	v_lshlrev_b32_e32 v206, 16, v174
	v_and_b32_e32 v207, 0xffff0000, v174
	v_lshlrev_b32_e32 v208, 16, v175
	v_and_b32_e32 v209, 0xffff0000, v175
	v_pk_add_f32 v[198:199], v[36:37], v[208:209]
	v_pk_add_f32 v[196:197], v[34:35], v[206:207]
	global_store_dwordx4 v[150:151], v[196:199], off offset:576
	s_mov_b64 s[8:9], 0xa0000
	v_lshl_add_u64 v[150:151], v[148:149], 0, s[8:9]
	s_waitcnt vmcnt(15)
	v_lshlrev_b32_e32 v202, 16, v176
	v_and_b32_e32 v203, 0xffff0000, v176
	v_lshlrev_b32_e32 v204, 16, v177
	v_and_b32_e32 v205, 0xffff0000, v177
	v_pk_add_f32 v[194:195], v[32:33], v[204:205]
	v_pk_add_f32 v[192:193], v[30:31], v[202:203]
	global_store_dwordx4 v[150:151], v[192:195], off
	s_waitcnt vmcnt(15)
	v_lshlrev_b32_e32 v206, 16, v178
	v_and_b32_e32 v207, 0xffff0000, v178
	v_lshlrev_b32_e32 v208, 16, v179
	v_and_b32_e32 v209, 0xffff0000, v179
	v_pk_add_f32 v[198:199], v[28:29], v[208:209]
	v_pk_add_f32 v[196:197], v[26:27], v[206:207]
	global_store_dwordx4 v[150:151], v[196:199], off offset:64
	s_waitcnt vmcnt(15)
	v_lshlrev_b32_e32 v202, 16, v180
	v_and_b32_e32 v203, 0xffff0000, v180
	v_lshlrev_b32_e32 v204, 16, v181
	v_and_b32_e32 v205, 0xffff0000, v181
	v_pk_add_f32 v[194:195], v[24:25], v[204:205]
	v_pk_add_f32 v[192:193], v[22:23], v[202:203]
	global_store_dwordx4 v[150:151], v[192:195], off offset:512
	s_waitcnt vmcnt(15)
	v_lshlrev_b32_e32 v206, 16, v182
	v_and_b32_e32 v207, 0xffff0000, v182
	v_lshlrev_b32_e32 v208, 16, v183
	v_and_b32_e32 v209, 0xffff0000, v183
	v_pk_add_f32 v[198:199], v[20:21], v[208:209]
	v_pk_add_f32 v[196:197], v[18:19], v[206:207]
	global_store_dwordx4 v[150:151], v[196:199], off offset:576
	s_mov_b64 s[8:9], 0xb0000
	v_lshl_add_u64 v[150:151], v[148:149], 0, s[8:9]
	s_waitcnt vmcnt(15)
	v_lshlrev_b32_e32 v202, 16, v184
	v_and_b32_e32 v203, 0xffff0000, v184
	v_lshlrev_b32_e32 v204, 16, v185
	v_and_b32_e32 v205, 0xffff0000, v185
	v_pk_add_f32 v[194:195], v[16:17], v[204:205]
	v_pk_add_f32 v[192:193], v[14:15], v[202:203]
	global_store_dwordx4 v[150:151], v[192:195], off
	s_waitcnt vmcnt(15)
	v_lshlrev_b32_e32 v206, 16, v186
	v_and_b32_e32 v207, 0xffff0000, v186
	v_lshlrev_b32_e32 v208, 16, v187
	v_and_b32_e32 v209, 0xffff0000, v187
	v_pk_add_f32 v[198:199], v[12:13], v[208:209]
	v_pk_add_f32 v[196:197], v[10:11], v[206:207]
	global_store_dwordx4 v[150:151], v[196:199], off offset:64
	s_waitcnt vmcnt(15)
	v_lshlrev_b32_e32 v202, 16, v188
	v_and_b32_e32 v203, 0xffff0000, v188
	v_lshlrev_b32_e32 v204, 16, v189
	v_and_b32_e32 v205, 0xffff0000, v189
	v_pk_add_f32 v[194:195], v[8:9], v[204:205]
	v_pk_add_f32 v[192:193], v[6:7], v[202:203]
	global_store_dwordx4 v[150:151], v[192:195], off offset:512
	s_waitcnt vmcnt(15)
	v_lshlrev_b32_e32 v206, 16, v190
	v_and_b32_e32 v207, 0xffff0000, v190
	v_lshlrev_b32_e32 v208, 16, v191
	v_and_b32_e32 v209, 0xffff0000, v191
	v_pk_add_f32 v[198:199], v[4:5], v[208:209]
	v_pk_add_f32 v[196:197], v[2:3], v[206:207]
	global_store_dwordx4 v[150:151], v[196:199], off offset:576
	s_mov_b64 s[8:9], 0
.LBB0_986:
	s_andn2_b64 vcc, exec, s[8:9]
	s_cbranch_vccnz .LBB0_988
	v_add_u32_e32 v150, s10, v155
	v_readlane_b32 s8, v254, 63
	v_ashrrev_i32_e32 v151, 31, v150
	v_readlane_b32 s9, v255, 0
	v_lshl_or_b32 v144, s44, 8, v138
	v_ashrrev_i32_e32 v145, 31, v144
	v_lshl_add_u64 v[146:147], v[150:151], 2, s[8:9]
	global_load_dword v202, v[146:147], off
	global_load_dword v203, v[146:147], off offset:64
	global_load_dword v204, v[146:147], off offset:128
	global_load_dword v205, v[146:147], off offset:192
	global_load_dword v206, v[146:147], off offset:512
	global_load_dword v207, v[146:147], off offset:576
	global_load_dword v208, v[146:147], off offset:640
	global_load_dword v209, v[146:147], off offset:704
	v_lshl_add_u64 v[148:149], v[144:145], 1, s[74:75]
	v_lshlrev_b64 v[144:145], 13, v[150:151]
	v_lshl_add_u64 v[144:145], v[148:149], 0, v[144:145]
	s_mov_b32 s3, 0x100000
	s_waitcnt vmcnt(0)
	v_fmamk_f32 v0, v202, 0x3a800000, v139
	v_rsq_f32_e32 v0, v0
	s_nop 0
	v_pk_mul_f32 v[160:161], v[128:129], v[0:1] op_sel_hi:[1,0]
	v_pk_mul_f32 v[162:163], v[126:127], v[0:1] op_sel_hi:[1,0]
	v_pk_mul_f32 v[164:165], v[124:125], v[0:1] op_sel_hi:[1,0]
	v_pk_mul_f32 v[166:167], v[122:123], v[0:1] op_sel_hi:[1,0]
	v_max_f32_e32 v160, 0, v160
	v_max_f32_e32 v151, 0, v162
	v_max_f32_e32 v159, 0, v166
	v_max_f32_e32 v162, 0, v163
	v_max_f32_e32 v163, 0, v167
	v_mul_f32_e32 v166, v160, v160
	v_max_f32_e32 v160, 0, v161
	v_max_f32_e32 v161, 0, v165
	v_mul_f32_e32 v151, v151, v151
	v_mul_f32_e32 v162, v162, v162
	v_mul_f32_e32 v163, v163, v163
	v_max_f32_e32 v164, 0, v164
	v_mul_f32_e32 v165, v160, v160
	v_mul_f32_e32 v167, v161, v161
	v_cvt_pk_bf16_f32 v160, v151, v162
	v_cvt_pk_bf16_f32 v161, v166, v165
	v_mul_f32_e32 v159, v159, v159
	v_mul_f32_e32 v164, v164, v164
	v_cvt_pk_bf16_f32 v162, v159, v163
	v_cvt_pk_bf16_f32 v163, v164, v167
	global_store_dwordx4 v[144:145], v[160:163], off
	v_pk_mul_f32 v[164:165], v[116:117], v[0:1] op_sel_hi:[1,0]
	v_pk_mul_f32 v[166:167], v[114:115], v[0:1] op_sel_hi:[1,0]
	v_pk_mul_f32 v[160:161], v[120:121], v[0:1] op_sel_hi:[1,0]
	v_pk_mul_f32 v[162:163], v[118:119], v[0:1] op_sel_hi:[1,0]
	v_max_f32_e32 v160, 0, v160
	v_max_f32_e32 v0, 0, v162
	v_max_f32_e32 v159, 0, v163
	v_max_f32_e32 v162, 0, v167
	v_max_f32_e32 v163, 0, v164
	v_mul_f32_e32 v164, v160, v160
	v_max_f32_e32 v160, 0, v161
	v_max_f32_e32 v151, 0, v166
	v_mul_f32_e32 v0, v0, v0
	v_mul_f32_e32 v159, v159, v159
	v_mul_f32_e32 v162, v162, v162
	v_mul_f32_e32 v163, v163, v163
	v_max_f32_e32 v161, 0, v165
	v_mul_f32_e32 v165, v160, v160
	v_cvt_pk_bf16_f32 v160, v0, v159
	v_mul_f32_e32 v151, v151, v151
	v_mul_f32_e32 v166, v161, v161
	v_cvt_pk_bf16_f32 v161, v164, v165
	v_cvt_pk_bf16_f32 v162, v151, v162
	v_cvt_pk_bf16_f32 v163, v163, v166
	global_store_dwordx4 v[144:145], v[160:163], off offset:256
	s_nop 1
	v_or_b32_e32 v160, 16, v150
	v_ashrrev_i32_e32 v161, 31, v160
	v_lshl_add_u64 v[162:163], v[160:161], 2, s[8:9]
	v_lshlrev_b64 v[160:161], 13, v[160:161]
	v_lshl_add_u64 v[164:165], v[148:149], 0, v[160:161]
	v_fmamk_f32 v0, v203, 0x3a800000, v139
	v_rsq_f32_e32 v0, v0
	s_nop 0
	v_pk_mul_f32 v[160:161], v[112:113], v[0:1] op_sel_hi:[1,0]
	v_pk_mul_f32 v[162:163], v[110:111], v[0:1] op_sel_hi:[1,0]
	v_pk_mul_f32 v[166:167], v[108:109], v[0:1] op_sel_hi:[1,0]
	v_pk_mul_f32 v[168:169], v[106:107], v[0:1] op_sel_hi:[1,0]
	v_max_f32_e32 v160, 0, v160
	v_max_f32_e32 v151, 0, v162
	v_max_f32_e32 v159, 0, v168
	v_max_f32_e32 v162, 0, v163
	v_max_f32_e32 v163, 0, v169
	v_mul_f32_e32 v168, v160, v160
	v_max_f32_e32 v160, 0, v161
	v_max_f32_e32 v161, 0, v167
	v_mul_f32_e32 v151, v151, v151
	v_mul_f32_e32 v162, v162, v162
	v_mul_f32_e32 v163, v163, v163
	v_max_f32_e32 v166, 0, v166
	v_mul_f32_e32 v167, v160, v160
	v_mul_f32_e32 v169, v161, v161
	v_cvt_pk_bf16_f32 v160, v151, v162
	v_cvt_pk_bf16_f32 v161, v168, v167
	v_mul_f32_e32 v159, v159, v159
	v_mul_f32_e32 v166, v166, v166
	v_cvt_pk_bf16_f32 v162, v159, v163
	v_cvt_pk_bf16_f32 v163, v166, v169
	global_store_dwordx4 v[164:165], v[160:163], off
	v_pk_mul_f32 v[166:167], v[100:101], v[0:1] op_sel_hi:[1,0]
	v_pk_mul_f32 v[168:169], v[98:99], v[0:1] op_sel_hi:[1,0]
	v_pk_mul_f32 v[160:161], v[104:105], v[0:1] op_sel_hi:[1,0]
	v_pk_mul_f32 v[162:163], v[102:103], v[0:1] op_sel_hi:[1,0]
	v_max_f32_e32 v160, 0, v160
	v_max_f32_e32 v0, 0, v162
	v_max_f32_e32 v159, 0, v163
	v_max_f32_e32 v162, 0, v169
	v_max_f32_e32 v163, 0, v166
	v_mul_f32_e32 v166, v160, v160
	v_max_f32_e32 v160, 0, v161
	v_max_f32_e32 v151, 0, v168
	v_mul_f32_e32 v0, v0, v0
	v_mul_f32_e32 v159, v159, v159
	v_mul_f32_e32 v162, v162, v162
	v_mul_f32_e32 v163, v163, v163
	v_max_f32_e32 v161, 0, v167
	v_mul_f32_e32 v167, v160, v160
	v_cvt_pk_bf16_f32 v160, v0, v159
	v_mul_f32_e32 v151, v151, v151
	v_mul_f32_e32 v168, v161, v161
	v_cvt_pk_bf16_f32 v161, v166, v167
	v_cvt_pk_bf16_f32 v162, v151, v162
	v_cvt_pk_bf16_f32 v163, v163, v168
	global_store_dwordx4 v[164:165], v[160:163], off offset:256
	s_nop 1
	v_or_b32_e32 v160, 32, v150
	v_ashrrev_i32_e32 v161, 31, v160
	v_lshl_add_u64 v[162:163], v[160:161], 2, s[8:9]
	v_lshlrev_b64 v[160:161], 13, v[160:161]
	v_lshl_add_u64 v[164:165], v[148:149], 0, v[160:161]
	v_or_b32_e32 v150, 48, v150
	v_fmamk_f32 v0, v204, 0x3a800000, v139
	v_rsq_f32_e32 v0, v0
	s_nop 0
	v_pk_mul_f32 v[160:161], v[96:97], v[0:1] op_sel_hi:[1,0]
	v_pk_mul_f32 v[162:163], v[94:95], v[0:1] op_sel_hi:[1,0]
	v_pk_mul_f32 v[168:169], v[90:91], v[0:1] op_sel_hi:[1,0]
	v_pk_mul_f32 v[166:167], v[92:93], v[0:1] op_sel_hi:[1,0]
	v_max_f32_e32 v151, 0, v162
	v_max_f32_e32 v162, 0, v163
	v_max_f32_e32 v163, 0, v169
	v_max_f32_e32 v160, 0, v160
	v_max_f32_e32 v159, 0, v168
	v_mul_f32_e32 v162, v162, v162
	v_mul_f32_e32 v163, v163, v163
	v_max_f32_e32 v166, 0, v166
	v_mul_f32_e32 v168, v160, v160
	v_max_f32_e32 v160, 0, v161
	v_max_f32_e32 v161, 0, v167
	v_mul_f32_e32 v151, v151, v151
	v_mul_f32_e32 v159, v159, v159
	v_mul_f32_e32 v166, v166, v166
	v_mul_f32_e32 v167, v160, v160
	v_mul_f32_e32 v169, v161, v161
	v_cvt_pk_bf16_f32 v160, v151, v162
	v_cvt_pk_bf16_f32 v161, v168, v167
	v_cvt_pk_bf16_f32 v162, v159, v163
	v_cvt_pk_bf16_f32 v163, v166, v169
	global_store_dwordx4 v[164:165], v[160:163], off
	v_pk_mul_f32 v[168:169], v[82:83], v[0:1] op_sel_hi:[1,0]
	v_pk_mul_f32 v[166:167], v[84:85], v[0:1] op_sel_hi:[1,0]
	v_pk_mul_f32 v[160:161], v[88:89], v[0:1] op_sel_hi:[1,0]
	v_pk_mul_f32 v[162:163], v[86:87], v[0:1] op_sel_hi:[1,0]
	v_max_f32_e32 v151, 0, v168
	v_max_f32_e32 v0, 0, v162
	v_max_f32_e32 v162, 0, v169
	v_max_f32_e32 v160, 0, v160
	v_mul_f32_e32 v151, v151, v151
	v_max_f32_e32 v159, 0, v163
	v_mul_f32_e32 v162, v162, v162
	v_max_f32_e32 v163, 0, v166
	v_mul_f32_e32 v166, v160, v160
	v_max_f32_e32 v160, 0, v161
	v_max_f32_e32 v161, 0, v167
	v_mul_f32_e32 v0, v0, v0
	v_mul_f32_e32 v159, v159, v159
	v_mul_f32_e32 v163, v163, v163
	v_mul_f32_e32 v167, v160, v160
	v_mul_f32_e32 v168, v161, v161
	v_cvt_pk_bf16_f32 v160, v0, v159
	v_cvt_pk_bf16_f32 v161, v166, v167
	v_cvt_pk_bf16_f32 v162, v151, v162
	v_ashrrev_i32_e32 v151, 31, v150
	v_cvt_pk_bf16_f32 v163, v163, v168
	global_store_dwordx4 v[164:165], v[160:163], off offset:256
	s_nop 1
	v_lshl_add_u64 v[160:161], v[150:151], 2, s[8:9]
	v_lshlrev_b64 v[150:151], 13, v[150:151]
	v_lshl_add_u64 v[148:149], v[148:149], 0, v[150:151]
	s_mov_b64 s[8:9], 0x100000
	v_fmamk_f32 v0, v205, 0x3a800000, v139
	v_rsq_f32_e32 v0, v0
	s_nop 0
	v_pk_mul_f32 v[160:161], v[78:79], v[0:1] op_sel_hi:[1,0]
	v_pk_mul_f32 v[164:165], v[74:75], v[0:1] op_sel_hi:[1,0]
	v_max_f32_e32 v159, 0, v160
	v_max_f32_e32 v160, 0, v164
	v_pk_mul_f32 v[162:163], v[76:77], v[0:1] op_sel_hi:[1,0]
	v_mul_f32_e32 v164, v160, v160
	v_max_f32_e32 v160, 0, v161
	v_max_f32_e32 v161, 0, v165
	v_pk_mul_f32 v[150:151], v[80:81], v[0:1] op_sel_hi:[1,0]
	v_mul_f32_e32 v165, v161, v161
	v_max_f32_e32 v161, 0, v162
	v_mul_f32_e32 v160, v160, v160
	v_max_f32_e32 v150, 0, v150
	v_mul_f32_e32 v166, v161, v161
	v_max_f32_e32 v151, 0, v151
	v_max_f32_e32 v161, 0, v163
	v_mul_f32_e32 v159, v159, v159
	v_mul_f32_e32 v150, v150, v150
	v_mul_f32_e32 v151, v151, v151
	v_mul_f32_e32 v163, v161, v161
	v_cvt_pk_bf16_f32 v160, v159, v160
	v_cvt_pk_bf16_f32 v161, v150, v151
	v_cvt_pk_bf16_f32 v162, v164, v165
	v_cvt_pk_bf16_f32 v163, v166, v163
	global_store_dwordx4 v[148:149], v[160:163], off
	v_pk_mul_f32 v[164:165], v[66:67], v[0:1] op_sel_hi:[1,0]
	v_pk_mul_f32 v[150:151], v[72:73], v[0:1] op_sel_hi:[1,0]
	v_pk_mul_f32 v[160:161], v[70:71], v[0:1] op_sel_hi:[1,0]
	v_pk_mul_f32 v[162:163], v[68:69], v[0:1] op_sel_hi:[1,0]
	v_max_f32_e32 v0, 0, v160
	v_max_f32_e32 v160, 0, v161
	v_max_f32_e32 v161, 0, v165
	v_max_f32_e32 v159, 0, v164
	v_mul_f32_e32 v164, v161, v161
	v_max_f32_e32 v161, 0, v162
	v_mul_f32_e32 v165, v161, v161
	v_max_f32_e32 v161, 0, v163
	v_mul_f32_e32 v160, v160, v160
	v_max_f32_e32 v150, 0, v150
	v_max_f32_e32 v151, 0, v151
	v_mul_f32_e32 v163, v161, v161
	v_mul_f32_e32 v0, v0, v0
	v_mul_f32_e32 v159, v159, v159
	v_mul_f32_e32 v150, v150, v150
	v_mul_f32_e32 v151, v151, v151
	v_cvt_pk_bf16_f32 v160, v0, v160
	v_cvt_pk_bf16_f32 v161, v150, v151
	v_cvt_pk_bf16_f32 v162, v159, v164
	v_cvt_pk_bf16_f32 v163, v165, v163
	global_store_dwordx4 v[148:149], v[160:163], off offset:256
	v_lshl_add_u64 v[148:149], v[144:145], 0, s[8:9]
	s_mov_b64 s[8:9], 0x120000
	v_fmamk_f32 v0, v206, 0x3a800000, v139
	v_rsq_f32_e32 v0, v0
	s_nop 0
	v_pk_mul_f32 v[160:161], v[62:63], v[0:1] op_sel_hi:[1,0]
	v_pk_mul_f32 v[164:165], v[58:59], v[0:1] op_sel_hi:[1,0]
	v_max_f32_e32 v159, 0, v160
	v_max_f32_e32 v160, 0, v164
	v_pk_mul_f32 v[150:151], v[64:65], v[0:1] op_sel_hi:[1,0]
	v_pk_mul_f32 v[162:163], v[60:61], v[0:1] op_sel_hi:[1,0]
	v_mul_f32_e32 v164, v160, v160
	v_max_f32_e32 v160, 0, v161
	v_max_f32_e32 v161, 0, v165
	v_mul_f32_e32 v165, v161, v161
	v_max_f32_e32 v150, 0, v150
	v_max_f32_e32 v161, 0, v162
	v_mul_f32_e32 v160, v160, v160
	v_mul_f32_e32 v150, v150, v150
	v_mul_f32_e32 v166, v161, v161
	v_max_f32_e32 v151, 0, v151
	v_max_f32_e32 v161, 0, v163
	v_mul_f32_e32 v159, v159, v159
	v_mul_f32_e32 v151, v151, v151
	v_mul_f32_e32 v163, v161, v161
	v_cvt_pk_bf16_f32 v160, v159, v160
	v_cvt_pk_bf16_f32 v161, v150, v151
	v_add_co_u32_e32 v150, vcc, s3, v144
	v_cvt_pk_bf16_f32 v162, v164, v165
	v_cvt_pk_bf16_f32 v163, v166, v163
	v_pk_mul_f32 v[164:165], v[50:51], v[0:1] op_sel_hi:[1,0]
	s_nop 0
	v_addc_co_u32_e32 v151, vcc, 0, v145, vcc
	global_store_dwordx4 v[150:151], v[160:163], off
	v_pk_mul_f32 v[150:151], v[56:57], v[0:1] op_sel_hi:[1,0]
	v_max_f32_e32 v159, 0, v164
	v_pk_mul_f32 v[160:161], v[54:55], v[0:1] op_sel_hi:[1,0]
	v_pk_mul_f32 v[162:163], v[52:53], v[0:1] op_sel_hi:[1,0]
	v_max_f32_e32 v0, 0, v160
	v_max_f32_e32 v160, 0, v161
	v_max_f32_e32 v161, 0, v165
	v_mul_f32_e32 v164, v161, v161
	v_max_f32_e32 v161, 0, v162
	v_mul_f32_e32 v165, v161, v161
	v_max_f32_e32 v161, 0, v163
	v_mul_f32_e32 v160, v160, v160
	v_max_f32_e32 v150, 0, v150
	v_max_f32_e32 v151, 0, v151
	v_mul_f32_e32 v163, v161, v161
	v_mul_f32_e32 v0, v0, v0
	v_mul_f32_e32 v159, v159, v159
	v_mul_f32_e32 v150, v150, v150
	v_mul_f32_e32 v151, v151, v151
	v_cvt_pk_bf16_f32 v160, v0, v160
	v_cvt_pk_bf16_f32 v161, v150, v151
	v_cvt_pk_bf16_f32 v162, v159, v164
	v_cvt_pk_bf16_f32 v163, v165, v163
	global_store_dwordx4 v[148:149], v[160:163], off offset:256
	s_mov_b32 s3, 0x120000
	v_lshl_add_u64 v[148:149], v[144:145], 0, s[8:9]
	s_mov_b64 s[8:9], 0x140000
	v_fmamk_f32 v0, v207, 0x3a800000, v139
	v_rsq_f32_e32 v0, v0
	s_nop 0
	v_pk_mul_f32 v[160:161], v[46:47], v[0:1] op_sel_hi:[1,0]
	v_pk_mul_f32 v[164:165], v[42:43], v[0:1] op_sel_hi:[1,0]
	v_max_f32_e32 v159, 0, v160
	v_max_f32_e32 v160, 0, v164
	v_pk_mul_f32 v[150:151], v[48:49], v[0:1] op_sel_hi:[1,0]
	v_pk_mul_f32 v[162:163], v[44:45], v[0:1] op_sel_hi:[1,0]
	v_mul_f32_e32 v164, v160, v160
	v_max_f32_e32 v160, 0, v161
	v_max_f32_e32 v161, 0, v165
	v_mul_f32_e32 v165, v161, v161
	v_max_f32_e32 v150, 0, v150
	v_max_f32_e32 v161, 0, v162
	v_mul_f32_e32 v160, v160, v160
	v_mul_f32_e32 v150, v150, v150
	v_mul_f32_e32 v166, v161, v161
	v_max_f32_e32 v151, 0, v151
	v_max_f32_e32 v161, 0, v163
	v_mul_f32_e32 v159, v159, v159
	v_mul_f32_e32 v151, v151, v151
	v_mul_f32_e32 v163, v161, v161
	v_cvt_pk_bf16_f32 v160, v159, v160
	v_cvt_pk_bf16_f32 v161, v150, v151
	v_add_co_u32_e32 v150, vcc, s3, v144
	v_cvt_pk_bf16_f32 v162, v164, v165
	v_cvt_pk_bf16_f32 v163, v166, v163
	v_pk_mul_f32 v[164:165], v[34:35], v[0:1] op_sel_hi:[1,0]
	s_nop 0
	v_addc_co_u32_e32 v151, vcc, 0, v145, vcc
	global_store_dwordx4 v[150:151], v[160:163], off
	v_pk_mul_f32 v[150:151], v[40:41], v[0:1] op_sel_hi:[1,0]
	v_max_f32_e32 v159, 0, v164
	v_pk_mul_f32 v[160:161], v[38:39], v[0:1] op_sel_hi:[1,0]
	v_pk_mul_f32 v[162:163], v[36:37], v[0:1] op_sel_hi:[1,0]
	v_max_f32_e32 v0, 0, v160
	v_max_f32_e32 v160, 0, v161
	v_max_f32_e32 v161, 0, v165
	v_mul_f32_e32 v164, v161, v161
	v_max_f32_e32 v161, 0, v162
	v_mul_f32_e32 v165, v161, v161
	v_max_f32_e32 v161, 0, v163
	v_mul_f32_e32 v160, v160, v160
	v_max_f32_e32 v150, 0, v150
	v_max_f32_e32 v151, 0, v151
	v_mul_f32_e32 v163, v161, v161
	v_mul_f32_e32 v0, v0, v0
	v_mul_f32_e32 v159, v159, v159
	v_mul_f32_e32 v150, v150, v150
	v_mul_f32_e32 v151, v151, v151
	v_cvt_pk_bf16_f32 v160, v0, v160
	v_cvt_pk_bf16_f32 v161, v150, v151
	v_cvt_pk_bf16_f32 v162, v159, v164
	v_cvt_pk_bf16_f32 v163, v165, v163
	global_store_dwordx4 v[148:149], v[160:163], off offset:256
	s_mov_b32 s3, 0x140000
	v_lshl_add_u64 v[148:149], v[144:145], 0, s[8:9]
	s_mov_b64 s[8:9], 0x160000
	v_fmamk_f32 v0, v208, 0x3a800000, v139
	v_rsq_f32_e32 v0, v0
	s_nop 0
	v_pk_mul_f32 v[160:161], v[30:31], v[0:1] op_sel_hi:[1,0]
	v_pk_mul_f32 v[164:165], v[26:27], v[0:1] op_sel_hi:[1,0]
	v_max_f32_e32 v159, 0, v160
	v_max_f32_e32 v160, 0, v164
	v_pk_mul_f32 v[150:151], v[32:33], v[0:1] op_sel_hi:[1,0]
	v_pk_mul_f32 v[162:163], v[28:29], v[0:1] op_sel_hi:[1,0]
	v_mul_f32_e32 v164, v160, v160
	v_max_f32_e32 v160, 0, v161
	v_max_f32_e32 v161, 0, v165
	v_mul_f32_e32 v165, v161, v161
	v_max_f32_e32 v150, 0, v150
	v_max_f32_e32 v161, 0, v162
	v_mul_f32_e32 v160, v160, v160
	v_mul_f32_e32 v150, v150, v150
	v_mul_f32_e32 v166, v161, v161
	v_max_f32_e32 v151, 0, v151
	v_max_f32_e32 v161, 0, v163
	v_mul_f32_e32 v159, v159, v159
	v_mul_f32_e32 v151, v151, v151
	v_mul_f32_e32 v163, v161, v161
	v_cvt_pk_bf16_f32 v160, v159, v160
	v_cvt_pk_bf16_f32 v161, v150, v151
	v_add_co_u32_e32 v150, vcc, s3, v144
	v_cvt_pk_bf16_f32 v162, v164, v165
	v_cvt_pk_bf16_f32 v163, v166, v163
	v_pk_mul_f32 v[164:165], v[18:19], v[0:1] op_sel_hi:[1,0]
	s_nop 0
	v_addc_co_u32_e32 v151, vcc, 0, v145, vcc
	global_store_dwordx4 v[150:151], v[160:163], off
	v_pk_mul_f32 v[150:151], v[24:25], v[0:1] op_sel_hi:[1,0]
	v_max_f32_e32 v159, 0, v164
	v_pk_mul_f32 v[160:161], v[22:23], v[0:1] op_sel_hi:[1,0]
	v_pk_mul_f32 v[162:163], v[20:21], v[0:1] op_sel_hi:[1,0]
	v_max_f32_e32 v0, 0, v160
	v_max_f32_e32 v160, 0, v161
	v_max_f32_e32 v161, 0, v165
	v_mul_f32_e32 v164, v161, v161
	v_max_f32_e32 v161, 0, v162
	v_mul_f32_e32 v165, v161, v161
	v_max_f32_e32 v161, 0, v163
	v_mul_f32_e32 v160, v160, v160
	v_max_f32_e32 v150, 0, v150
	v_max_f32_e32 v151, 0, v151
	v_mul_f32_e32 v163, v161, v161
	v_mul_f32_e32 v0, v0, v0
	v_mul_f32_e32 v159, v159, v159
	v_mul_f32_e32 v150, v150, v150
	v_mul_f32_e32 v151, v151, v151
	v_cvt_pk_bf16_f32 v160, v0, v160
	v_cvt_pk_bf16_f32 v161, v150, v151
	v_cvt_pk_bf16_f32 v162, v159, v164
	v_cvt_pk_bf16_f32 v163, v165, v163
	global_store_dwordx4 v[148:149], v[160:163], off offset:256
	s_mov_b32 s3, 0x160000
	v_lshl_add_u64 v[146:147], v[144:145], 0, s[8:9]
	v_add_co_u32_e32 v144, vcc, s3, v144
	v_fmamk_f32 v0, v209, 0x3a800000, v139
	v_rsq_f32_e32 v0, v0
	v_addc_co_u32_e32 v145, vcc, 0, v145, vcc
	v_pk_mul_f32 v[148:149], v[16:17], v[0:1] op_sel_hi:[1,0]
	v_pk_mul_f32 v[150:151], v[14:15], v[0:1] op_sel_hi:[1,0]
	v_pk_mul_f32 v[160:161], v[12:13], v[0:1] op_sel_hi:[1,0]
	v_pk_mul_f32 v[162:163], v[10:11], v[0:1] op_sel_hi:[1,0]
	v_max_f32_e32 v148, 0, v148
	v_max_f32_e32 v150, 0, v150
	v_max_f32_e32 v159, 0, v162
	v_max_f32_e32 v151, 0, v151
	v_max_f32_e32 v162, 0, v163
	v_max_f32_e32 v160, 0, v160
	v_mul_f32_e32 v163, v148, v148
	v_max_f32_e32 v148, 0, v149
	v_max_f32_e32 v149, 0, v161
	v_mul_f32_e32 v150, v150, v150
	v_mul_f32_e32 v151, v151, v151
	v_mul_f32_e32 v160, v160, v160
	v_mul_f32_e32 v161, v148, v148
	v_mul_f32_e32 v164, v149, v149
	v_cvt_pk_bf16_f32 v148, v150, v151
	v_cvt_pk_bf16_f32 v149, v163, v161
	v_mul_f32_e32 v159, v159, v159
	v_mul_f32_e32 v162, v162, v162
	v_cvt_pk_bf16_f32 v150, v159, v162
	v_cvt_pk_bf16_f32 v151, v160, v164
	global_store_dwordx4 v[144:145], v[148:151], off
	v_pk_mul_f32 v[160:161], v[2:3], v[0:1] op_sel_hi:[1,0]
	v_pk_mul_f32 v[144:145], v[8:9], v[0:1] op_sel_hi:[1,0]
	v_pk_mul_f32 v[148:149], v[6:7], v[0:1] op_sel_hi:[1,0]
	v_pk_mul_f32 v[150:151], v[4:5], v[0:1] op_sel_hi:[1,0]
	v_max_f32_e32 v0, 0, v148
	v_max_f32_e32 v148, 0, v160
	v_mul_f32_e32 v159, v148, v148
	v_max_f32_e32 v148, 0, v149
	v_max_f32_e32 v149, 0, v161
	v_mul_f32_e32 v160, v149, v149
	v_max_f32_e32 v149, 0, v150
	v_mul_f32_e32 v161, v149, v149
	v_max_f32_e32 v149, 0, v151
	v_mul_f32_e32 v148, v148, v148
	v_max_f32_e32 v144, 0, v144
	v_max_f32_e32 v145, 0, v145
	v_mul_f32_e32 v151, v149, v149
	v_mul_f32_e32 v0, v0, v0
	v_mul_f32_e32 v144, v144, v144
	v_mul_f32_e32 v145, v145, v145
	v_cvt_pk_bf16_f32 v148, v0, v148
	v_cvt_pk_bf16_f32 v149, v144, v145
	v_cvt_pk_bf16_f32 v150, v159, v160
	v_cvt_pk_bf16_f32 v151, v161, v151
	global_store_dwordx4 v[146:147], v[148:151], off offset:256

.LBB0_989:
	s_andn2_b64 vcc, exec, s[8:9]
	s_cbranch_vccnz .LBB0_1007
	v_readlane_b32 s76, v254, 28
	v_readlane_b32 s77, v254, 29
	v_readlane_b32 s34, v254, 63
	v_readlane_b32 s35, v255, 0
	v_add_u32_e32 v146, s10, v155
	v_lshl_or_b32 v144, s44, 8, v157
	v_ashrrev_i32_e32 v147, 31, v146
	v_ashrrev_i32_e32 v145, 31, v144
	v_lshlrev_b64 v[148:149], 10, v[146:147]
	v_lshl_add_u64 v[144:145], v[148:149], 0, v[144:145]
	v_xor_b32_e32 v203, 16, v201
	v_xor_b32_e32 v204, 32, v201
	v_lshlrev_b32_e32 v203, 2, v203
	v_lshlrev_b32_e32 v204, 2, v204
	v_lshl_add_u64 v[148:149], v[144:145], 2, s[76:77]
	v_lshl_add_u64 v[150:151], v[144:145], 1, s[96:97]
	v_lshl_add_u64 v[146:147], v[146:147], 2, s[34:35]
	global_load_dwordx4 v[160:163], v[148:149], off
	global_load_dwordx4 v[164:167], v[148:149], off offset:64
	global_load_dwordx4 v[168:171], v[148:149], off offset:512
	global_load_dwordx4 v[172:175], v[148:149], off offset:576
	s_mov_b64 s[8:9], 0x10000
	v_lshl_add_u64 v[206:207], v[148:149], 0, s[8:9]
	global_load_dwordx4 v[176:179], v[206:207], off
	global_load_dwordx4 v[180:183], v[206:207], off offset:64
	global_load_dwordx4 v[184:187], v[206:207], off offset:512
	global_load_dwordx4 v[188:191], v[206:207], off offset:576
	s_waitcnt vmcnt(7)
	v_pk_add_f32 v[160:161], v[126:127], v[160:161]
	v_pk_add_f32 v[162:163], v[128:129], v[162:163]
	v_cvt_pk_bf16_f32 v192, v160, v161
	v_cvt_pk_bf16_f32 v193, v162, v163
	global_store_dwordx2 v[150:151], v[192:193], off
	v_mul_f32_e32 v196, v161, v161
	v_fmac_f32_e32 v196, v160, v160
	v_mul_f32_e32 v197, v163, v163
	v_fmac_f32_e32 v197, v162, v162
	v_add_f32_e32 v198, v196, v197
	s_waitcnt vmcnt(7)
	v_pk_add_f32 v[164:165], v[122:123], v[164:165]
	v_pk_add_f32 v[166:167], v[124:125], v[166:167]
	v_cvt_pk_bf16_f32 v194, v164, v165
	v_cvt_pk_bf16_f32 v195, v166, v167
	global_store_dwordx2 v[150:151], v[194:195], off offset:32
	v_mul_f32_e32 v196, v165, v165
	v_fmac_f32_e32 v196, v164, v164
	v_mul_f32_e32 v197, v167, v167
	v_fmac_f32_e32 v197, v166, v166
	v_add_f32_e32 v196, v196, v197
	v_add_f32_e32 v198, v198, v196
	s_waitcnt vmcnt(7)
	v_pk_add_f32 v[168:169], v[118:119], v[168:169]
	v_pk_add_f32 v[170:171], v[120:121], v[170:171]
	v_cvt_pk_bf16_f32 v192, v168, v169
	v_cvt_pk_bf16_f32 v193, v170, v171
	global_store_dwordx2 v[150:151], v[192:193], off offset:256
	v_mul_f32_e32 v196, v169, v169
	v_fmac_f32_e32 v196, v168, v168
	v_mul_f32_e32 v197, v171, v171
	v_fmac_f32_e32 v197, v170, v170
	v_add_f32_e32 v196, v196, v197
	v_add_f32_e32 v198, v198, v196
	s_waitcnt vmcnt(7)
	v_pk_add_f32 v[172:173], v[114:115], v[172:173]
	v_pk_add_f32 v[174:175], v[116:117], v[174:175]
	v_cvt_pk_bf16_f32 v194, v172, v173
	v_cvt_pk_bf16_f32 v195, v174, v175
	global_store_dwordx2 v[150:151], v[194:195], off offset:288
	v_mul_f32_e32 v196, v173, v173
	v_fmac_f32_e32 v196, v172, v172
	v_mul_f32_e32 v197, v175, v175
	v_fmac_f32_e32 v197, v174, v174
	v_add_f32_e32 v196, v196, v197
	v_add_f32_e32 v198, v198, v196
	ds_bpermute_b32 v199, v203, v198
	s_waitcnt lgkmcnt(0)
	v_add_f32_e32 v198, v198, v199
	ds_bpermute_b32 v199, v204, v198
	s_waitcnt lgkmcnt(0)
	v_add_f32_e32 v198, v198, v199
	s_and_saveexec_b64 s[8:9], s[4:5]
	global_atomic_add_f32 v[146:147], v198, off
	s_or_b64 exec, exec, s[8:9]
	s_mov_b64 s[8:9], 0x8000
	v_lshl_add_u64 v[208:209], v[150:151], 0, s[8:9]
	s_waitcnt vmcnt(8)
	v_pk_add_f32 v[176:177], v[110:111], v[176:177]
	v_pk_add_f32 v[178:179], v[112:113], v[178:179]
	v_cvt_pk_bf16_f32 v192, v176, v177
	v_cvt_pk_bf16_f32 v193, v178, v179
	global_store_dwordx2 v[208:209], v[192:193], off
	v_mul_f32_e32 v196, v177, v177
	v_fmac_f32_e32 v196, v176, v176
	v_mul_f32_e32 v197, v179, v179
	v_fmac_f32_e32 v197, v178, v178
	v_add_f32_e32 v198, v196, v197
	s_waitcnt vmcnt(8)
	v_pk_add_f32 v[180:181], v[106:107], v[180:181]
	v_pk_add_f32 v[182:183], v[108:109], v[182:183]
	v_cvt_pk_bf16_f32 v194, v180, v181
	v_cvt_pk_bf16_f32 v195, v182, v183
	global_store_dwordx2 v[208:209], v[194:195], off offset:32
	v_mul_f32_e32 v196, v181, v181
	v_fmac_f32_e32 v196, v180, v180
	v_mul_f32_e32 v197, v183, v183
	v_fmac_f32_e32 v197, v182, v182
	v_add_f32_e32 v196, v196, v197
	v_add_f32_e32 v198, v198, v196
	s_waitcnt vmcnt(8)
	v_pk_add_f32 v[184:185], v[102:103], v[184:185]
	v_pk_add_f32 v[186:187], v[104:105], v[186:187]
	v_cvt_pk_bf16_f32 v192, v184, v185
	v_cvt_pk_bf16_f32 v193, v186, v187
	global_store_dwordx2 v[208:209], v[192:193], off offset:256
	v_mul_f32_e32 v196, v185, v185
	v_fmac_f32_e32 v196, v184, v184
	v_mul_f32_e32 v197, v187, v187
	v_fmac_f32_e32 v197, v186, v186
	v_add_f32_e32 v196, v196, v197
	v_add_f32_e32 v198, v198, v196
	s_waitcnt vmcnt(8)
	v_pk_add_f32 v[188:189], v[98:99], v[188:189]
	v_pk_add_f32 v[190:191], v[100:101], v[190:191]
	v_cvt_pk_bf16_f32 v194, v188, v189
	v_cvt_pk_bf16_f32 v195, v190, v191
	global_store_dwordx2 v[208:209], v[194:195], off offset:288
	v_mul_f32_e32 v196, v189, v189
	v_fmac_f32_e32 v196, v188, v188
	v_mul_f32_e32 v197, v191, v191
	v_fmac_f32_e32 v197, v190, v190
	v_add_f32_e32 v196, v196, v197
	v_add_f32_e32 v198, v198, v196
	ds_bpermute_b32 v199, v203, v198
	s_waitcnt lgkmcnt(0)
	v_add_f32_e32 v198, v198, v199
	ds_bpermute_b32 v199, v204, v198
	v_add_co_u32_e32 v210, vcc, 0x40, v146
	s_waitcnt lgkmcnt(0)
	s_nop 1
	v_addc_co_u32_e32 v211, vcc, 0, v147, vcc
	v_add_f32_e32 v198, v198, v199
	s_and_saveexec_b64 s[8:9], s[4:5]
	global_atomic_add_f32 v[210:211], v198, off
	s_or_b64 exec, exec, s[8:9]
	s_mov_b64 s[8:9], 0x20000
	v_lshl_add_u64 v[206:207], v[148:149], 0, s[8:9]
	global_load_dwordx4 v[160:163], v[206:207], off
	global_load_dwordx4 v[164:167], v[206:207], off offset:64
	global_load_dwordx4 v[168:171], v[206:207], off offset:512
	global_load_dwordx4 v[172:175], v[206:207], off offset:576
	s_mov_b64 s[8:9], 0x30000
	v_lshl_add_u64 v[206:207], v[148:149], 0, s[8:9]
	global_load_dwordx4 v[176:179], v[206:207], off
	global_load_dwordx4 v[180:183], v[206:207], off offset:64
	global_load_dwordx4 v[184:187], v[206:207], off offset:512
	global_load_dwordx4 v[188:191], v[206:207], off offset:576
	s_mov_b64 s[8:9], 0x10000
	v_lshl_add_u64 v[208:209], v[150:151], 0, s[8:9]
	s_waitcnt vmcnt(7)
	v_pk_add_f32 v[160:161], v[94:95], v[160:161]
	v_pk_add_f32 v[162:163], v[96:97], v[162:163]
	v_cvt_pk_bf16_f32 v192, v160, v161
	v_cvt_pk_bf16_f32 v193, v162, v163
	global_store_dwordx2 v[208:209], v[192:193], off
	v_mul_f32_e32 v196, v161, v161
	v_fmac_f32_e32 v196, v160, v160
	v_mul_f32_e32 v197, v163, v163
	v_fmac_f32_e32 v197, v162, v162
	v_add_f32_e32 v198, v196, v197
	s_waitcnt vmcnt(7)
	v_pk_add_f32 v[164:165], v[90:91], v[164:165]
	v_pk_add_f32 v[166:167], v[92:93], v[166:167]
	v_cvt_pk_bf16_f32 v194, v164, v165
	v_cvt_pk_bf16_f32 v195, v166, v167
	global_store_dwordx2 v[208:209], v[194:195], off offset:32
	v_mul_f32_e32 v196, v165, v165
	v_fmac_f32_e32 v196, v164, v164
	v_mul_f32_e32 v197, v167, v167
	v_fmac_f32_e32 v197, v166, v166
	v_add_f32_e32 v196, v196, v197
	v_add_f32_e32 v198, v198, v196
	s_waitcnt vmcnt(7)
	v_pk_add_f32 v[168:169], v[86:87], v[168:169]
	v_pk_add_f32 v[170:171], v[88:89], v[170:171]
	v_cvt_pk_bf16_f32 v192, v168, v169
	v_cvt_pk_bf16_f32 v193, v170, v171
	global_store_dwordx2 v[208:209], v[192:193], off offset:256
	v_mul_f32_e32 v196, v169, v169
	v_fmac_f32_e32 v196, v168, v168
	v_mul_f32_e32 v197, v171, v171
	v_fmac_f32_e32 v197, v170, v170
	v_add_f32_e32 v196, v196, v197
	v_add_f32_e32 v198, v198, v196
	s_waitcnt vmcnt(7)
	v_pk_add_f32 v[172:173], v[82:83], v[172:173]
	v_pk_add_f32 v[174:175], v[84:85], v[174:175]
	v_cvt_pk_bf16_f32 v194, v172, v173
	v_cvt_pk_bf16_f32 v195, v174, v175
	global_store_dwordx2 v[208:209], v[194:195], off offset:288
	v_mul_f32_e32 v196, v173, v173
	v_fmac_f32_e32 v196, v172, v172
	v_mul_f32_e32 v197, v175, v175
	v_fmac_f32_e32 v197, v174, v174
	v_add_f32_e32 v196, v196, v197
	v_add_f32_e32 v198, v198, v196
	ds_bpermute_b32 v199, v203, v198
	s_waitcnt lgkmcnt(0)
	v_add_f32_e32 v198, v198, v199
	ds_bpermute_b32 v199, v204, v198
	v_add_co_u32_e32 v210, vcc, 0x80, v146
	s_waitcnt lgkmcnt(0)
	s_nop 1
	v_addc_co_u32_e32 v211, vcc, 0, v147, vcc
	v_add_f32_e32 v198, v198, v199
	s_and_saveexec_b64 s[8:9], s[4:5]
	global_atomic_add_f32 v[210:211], v198, off
	s_or_b64 exec, exec, s[8:9]
	s_mov_b64 s[8:9], 0x18000
	v_lshl_add_u64 v[208:209], v[150:151], 0, s[8:9]
	s_waitcnt vmcnt(8)
	v_pk_add_f32 v[176:177], v[78:79], v[176:177]
	v_pk_add_f32 v[178:179], v[80:81], v[178:179]
	v_cvt_pk_bf16_f32 v192, v176, v177
	v_cvt_pk_bf16_f32 v193, v178, v179
	global_store_dwordx2 v[208:209], v[192:193], off
	v_mul_f32_e32 v196, v177, v177
	v_fmac_f32_e32 v196, v176, v176
	v_mul_f32_e32 v197, v179, v179
	v_fmac_f32_e32 v197, v178, v178
	v_add_f32_e32 v198, v196, v197
	s_waitcnt vmcnt(8)
	v_pk_add_f32 v[180:181], v[74:75], v[180:181]
	v_pk_add_f32 v[182:183], v[76:77], v[182:183]
	v_cvt_pk_bf16_f32 v194, v180, v181
	v_cvt_pk_bf16_f32 v195, v182, v183
	global_store_dwordx2 v[208:209], v[194:195], off offset:32
	v_mul_f32_e32 v196, v181, v181
	v_fmac_f32_e32 v196, v180, v180
	v_mul_f32_e32 v197, v183, v183
	v_fmac_f32_e32 v197, v182, v182
	v_add_f32_e32 v196, v196, v197
	v_add_f32_e32 v198, v198, v196
	s_waitcnt vmcnt(8)
	v_pk_add_f32 v[184:185], v[70:71], v[184:185]
	v_pk_add_f32 v[186:187], v[72:73], v[186:187]
	v_cvt_pk_bf16_f32 v192, v184, v185
	v_cvt_pk_bf16_f32 v193, v186, v187
	global_store_dwordx2 v[208:209], v[192:193], off offset:256
	v_mul_f32_e32 v196, v185, v185
	v_fmac_f32_e32 v196, v184, v184
	v_mul_f32_e32 v197, v187, v187
	v_fmac_f32_e32 v197, v186, v186
	v_add_f32_e32 v196, v196, v197
	v_add_f32_e32 v198, v198, v196
	s_waitcnt vmcnt(8)
	v_pk_add_f32 v[188:189], v[66:67], v[188:189]
	v_pk_add_f32 v[190:191], v[68:69], v[190:191]
	v_cvt_pk_bf16_f32 v194, v188, v189
	v_cvt_pk_bf16_f32 v195, v190, v191
	global_store_dwordx2 v[208:209], v[194:195], off offset:288
	v_mul_f32_e32 v196, v189, v189
	v_fmac_f32_e32 v196, v188, v188
	v_mul_f32_e32 v197, v191, v191
	v_fmac_f32_e32 v197, v190, v190
	v_add_f32_e32 v196, v196, v197
	v_add_f32_e32 v198, v198, v196
	ds_bpermute_b32 v199, v203, v198
	s_waitcnt lgkmcnt(0)
	v_add_f32_e32 v198, v198, v199
	ds_bpermute_b32 v199, v204, v198
	v_add_co_u32_e32 v210, vcc, 0xc0, v146
	s_waitcnt lgkmcnt(0)
	s_nop 1
	v_addc_co_u32_e32 v211, vcc, 0, v147, vcc
	v_add_f32_e32 v198, v198, v199
	s_and_saveexec_b64 s[8:9], s[4:5]
	global_atomic_add_f32 v[210:211], v198, off
	s_or_b64 exec, exec, s[8:9]
	s_mov_b64 s[8:9], 0x80000
	v_lshl_add_u64 v[206:207], v[148:149], 0, s[8:9]
	global_load_dwordx4 v[160:163], v[206:207], off
	global_load_dwordx4 v[164:167], v[206:207], off offset:64
	global_load_dwordx4 v[168:171], v[206:207], off offset:512
	global_load_dwordx4 v[172:175], v[206:207], off offset:576
	s_mov_b64 s[8:9], 0x90000
	v_lshl_add_u64 v[206:207], v[148:149], 0, s[8:9]
	global_load_dwordx4 v[176:179], v[206:207], off
	global_load_dwordx4 v[180:183], v[206:207], off offset:64
	global_load_dwordx4 v[184:187], v[206:207], off offset:512
	global_load_dwordx4 v[188:191], v[206:207], off offset:576
	s_mov_b64 s[8:9], 0x40000
	v_lshl_add_u64 v[208:209], v[150:151], 0, s[8:9]
	s_waitcnt vmcnt(7)
	v_pk_add_f32 v[160:161], v[62:63], v[160:161]
	v_pk_add_f32 v[162:163], v[64:65], v[162:163]
	v_cvt_pk_bf16_f32 v192, v160, v161
	v_cvt_pk_bf16_f32 v193, v162, v163
	global_store_dwordx2 v[208:209], v[192:193], off
	v_mul_f32_e32 v196, v161, v161
	v_fmac_f32_e32 v196, v160, v160
	v_mul_f32_e32 v197, v163, v163
	v_fmac_f32_e32 v197, v162, v162
	v_add_f32_e32 v198, v196, v197
	s_waitcnt vmcnt(7)
	v_pk_add_f32 v[164:165], v[58:59], v[164:165]
	v_pk_add_f32 v[166:167], v[60:61], v[166:167]
	v_cvt_pk_bf16_f32 v194, v164, v165
	v_cvt_pk_bf16_f32 v195, v166, v167
	global_store_dwordx2 v[208:209], v[194:195], off offset:32
	v_mul_f32_e32 v196, v165, v165
	v_fmac_f32_e32 v196, v164, v164
	v_mul_f32_e32 v197, v167, v167
	v_fmac_f32_e32 v197, v166, v166
	v_add_f32_e32 v196, v196, v197
	v_add_f32_e32 v198, v198, v196
	s_waitcnt vmcnt(7)
	v_pk_add_f32 v[168:169], v[54:55], v[168:169]
	v_pk_add_f32 v[170:171], v[56:57], v[170:171]
	v_cvt_pk_bf16_f32 v192, v168, v169
	v_cvt_pk_bf16_f32 v193, v170, v171
	global_store_dwordx2 v[208:209], v[192:193], off offset:256
	v_mul_f32_e32 v196, v169, v169
	v_fmac_f32_e32 v196, v168, v168
	v_mul_f32_e32 v197, v171, v171
	v_fmac_f32_e32 v197, v170, v170
	v_add_f32_e32 v196, v196, v197
	v_add_f32_e32 v198, v198, v196
	s_waitcnt vmcnt(7)
	v_pk_add_f32 v[172:173], v[50:51], v[172:173]
	v_pk_add_f32 v[174:175], v[52:53], v[174:175]
	v_cvt_pk_bf16_f32 v194, v172, v173
	v_cvt_pk_bf16_f32 v195, v174, v175
	global_store_dwordx2 v[208:209], v[194:195], off offset:288
	v_mul_f32_e32 v196, v173, v173
	v_fmac_f32_e32 v196, v172, v172
	v_mul_f32_e32 v197, v175, v175
	v_fmac_f32_e32 v197, v174, v174
	v_add_f32_e32 v196, v196, v197
	v_add_f32_e32 v198, v198, v196
	ds_bpermute_b32 v199, v203, v198
	s_waitcnt lgkmcnt(0)
	v_add_f32_e32 v198, v198, v199
	ds_bpermute_b32 v199, v204, v198
	v_add_co_u32_e32 v210, vcc, 0x200, v146
	s_waitcnt lgkmcnt(0)
	s_nop 1
	v_addc_co_u32_e32 v211, vcc, 0, v147, vcc
	v_add_f32_e32 v198, v198, v199
	s_and_saveexec_b64 s[8:9], s[4:5]
	global_atomic_add_f32 v[210:211], v198, off
	s_or_b64 exec, exec, s[8:9]
	s_mov_b64 s[8:9], 0x48000
	v_lshl_add_u64 v[208:209], v[150:151], 0, s[8:9]
	s_waitcnt vmcnt(8)
	v_pk_add_f32 v[176:177], v[46:47], v[176:177]
	v_pk_add_f32 v[178:179], v[48:49], v[178:179]
	v_cvt_pk_bf16_f32 v192, v176, v177
	v_cvt_pk_bf16_f32 v193, v178, v179
	global_store_dwordx2 v[208:209], v[192:193], off
	v_mul_f32_e32 v196, v177, v177
	v_fmac_f32_e32 v196, v176, v176
	v_mul_f32_e32 v197, v179, v179
	v_fmac_f32_e32 v197, v178, v178
	v_add_f32_e32 v198, v196, v197
	s_waitcnt vmcnt(8)
	v_pk_add_f32 v[180:181], v[42:43], v[180:181]
	v_pk_add_f32 v[182:183], v[44:45], v[182:183]
	v_cvt_pk_bf16_f32 v194, v180, v181
	v_cvt_pk_bf16_f32 v195, v182, v183
	global_store_dwordx2 v[208:209], v[194:195], off offset:32
	v_mul_f32_e32 v196, v181, v181
	v_fmac_f32_e32 v196, v180, v180
	v_mul_f32_e32 v197, v183, v183
	v_fmac_f32_e32 v197, v182, v182
	v_add_f32_e32 v196, v196, v197
	v_add_f32_e32 v198, v198, v196
	s_waitcnt vmcnt(8)
	v_pk_add_f32 v[184:185], v[38:39], v[184:185]
	v_pk_add_f32 v[186:187], v[40:41], v[186:187]
	v_cvt_pk_bf16_f32 v192, v184, v185
	v_cvt_pk_bf16_f32 v193, v186, v187
	global_store_dwordx2 v[208:209], v[192:193], off offset:256
	v_mul_f32_e32 v196, v185, v185
	v_fmac_f32_e32 v196, v184, v184
	v_mul_f32_e32 v197, v187, v187
	v_fmac_f32_e32 v197, v186, v186
	v_add_f32_e32 v196, v196, v197
	v_add_f32_e32 v198, v198, v196
	s_waitcnt vmcnt(8)
	v_pk_add_f32 v[188:189], v[34:35], v[188:189]
	v_pk_add_f32 v[190:191], v[36:37], v[190:191]
	v_cvt_pk_bf16_f32 v194, v188, v189
	v_cvt_pk_bf16_f32 v195, v190, v191
	global_store_dwordx2 v[208:209], v[194:195], off offset:288
	v_mul_f32_e32 v196, v189, v189
	v_fmac_f32_e32 v196, v188, v188
	v_mul_f32_e32 v197, v191, v191
	v_fmac_f32_e32 v197, v190, v190
	v_add_f32_e32 v196, v196, v197
	v_add_f32_e32 v198, v198, v196
	ds_bpermute_b32 v199, v203, v198
	s_waitcnt lgkmcnt(0)
	v_add_f32_e32 v198, v198, v199
	ds_bpermute_b32 v199, v204, v198
	v_add_co_u32_e32 v210, vcc, 0x240, v146
	s_waitcnt lgkmcnt(0)
	s_nop 1
	v_addc_co_u32_e32 v211, vcc, 0, v147, vcc
	v_add_f32_e32 v198, v198, v199
	s_and_saveexec_b64 s[8:9], s[4:5]
	global_atomic_add_f32 v[210:211], v198, off
	s_or_b64 exec, exec, s[8:9]
	s_mov_b64 s[8:9], 0xa0000
	v_lshl_add_u64 v[206:207], v[148:149], 0, s[8:9]
	global_load_dwordx4 v[160:163], v[206:207], off
	global_load_dwordx4 v[164:167], v[206:207], off offset:64
	global_load_dwordx4 v[168:171], v[206:207], off offset:512
	global_load_dwordx4 v[172:175], v[206:207], off offset:576
	s_mov_b64 s[8:9], 0xb0000
	v_lshl_add_u64 v[206:207], v[148:149], 0, s[8:9]
	global_load_dwordx4 v[176:179], v[206:207], off
	global_load_dwordx4 v[180:183], v[206:207], off offset:64
	global_load_dwordx4 v[184:187], v[206:207], off offset:512
	global_load_dwordx4 v[188:191], v[206:207], off offset:576
	s_mov_b64 s[8:9], 0x50000
	v_lshl_add_u64 v[208:209], v[150:151], 0, s[8:9]
	s_waitcnt vmcnt(7)
	v_pk_add_f32 v[160:161], v[30:31], v[160:161]
	v_pk_add_f32 v[162:163], v[32:33], v[162:163]
	v_cvt_pk_bf16_f32 v192, v160, v161
	v_cvt_pk_bf16_f32 v193, v162, v163
	global_store_dwordx2 v[208:209], v[192:193], off
	v_mul_f32_e32 v196, v161, v161
	v_fmac_f32_e32 v196, v160, v160
	v_mul_f32_e32 v197, v163, v163
	v_fmac_f32_e32 v197, v162, v162
	v_add_f32_e32 v198, v196, v197
	s_waitcnt vmcnt(7)
	v_pk_add_f32 v[164:165], v[26:27], v[164:165]
	v_pk_add_f32 v[166:167], v[28:29], v[166:167]
	v_cvt_pk_bf16_f32 v194, v164, v165
	v_cvt_pk_bf16_f32 v195, v166, v167
	global_store_dwordx2 v[208:209], v[194:195], off offset:32
	v_mul_f32_e32 v196, v165, v165
	v_fmac_f32_e32 v196, v164, v164
	v_mul_f32_e32 v197, v167, v167
	v_fmac_f32_e32 v197, v166, v166
	v_add_f32_e32 v196, v196, v197
	v_add_f32_e32 v198, v198, v196
	s_waitcnt vmcnt(7)
	v_pk_add_f32 v[168:169], v[22:23], v[168:169]
	v_pk_add_f32 v[170:171], v[24:25], v[170:171]
	v_cvt_pk_bf16_f32 v192, v168, v169
	v_cvt_pk_bf16_f32 v193, v170, v171
	global_store_dwordx2 v[208:209], v[192:193], off offset:256
	v_mul_f32_e32 v196, v169, v169
	v_fmac_f32_e32 v196, v168, v168
	v_mul_f32_e32 v197, v171, v171
	v_fmac_f32_e32 v197, v170, v170
	v_add_f32_e32 v196, v196, v197
	v_add_f32_e32 v198, v198, v196
	s_waitcnt vmcnt(7)
	v_pk_add_f32 v[172:173], v[18:19], v[172:173]
	v_pk_add_f32 v[174:175], v[20:21], v[174:175]
	v_cvt_pk_bf16_f32 v194, v172, v173
	v_cvt_pk_bf16_f32 v195, v174, v175
	global_store_dwordx2 v[208:209], v[194:195], off offset:288
	v_mul_f32_e32 v196, v173, v173
	v_fmac_f32_e32 v196, v172, v172
	v_mul_f32_e32 v197, v175, v175
	v_fmac_f32_e32 v197, v174, v174
	v_add_f32_e32 v196, v196, v197
	v_add_f32_e32 v198, v198, v196
	ds_bpermute_b32 v199, v203, v198
	s_waitcnt lgkmcnt(0)
	v_add_f32_e32 v198, v198, v199
	ds_bpermute_b32 v199, v204, v198
	v_add_co_u32_e32 v210, vcc, 0x280, v146
	s_waitcnt lgkmcnt(0)
	s_nop 1
	v_addc_co_u32_e32 v211, vcc, 0, v147, vcc
	v_add_f32_e32 v198, v198, v199
	s_and_saveexec_b64 s[8:9], s[4:5]
	global_atomic_add_f32 v[210:211], v198, off
	s_or_b64 exec, exec, s[8:9]
	s_mov_b64 s[8:9], 0x58000
	v_lshl_add_u64 v[208:209], v[150:151], 0, s[8:9]
	s_waitcnt vmcnt(8)
	v_pk_add_f32 v[176:177], v[14:15], v[176:177]
	v_pk_add_f32 v[178:179], v[16:17], v[178:179]
	v_cvt_pk_bf16_f32 v192, v176, v177
	v_cvt_pk_bf16_f32 v193, v178, v179
	global_store_dwordx2 v[208:209], v[192:193], off
	v_mul_f32_e32 v196, v177, v177
	v_fmac_f32_e32 v196, v176, v176
	v_mul_f32_e32 v197, v179, v179
	v_fmac_f32_e32 v197, v178, v178
	v_add_f32_e32 v198, v196, v197
	s_waitcnt vmcnt(8)
	v_pk_add_f32 v[180:181], v[10:11], v[180:181]
	v_pk_add_f32 v[182:183], v[12:13], v[182:183]
	v_cvt_pk_bf16_f32 v194, v180, v181
	v_cvt_pk_bf16_f32 v195, v182, v183
	global_store_dwordx2 v[208:209], v[194:195], off offset:32
	v_mul_f32_e32 v196, v181, v181
	v_fmac_f32_e32 v196, v180, v180
	v_mul_f32_e32 v197, v183, v183
	v_fmac_f32_e32 v197, v182, v182
	v_add_f32_e32 v196, v196, v197
	v_add_f32_e32 v198, v198, v196
	s_waitcnt vmcnt(8)
	v_pk_add_f32 v[184:185], v[6:7], v[184:185]
	v_pk_add_f32 v[186:187], v[8:9], v[186:187]
	v_cvt_pk_bf16_f32 v192, v184, v185
	v_cvt_pk_bf16_f32 v193, v186, v187
	global_store_dwordx2 v[208:209], v[192:193], off offset:256
	v_mul_f32_e32 v196, v185, v185
	v_fmac_f32_e32 v196, v184, v184
	v_mul_f32_e32 v197, v187, v187
	v_fmac_f32_e32 v197, v186, v186
	v_add_f32_e32 v196, v196, v197
	v_add_f32_e32 v198, v198, v196
	s_waitcnt vmcnt(8)
	v_pk_add_f32 v[188:189], v[2:3], v[188:189]
	v_pk_add_f32 v[190:191], v[4:5], v[190:191]
	v_cvt_pk_bf16_f32 v194, v188, v189
	v_cvt_pk_bf16_f32 v195, v190, v191
	global_store_dwordx2 v[208:209], v[194:195], off offset:288
	v_mul_f32_e32 v196, v189, v189
	v_fmac_f32_e32 v196, v188, v188
	v_mul_f32_e32 v197, v191, v191
	v_fmac_f32_e32 v197, v190, v190
	v_add_f32_e32 v196, v196, v197
	v_add_f32_e32 v198, v198, v196
	ds_bpermute_b32 v199, v203, v198
	s_waitcnt lgkmcnt(0)
	v_add_f32_e32 v198, v198, v199
	ds_bpermute_b32 v199, v204, v198
	v_add_co_u32_e32 v210, vcc, 0x2c0, v146
	s_waitcnt lgkmcnt(0)
	s_nop 1
	v_addc_co_u32_e32 v211, vcc, 0, v147, vcc
	v_add_f32_e32 v198, v198, v199
	s_and_saveexec_b64 s[8:9], s[4:5]
	global_atomic_add_f32 v[210:211], v198, off
	s_or_b64 exec, exec, s[8:9]
